# speedup vs baseline: 1.0739x; 1.0220x over previous
; #define MFMA16(a, b, c) __builtin_amdgcn_mfma_f32_16x16x32_bf16((a), (b), (c), 0, 0, 0)
; DI void score_phase(const bf16_t* PROJ, unsigned short* SC, int c, char* smem, int bid, int nb) {
;     ...
;     for (int h = 0; h < 16; ++h) {
;       const bf16x8 qa0 = *(const bf16x8*)(rowp0 + C_IQ + h * 64 + fq * 8), qa1 = *(const bf16x8*)(rowp0 + C_IQ + h * 64 + 32 + fq * 8);
;       const bf16x8 qb0f = *(const bf16x8*)(rowp1 + C_IQ + h * 64 + fq * 8), qb1f = *(const bf16x8*)(rowp1 + C_IQ + h * 64 + 32 + fq * 8);
;       const float w0 = sW[fr * 17 + h], w1 = sW[(16 + fr) * 17 + h];
; #pragma unroll
;       for (int nj = 0; nj < 8; ++nj) {
;         f32x4 d = MFMA16(kf[nj][0], qa0, ((f32x4){0.f, 0.f, 0.f, 0.f}));
;         d = MFMA16(kf[nj][1], qa1, d);
;         f32x4 e = MFMA16(kf[nj][0], qb0f, ((f32x4){0.f, 0.f, 0.f, 0.f}));
;         e = MFMA16(kf[nj][1], qb1f, e);
; #pragma unroll
;         for (int r = 0; r < 4; ++r) { sc[0][nj][r] += w0 * fmaxf(d[r], 0.f); sc[1][nj][r] += w1 * fmaxf(e[r], 0.f); }
;       }
.LBB0_1061:
	v_lshl_add_u64 v[72:73], v[136:137], 0, s[6:7]
	v_add_co_u32_e32 v68, vcc, s2, v72
	s_add_u32 s6, s6, 0x80
	s_nop 0
	v_addc_co_u32_e32 v69, vcc, 0, v73, vcc
	v_add_co_u32_e32 v76, vcc, s3, v72
	global_load_dwordx4 v[64:67], v[68:69], off offset:128
	s_nop 0
	global_load_dwordx4 v[68:71], v[68:69], off offset:192
	v_addc_co_u32_e32 v77, vcc, 0, v73, vcc
	global_load_dwordx4 v[72:75], v[76:77], off offset:128
	s_nop 0
	global_load_dwordx4 v[76:79], v[76:77], off offset:192
	ds_read_b32 v152, v158
	ds_read_b32 v150, v158 offset:1088
	s_addc_u32 s7, s7, 0
	v_add_u32_e32 v158, 4, v158
	s_cmpk_eq_i32 s6, 0x800
	s_waitcnt vmcnt(3)
	v_mfma_f32_16x16x32_bf16 v[160:163], v[0:3], v[64:67], 0
	s_waitcnt vmcnt(1)
	v_mfma_f32_16x16x32_bf16 v[164:167], v[0:3], v[72:75], 0
	v_mfma_f32_16x16x32_bf16 v[160:163], v[4:7], v[68:71], v[160:163]
	s_waitcnt vmcnt(0)
	v_mfma_f32_16x16x32_bf16 v[164:167], v[4:7], v[76:79], v[164:167]
	s_nop 5
	v_max_f32_e32 v160, 0, v160
	s_nop 0
	v_max_f32_e32 v164, 0, v164
	v_max_f32_e32 v161, 0, v161
	v_max_f32_e32 v165, 0, v165
	s_waitcnt lgkmcnt(1)
	v_pk_fma_f32 v[146:147], v[152:153], v[160:161], v[146:147] op_sel_hi:[0,1,1]
	v_max_f32_e32 v160, 0, v162
	v_max_f32_e32 v162, 0, v166
	v_max_f32_e32 v161, 0, v163
	v_max_f32_e32 v163, 0, v167
	v_pk_fma_f32 v[148:149], v[152:153], v[160:161], v[148:149] op_sel_hi:[0,1,1]
	s_waitcnt lgkmcnt(0)
	v_pk_fma_f32 v[114:115], v[150:151], v[162:163], v[114:115] op_sel_hi:[0,1,1]
	v_mfma_f32_16x16x32_bf16 v[160:163], v[8:11], v[64:67], 0
	v_fma_f32 v112, v150, v164, v112
	v_fma_f32 v113, v150, v165, v113
	v_mfma_f32_16x16x32_bf16 v[164:167], v[8:11], v[72:75], 0
	v_mfma_f32_16x16x32_bf16 v[160:163], v[12:15], v[68:71], v[160:163]
	v_mfma_f32_16x16x32_bf16 v[164:167], v[12:15], v[76:79], v[164:167]
	s_nop 6
	v_max_f32_e32 v160, 0, v160
	v_max_f32_e32 v164, 0, v164
	v_max_f32_e32 v161, 0, v161
	v_max_f32_e32 v165, 0, v165
	v_pk_fma_f32 v[142:143], v[152:153], v[160:161], v[142:143] op_sel_hi:[0,1,1]
	v_max_f32_e32 v160, 0, v162
	v_max_f32_e32 v162, 0, v166
	v_max_f32_e32 v161, 0, v163
	v_max_f32_e32 v163, 0, v167
	v_pk_fma_f32 v[144:145], v[152:153], v[160:161], v[144:145] op_sel_hi:[0,1,1]
	v_pk_fma_f32 v[110:111], v[150:151], v[162:163], v[110:111] op_sel_hi:[0,1,1]
	v_mfma_f32_16x16x32_bf16 v[160:163], v[16:19], v[64:67], 0
	v_fma_f32 v108, v150, v164, v108
	v_fma_f32 v109, v150, v165, v109
	v_mfma_f32_16x16x32_bf16 v[164:167], v[16:19], v[72:75], 0
	v_mfma_f32_16x16x32_bf16 v[160:163], v[20:23], v[68:71], v[160:163]
	v_mfma_f32_16x16x32_bf16 v[164:167], v[20:23], v[76:79], v[164:167]
	s_nop 6
	v_max_f32_e32 v160, 0, v160
	v_max_f32_e32 v164, 0, v164
	v_max_f32_e32 v161, 0, v161
	v_max_f32_e32 v165, 0, v165
	v_pk_fma_f32 v[138:139], v[152:153], v[160:161], v[138:139] op_sel_hi:[0,1,1]
	v_max_f32_e32 v160, 0, v162
	v_max_f32_e32 v162, 0, v166
	v_max_f32_e32 v161, 0, v163
	v_max_f32_e32 v163, 0, v167
	v_pk_fma_f32 v[140:141], v[152:153], v[160:161], v[140:141] op_sel_hi:[0,1,1]
	v_pk_fma_f32 v[106:107], v[150:151], v[162:163], v[106:107] op_sel_hi:[0,1,1]
	v_mfma_f32_16x16x32_bf16 v[160:163], v[24:27], v[64:67], 0
	v_fma_f32 v104, v150, v164, v104
	v_fma_f32 v105, v150, v165, v105
	v_mfma_f32_16x16x32_bf16 v[164:167], v[24:27], v[72:75], 0
	v_mfma_f32_16x16x32_bf16 v[160:163], v[28:31], v[68:71], v[160:163]
	v_mfma_f32_16x16x32_bf16 v[164:167], v[28:31], v[76:79], v[164:167]
	s_nop 6
	v_max_f32_e32 v160, 0, v160
	v_max_f32_e32 v164, 0, v164
	v_max_f32_e32 v161, 0, v161
	v_max_f32_e32 v165, 0, v165
	v_pk_fma_f32 v[132:133], v[152:153], v[160:161], v[132:133] op_sel_hi:[0,1,1]
	v_max_f32_e32 v160, 0, v162
	v_max_f32_e32 v162, 0, v166
	v_max_f32_e32 v161, 0, v163
	v_max_f32_e32 v163, 0, v167
	v_pk_fma_f32 v[134:135], v[152:153], v[160:161], v[134:135] op_sel_hi:[0,1,1]
	v_pk_fma_f32 v[102:103], v[150:151], v[162:163], v[102:103] op_sel_hi:[0,1,1]
	v_mfma_f32_16x16x32_bf16 v[160:163], v[32:35], v[64:67], 0
	v_fma_f32 v100, v150, v164, v100
	v_fma_f32 v101, v150, v165, v101
	v_mfma_f32_16x16x32_bf16 v[164:167], v[32:35], v[72:75], 0
	v_mfma_f32_16x16x32_bf16 v[160:163], v[36:39], v[68:71], v[160:163]
	v_mfma_f32_16x16x32_bf16 v[164:167], v[36:39], v[76:79], v[164:167]
	s_nop 6
	v_max_f32_e32 v160, 0, v160
	v_max_f32_e32 v164, 0, v164
	v_max_f32_e32 v161, 0, v161
	v_max_f32_e32 v165, 0, v165
	v_pk_fma_f32 v[128:129], v[152:153], v[160:161], v[128:129] op_sel_hi:[0,1,1]
	v_max_f32_e32 v160, 0, v162
	v_max_f32_e32 v162, 0, v166
	v_max_f32_e32 v161, 0, v163
	v_max_f32_e32 v163, 0, v167
	v_pk_fma_f32 v[130:131], v[152:153], v[160:161], v[130:131] op_sel_hi:[0,1,1]
	v_pk_fma_f32 v[98:99], v[150:151], v[162:163], v[98:99] op_sel_hi:[0,1,1]
	v_mfma_f32_16x16x32_bf16 v[160:163], v[40:43], v[64:67], 0
	v_fma_f32 v96, v150, v164, v96
	v_fma_f32 v97, v150, v165, v97
	v_mfma_f32_16x16x32_bf16 v[164:167], v[40:43], v[72:75], 0
	v_mfma_f32_16x16x32_bf16 v[160:163], v[44:47], v[68:71], v[160:163]
	v_mfma_f32_16x16x32_bf16 v[164:167], v[44:47], v[76:79], v[164:167]
	s_nop 6
	v_max_f32_e32 v160, 0, v160
	v_max_f32_e32 v164, 0, v164
	v_max_f32_e32 v161, 0, v161
	v_max_f32_e32 v165, 0, v165
	v_pk_fma_f32 v[124:125], v[152:153], v[160:161], v[124:125] op_sel_hi:[0,1,1]
	v_max_f32_e32 v160, 0, v162
	v_max_f32_e32 v162, 0, v166
	v_max_f32_e32 v161, 0, v163
	v_max_f32_e32 v163, 0, v167
	v_pk_fma_f32 v[126:127], v[152:153], v[160:161], v[126:127] op_sel_hi:[0,1,1]
	v_pk_fma_f32 v[94:95], v[150:151], v[162:163], v[94:95] op_sel_hi:[0,1,1]
	v_mfma_f32_16x16x32_bf16 v[160:163], v[48:51], v[64:67], 0
	v_fma_f32 v92, v150, v164, v92
	v_fma_f32 v93, v150, v165, v93
	v_mfma_f32_16x16x32_bf16 v[64:67], v[56:59], v[64:67], 0
; #define MFMA16(a, b, c) __builtin_amdgcn_mfma_f32_16x16x32_bf16((a), (b), (c), 0, 0, 0)
; DI void score_phase(const bf16_t* PROJ, unsigned short* SC, int c, char* smem, int bid, int nb) {
;     ...
;       for (int nj = 0; nj < 8; ++nj) {
;         f32x4 d = MFMA16(kf[nj][0], qa0, ((f32x4){0.f, 0.f, 0.f, 0.f}));
;         d = MFMA16(kf[nj][1], qa1, d);
;         f32x4 e = MFMA16(kf[nj][0], qb0f, ((f32x4){0.f, 0.f, 0.f, 0.f}));
;         e = MFMA16(kf[nj][1], qb1f, e);
; #pragma unroll
;         for (int r = 0; r < 4; ++r) { sc[0][nj][r] += w0 * fmaxf(d[r], 0.f); sc[1][nj][r] += w1 * fmaxf(e[r], 0.f); }
;       }
;     }
; #pragma unroll
;     for (int mi = 0; mi < 2; ++mi) {
;       const int t = q0 + mi * 16 + fr;
;       unsigned short* op = SC + (size_t)(t - c * 4096) * S + s0 + fq * 4;
; #pragma unroll
;       for (int nj = 0; nj < 8; ++nj) {
;         unsigned w0 = __builtin_bit_cast(unsigned, __builtin_amdgcn_cvt_pkrtz(sc[mi][nj][0], sc[mi][nj][1]));
;         unsigned w1 = __builtin_bit_cast(unsigned, __builtin_amdgcn_cvt_pkrtz(sc[mi][nj][2], sc[mi][nj][3]));
;         const unsigned m0 = ((w0 >> 15) & 0x00010001u) * 0xffffu, m1 = ((w1 >> 15) & 0x00010001u) * 0xffffu;
;         w0 ^= (m0 | 0x80008000u); w1 ^= (m1 | 0x80008000u);
;         uint2 st2; st2.x = w0; st2.y = w1;
;         *(uint2*)(op + nj * 16) = st2;
	v_mfma_f32_16x16x32_bf16 v[164:167], v[48:51], v[72:75], 0
	v_mfma_f32_16x16x32_bf16 v[160:163], v[52:55], v[68:71], v[160:163]
	v_mfma_f32_16x16x32_bf16 v[64:67], v[60:63], v[68:71], v[64:67]
	v_mfma_f32_16x16x32_bf16 v[68:71], v[56:59], v[72:75], 0
	s_nop 5
	v_max_f32_e32 v160, 0, v160
	v_mfma_f32_16x16x32_bf16 v[164:167], v[52:55], v[76:79], v[164:167]
	v_max_f32_e32 v64, 0, v64
	v_max_f32_e32 v65, 0, v65
	v_mfma_f32_16x16x32_bf16 v[68:71], v[60:63], v[76:79], v[68:71]
	v_fma_f32 v116, v152, v64, v116
	v_fma_f32 v117, v152, v65, v117
	s_nop 1
	s_nop 0
	v_max_f32_e32 v164, 0, v164
	v_max_f32_e32 v161, 0, v161
	v_max_f32_e32 v165, 0, v165
	v_pk_fma_f32 v[120:121], v[152:153], v[160:161], v[120:121] op_sel_hi:[0,1,1]
	v_max_f32_e32 v160, 0, v162
	v_max_f32_e32 v69, 0, v69
	v_max_f32_e32 v64, v66, v66
	v_max_f32_e32 v66, 0, v70
	v_max_f32_e32 v162, 0, v166
	v_max_f32_e32 v64, 0, v64
	v_max_f32_e32 v65, 0, v67
	v_max_f32_e32 v161, 0, v163
	v_max_f32_e32 v159, v167, v167
	v_pk_fma_f32 v[118:119], v[152:153], v[64:65], v[118:119] op_sel_hi:[0,1,1]
	v_max_f32_e32 v64, v71, v71
	v_max_f32_e32 v163, 0, v159
	v_max_f32_e32 v68, 0, v68
	v_max_f32_e32 v67, 0, v64
	v_pk_fma_f32 v[88:89], v[150:151], v[164:165], v[88:89] op_sel_hi:[0,1,1]
	v_pk_fma_f32 v[122:123], v[152:153], v[160:161], v[122:123] op_sel_hi:[0,1,1]
	v_pk_fma_f32 v[90:91], v[150:151], v[162:163], v[90:91] op_sel_hi:[0,1,1]
	v_pk_fma_f32 v[84:85], v[150:151], v[68:69], v[84:85] op_sel_hi:[0,1,1]
	v_pk_fma_f32 v[86:87], v[150:151], v[66:67], v[86:87] op_sel_hi:[0,1,1]
	s_cbranch_scc0 .LBB0_1061
	v_add_u32_e32 v0, v155, v157
	v_ashrrev_i32_e32 v1, 31, v0
	v_lshlrev_b64 v[4:5], 15, v[0:1]
	v_cvt_pkrtz_f16_f32 v1, v146, v147
	v_cvt_pkrtz_f16_f32 v6, v148, v149
	v_lshrrev_b32_e32 v7, 15, v6
	v_lshrrev_b32_e32 v8, 15, v1
	v_and_b32_e32 v7, 0x10001, v7
	v_and_b32_e32 v8, 0x10001, v8
	s_ashr_i32 s5, s4, 31
	v_mul_u32_u24_e32 v8, 0xffff, v8
	v_mul_u32_u24_e32 v7, 0xffff, v7
	v_lshl_add_u64 v[2:3], s[4:5], 1, v[80:81]
	v_or_b32_e32 v7, 0x80008000, v7
	v_or_b32_e32 v8, 0x80008000, v8
	v_lshl_add_u64 v[4:5], v[2:3], 0, v[4:5]
	v_xor_b32_e32 v7, v7, v6
	v_xor_b32_e32 v6, v8, v1
	global_store_dwordx2 v[4:5], v[6:7], off
	v_cvt_pkrtz_f16_f32 v1, v142, v143
	v_cvt_pkrtz_f16_f32 v6, v144, v145
	v_lshrrev_b32_e32 v7, 15, v6
	v_lshrrev_b32_e32 v8, 15, v1
	v_and_b32_e32 v7, 0x10001, v7
	v_and_b32_e32 v8, 0x10001, v8
	v_mul_u32_u24_e32 v8, 0xffff, v8
	v_mul_u32_u24_e32 v7, 0xffff, v7
	v_or_b32_e32 v7, 0x80008000, v7
	v_or_b32_e32 v8, 0x80008000, v8
	v_xor_b32_e32 v7, v7, v6
	v_xor_b32_e32 v6, v8, v1
	global_store_dwordx2 v[4:5], v[6:7], off offset:32
	v_cvt_pkrtz_f16_f32 v1, v138, v139
	v_cvt_pkrtz_f16_f32 v6, v140, v141
	v_lshrrev_b32_e32 v7, 15, v6
	v_lshrrev_b32_e32 v8, 15, v1
	v_and_b32_e32 v7, 0x10001, v7
	v_and_b32_e32 v8, 0x10001, v8
	v_mul_u32_u24_e32 v8, 0xffff, v8
	v_mul_u32_u24_e32 v7, 0xffff, v7
	v_or_b32_e32 v7, 0x80008000, v7
	v_or_b32_e32 v8, 0x80008000, v8
	v_xor_b32_e32 v7, v7, v6
	v_xor_b32_e32 v6, v8, v1
	global_store_dwordx2 v[4:5], v[6:7], off offset:64
	v_cvt_pkrtz_f16_f32 v1, v132, v133
	v_cvt_pkrtz_f16_f32 v6, v134, v135
	v_lshrrev_b32_e32 v7, 15, v6
	v_lshrrev_b32_e32 v8, 15, v1
	v_and_b32_e32 v7, 0x10001, v7
	v_and_b32_e32 v8, 0x10001, v8
	v_mul_u32_u24_e32 v8, 0xffff, v8
	v_mul_u32_u24_e32 v7, 0xffff, v7
	v_or_b32_e32 v7, 0x80008000, v7
	v_or_b32_e32 v8, 0x80008000, v8
	v_xor_b32_e32 v7, v7, v6
	v_xor_b32_e32 v6, v8, v1
	global_store_dwordx2 v[4:5], v[6:7], off offset:96
	v_cvt_pkrtz_f16_f32 v1, v128, v129
	v_cvt_pkrtz_f16_f32 v6, v130, v131
	v_lshrrev_b32_e32 v7, 15, v6
	v_lshrrev_b32_e32 v8, 15, v1
	v_and_b32_e32 v7, 0x10001, v7
	v_and_b32_e32 v8, 0x10001, v8
	v_mul_u32_u24_e32 v8, 0xffff, v8
	v_mul_u32_u24_e32 v7, 0xffff, v7
	v_or_b32_e32 v7, 0x80008000, v7
	v_or_b32_e32 v8, 0x80008000, v8
	v_xor_b32_e32 v7, v7, v6
	v_xor_b32_e32 v6, v8, v1
	global_store_dwordx2 v[4:5], v[6:7], off offset:128
	v_cvt_pkrtz_f16_f32 v1, v124, v125
	v_cvt_pkrtz_f16_f32 v6, v126, v127
	v_lshrrev_b32_e32 v7, 15, v6
	v_lshrrev_b32_e32 v8, 15, v1
	v_and_b32_e32 v7, 0x10001, v7
	v_and_b32_e32 v8, 0x10001, v8
	v_mul_u32_u24_e32 v8, 0xffff, v8
	v_mul_u32_u24_e32 v7, 0xffff, v7
	v_or_b32_e32 v7, 0x80008000, v7
	v_or_b32_e32 v8, 0x80008000, v8
	v_xor_b32_e32 v7, v7, v6
	v_xor_b32_e32 v6, v8, v1
	global_store_dwordx2 v[4:5], v[6:7], off offset:160
	v_cvt_pkrtz_f16_f32 v1, v120, v121
	v_cvt_pkrtz_f16_f32 v6, v122, v123
	v_lshrrev_b32_e32 v7, 15, v6
; DI void score_phase(const bf16_t* PROJ, unsigned short* SC, int c, char* smem, int bid, int nb) {
;     ...
; #pragma unroll
;     for (int mi = 0; mi < 2; ++mi) {
;       const int t = q0 + mi * 16 + fr;
;       unsigned short* op = SC + (size_t)(t - c * 4096) * S + s0 + fq * 4;
; #pragma unroll
;       for (int nj = 0; nj < 8; ++nj) {
;         unsigned w0 = __builtin_bit_cast(unsigned, __builtin_amdgcn_cvt_pkrtz(sc[mi][nj][0], sc[mi][nj][1]));
;         unsigned w1 = __builtin_bit_cast(unsigned, __builtin_amdgcn_cvt_pkrtz(sc[mi][nj][2], sc[mi][nj][3]));
;         const unsigned m0 = ((w0 >> 15) & 0x00010001u) * 0xffffu, m1 = ((w1 >> 15) & 0x00010001u) * 0xffffu;
;         w0 ^= (m0 | 0x80008000u); w1 ^= (m1 | 0x80008000u);
;         uint2 st2; st2.x = w0; st2.y = w1;
;         *(uint2*)(op + nj * 16) = st2;
;       }
;     }
;   }
	v_lshrrev_b32_e32 v8, 15, v1
	v_and_b32_e32 v7, 0x10001, v7
	v_and_b32_e32 v8, 0x10001, v8
	v_mul_u32_u24_e32 v8, 0xffff, v8
	v_mul_u32_u24_e32 v7, 0xffff, v7
	v_or_b32_e32 v7, 0x80008000, v7
	v_or_b32_e32 v8, 0x80008000, v8
	v_xor_b32_e32 v7, v7, v6
	v_xor_b32_e32 v6, v8, v1
	global_store_dwordx2 v[4:5], v[6:7], off offset:192
	v_cvt_pkrtz_f16_f32 v1, v116, v117
	v_cvt_pkrtz_f16_f32 v6, v118, v119
	v_lshrrev_b32_e32 v7, 15, v6
	v_lshrrev_b32_e32 v8, 15, v1
	v_and_b32_e32 v7, 0x10001, v7
	v_and_b32_e32 v8, 0x10001, v8
	v_mul_u32_u24_e32 v8, 0xffff, v8
	v_mul_u32_u24_e32 v7, 0xffff, v7
	v_or_b32_e32 v7, 0x80008000, v7
	v_or_b32_e32 v8, 0x80008000, v8
	v_or_b32_e32 v0, 16, v0
	v_xor_b32_e32 v7, v7, v6
	v_xor_b32_e32 v6, v8, v1
	v_ashrrev_i32_e32 v1, 31, v0
	v_lshlrev_b64 v[0:1], 15, v[0:1]
	v_lshl_add_u64 v[0:1], v[2:3], 0, v[0:1]
	v_cvt_pkrtz_f16_f32 v2, v112, v113
	v_cvt_pkrtz_f16_f32 v3, v114, v115
	global_store_dwordx2 v[4:5], v[6:7], off offset:224
	v_lshrrev_b32_e32 v4, 15, v3
	v_lshrrev_b32_e32 v5, 15, v2
	v_and_b32_e32 v4, 0x10001, v4
	v_and_b32_e32 v5, 0x10001, v5
	v_mul_u32_u24_e32 v5, 0xffff, v5
	v_mul_u32_u24_e32 v4, 0xffff, v4
	v_or_b32_e32 v4, 0x80008000, v4
	v_or_b32_e32 v5, 0x80008000, v5
	v_xor_b32_e32 v3, v4, v3
	v_xor_b32_e32 v2, v5, v2
	global_store_dwordx2 v[0:1], v[2:3], off
	v_cvt_pkrtz_f16_f32 v2, v108, v109
	v_cvt_pkrtz_f16_f32 v3, v110, v111
	v_lshrrev_b32_e32 v4, 15, v3
	v_lshrrev_b32_e32 v5, 15, v2
	v_and_b32_e32 v4, 0x10001, v4
	v_and_b32_e32 v5, 0x10001, v5
	v_mul_u32_u24_e32 v5, 0xffff, v5
	v_mul_u32_u24_e32 v4, 0xffff, v4
	v_or_b32_e32 v4, 0x80008000, v4
	v_or_b32_e32 v5, 0x80008000, v5
	v_xor_b32_e32 v3, v4, v3
	v_xor_b32_e32 v2, v5, v2
	global_store_dwordx2 v[0:1], v[2:3], off offset:32
	v_cvt_pkrtz_f16_f32 v2, v104, v105
	v_cvt_pkrtz_f16_f32 v3, v106, v107
	v_lshrrev_b32_e32 v4, 15, v3
	v_lshrrev_b32_e32 v5, 15, v2
	v_and_b32_e32 v4, 0x10001, v4
	v_and_b32_e32 v5, 0x10001, v5
	v_mul_u32_u24_e32 v5, 0xffff, v5
	v_mul_u32_u24_e32 v4, 0xffff, v4
	v_or_b32_e32 v4, 0x80008000, v4
	v_or_b32_e32 v5, 0x80008000, v5
	v_xor_b32_e32 v3, v4, v3
	v_xor_b32_e32 v2, v5, v2
	global_store_dwordx2 v[0:1], v[2:3], off offset:64
	v_cvt_pkrtz_f16_f32 v2, v100, v101
	v_cvt_pkrtz_f16_f32 v3, v102, v103
	v_lshrrev_b32_e32 v4, 15, v3
	v_lshrrev_b32_e32 v5, 15, v2
	v_and_b32_e32 v4, 0x10001, v4
	v_and_b32_e32 v5, 0x10001, v5
	v_mul_u32_u24_e32 v5, 0xffff, v5
	v_mul_u32_u24_e32 v4, 0xffff, v4
	v_or_b32_e32 v4, 0x80008000, v4
	v_or_b32_e32 v5, 0x80008000, v5
	v_xor_b32_e32 v3, v4, v3
	v_xor_b32_e32 v2, v5, v2
	global_store_dwordx2 v[0:1], v[2:3], off offset:96
	v_cvt_pkrtz_f16_f32 v2, v96, v97
	v_cvt_pkrtz_f16_f32 v3, v98, v99
	v_lshrrev_b32_e32 v4, 15, v3
	v_lshrrev_b32_e32 v5, 15, v2
	v_and_b32_e32 v4, 0x10001, v4
	v_and_b32_e32 v5, 0x10001, v5
	v_mul_u32_u24_e32 v5, 0xffff, v5
	v_mul_u32_u24_e32 v4, 0xffff, v4
	v_or_b32_e32 v4, 0x80008000, v4
	v_or_b32_e32 v5, 0x80008000, v5
	v_xor_b32_e32 v3, v4, v3
	v_xor_b32_e32 v2, v5, v2
	global_store_dwordx2 v[0:1], v[2:3], off offset:128
	v_cvt_pkrtz_f16_f32 v2, v92, v93
	v_cvt_pkrtz_f16_f32 v3, v94, v95
	v_lshrrev_b32_e32 v4, 15, v3
	v_lshrrev_b32_e32 v5, 15, v2
	v_and_b32_e32 v4, 0x10001, v4
	v_and_b32_e32 v5, 0x10001, v5
	v_mul_u32_u24_e32 v5, 0xffff, v5
	v_mul_u32_u24_e32 v4, 0xffff, v4
	v_or_b32_e32 v4, 0x80008000, v4
	v_or_b32_e32 v5, 0x80008000, v5
	v_xor_b32_e32 v3, v4, v3
	v_xor_b32_e32 v2, v5, v2
	global_store_dwordx2 v[0:1], v[2:3], off offset:160
	v_cvt_pkrtz_f16_f32 v2, v88, v89
	v_cvt_pkrtz_f16_f32 v3, v90, v91
	v_lshrrev_b32_e32 v4, 15, v3
	v_lshrrev_b32_e32 v5, 15, v2
	v_and_b32_e32 v4, 0x10001, v4
	v_and_b32_e32 v5, 0x10001, v5
	v_mul_u32_u24_e32 v5, 0xffff, v5
	v_mul_u32_u24_e32 v4, 0xffff, v4
	v_or_b32_e32 v4, 0x80008000, v4
	v_or_b32_e32 v5, 0x80008000, v5
	v_xor_b32_e32 v3, v4, v3
	v_xor_b32_e32 v2, v5, v2
	global_store_dwordx2 v[0:1], v[2:3], off offset:192
	v_cvt_pkrtz_f16_f32 v2, v84, v85
	v_cvt_pkrtz_f16_f32 v3, v86, v87
	v_lshrrev_b32_e32 v4, 15, v3
	v_lshrrev_b32_e32 v5, 15, v2
	v_and_b32_e32 v4, 0x10001, v4
	v_and_b32_e32 v5, 0x10001, v5
	v_mul_u32_u24_e32 v5, 0xffff, v5
	v_mul_u32_u24_e32 v4, 0xffff, v4
	v_readlane_b32 s2, v249, 43
	v_or_b32_e32 v4, 0x80008000, v4
	v_or_b32_e32 v5, 0x80008000, v5
	s_add_i32 s12, s12, s2
	v_xor_b32_e32 v3, v4, v3
	v_xor_b32_e32 v2, v5, v2
	s_cmp_ge_i32 s12, s8
	v_readlane_b32 s3, v249, 44
	global_store_dwordx2 v[0:1], v[2:3], off offset:224
	s_cbranch_scc0 .LBB0_1055

; DI void gla3_phase(const P& p, int l, const bf16_t* PROJ, const float* US, bf16_t* OGLA, char* smem, int bid, int nb) {
;     ...
;       for (int kk = 0; kk < 128; ++kk) {
;         const f32x4 qv = *(const f32x4*)(QT + kk * LS + ty * 4), kv = *(const f32x4*)(KT + kk * LS + tx * 4);
; #pragma unroll
;         for (int i = 0; i < 4; ++i)
; #pragma unroll
;           for (int j = 0; j < 4; ++j) a[i][j] += qv[i] * kv[j];
;       }
.LBB0_1325:
	v_add_u32_e32 v42, s0, v94
	v_add_u32_e32 v43, s0, v101
	ds_read_b128 v[30:33], v42
	ds_read_b128 v[34:37], v43
	s_addk_i32 s0, 0x880
	s_cmpk_eq_u32 s0, 0x8800
	s_waitcnt lgkmcnt(0)
	v_mov_b32_e32 v38, v37
	v_mov_b32_e32 v0, v35
	v_mov_b32_e32 v1, v36
	v_pk_fma_f32 v[40:41], v[30:31], v[38:39], v[2:3] op_sel_hi:[1,0,1]
	v_mov_b32_e32 v2, v31
	v_mov_b32_e32 v3, v32
	v_pk_fma_f32 v[8:9], v[30:31], v[0:1], v[8:9] op_sel_hi:[0,1,1]
	v_pk_fma_f32 v[24:25], v[30:31], v[34:35], v[24:25] op_sel_hi:[1,0,1]
	v_pk_fma_f32 v[28:29], v[2:3], v[34:35], v[28:29] op_sel:[0,1,0]
	v_pk_fma_f32 v[30:31], v[2:3], v[36:37], v[6:7] op_sel_hi:[1,0,1]
	v_mov_b32_e32 v2, v33
	v_pk_fma_f32 v[26:27], v[32:33], v[34:35], v[26:27] op_sel_hi:[1,0,1]
	v_pk_fma_f32 v[10:11], v[2:3], v[0:1], v[10:11] op_sel_hi:[0,1,1]
	v_pk_fma_f32 v[32:33], v[32:33], v[38:39], v[4:5] op_sel_hi:[1,0,1]
	ds_read_b128 v[0:3], v42 offset:272
	ds_read_b128 v[4:7], v43 offset:272
	s_waitcnt lgkmcnt(0)
	v_mov_b32_e32 v34, v5
	v_mov_b32_e32 v35, v6
	v_mov_b32_e32 v36, v7
	v_pk_fma_f32 v[8:9], v[0:1], v[34:35], v[8:9] op_sel_hi:[0,1,1]
	v_pk_fma_f32 v[24:25], v[0:1], v[4:5], v[24:25] op_sel_hi:[1,0,1]
	v_pk_fma_f32 v[38:39], v[0:1], v[36:37], v[40:41] op_sel_hi:[1,0,1]
	v_mov_b32_e32 v0, v1
	v_mov_b32_e32 v1, v2
	v_pk_fma_f32 v[28:29], v[0:1], v[4:5], v[28:29] op_sel:[0,1,0]
	v_pk_fma_f32 v[30:31], v[0:1], v[6:7], v[30:31] op_sel_hi:[1,0,1]
	v_mov_b32_e32 v0, v3
	v_pk_fma_f32 v[26:27], v[2:3], v[4:5], v[26:27] op_sel_hi:[1,0,1]
	v_pk_fma_f32 v[10:11], v[0:1], v[34:35], v[10:11] op_sel_hi:[0,1,1]
	v_pk_fma_f32 v[32:33], v[2:3], v[36:37], v[32:33] op_sel_hi:[1,0,1]
	ds_read_b128 v[0:3], v42 offset:544
	ds_read_b128 v[4:7], v43 offset:544
	s_waitcnt lgkmcnt(0)
	v_mov_b32_e32 v34, v5
	v_mov_b32_e32 v35, v6
	v_mov_b32_e32 v36, v7
	v_pk_fma_f32 v[8:9], v[0:1], v[34:35], v[8:9] op_sel_hi:[0,1,1]
	v_pk_fma_f32 v[24:25], v[0:1], v[4:5], v[24:25] op_sel_hi:[1,0,1]
	v_pk_fma_f32 v[38:39], v[0:1], v[36:37], v[38:39] op_sel_hi:[1,0,1]
	v_mov_b32_e32 v0, v1
	v_mov_b32_e32 v1, v2
	v_pk_fma_f32 v[28:29], v[0:1], v[4:5], v[28:29] op_sel:[0,1,0]
	v_pk_fma_f32 v[30:31], v[0:1], v[6:7], v[30:31] op_sel_hi:[1,0,1]
	v_mov_b32_e32 v0, v3
	v_pk_fma_f32 v[26:27], v[2:3], v[4:5], v[26:27] op_sel_hi:[1,0,1]
	v_pk_fma_f32 v[10:11], v[0:1], v[34:35], v[10:11] op_sel_hi:[0,1,1]
	v_pk_fma_f32 v[32:33], v[2:3], v[36:37], v[32:33] op_sel_hi:[1,0,1]
	ds_read_b128 v[0:3], v42 offset:816
	ds_read_b128 v[4:7], v43 offset:816
	s_waitcnt lgkmcnt(0)
	v_mov_b32_e32 v34, v5
	v_mov_b32_e32 v35, v6
	v_mov_b32_e32 v36, v7
	v_pk_fma_f32 v[8:9], v[0:1], v[34:35], v[8:9] op_sel_hi:[0,1,1]
	v_pk_fma_f32 v[24:25], v[0:1], v[4:5], v[24:25] op_sel_hi:[1,0,1]
	v_pk_fma_f32 v[38:39], v[0:1], v[36:37], v[38:39] op_sel_hi:[1,0,1]
	v_mov_b32_e32 v0, v1
	v_mov_b32_e32 v1, v2
	v_pk_fma_f32 v[28:29], v[0:1], v[4:5], v[28:29] op_sel:[0,1,0]
	v_pk_fma_f32 v[30:31], v[0:1], v[6:7], v[30:31] op_sel_hi:[1,0,1]
	v_mov_b32_e32 v0, v3
	v_pk_fma_f32 v[26:27], v[2:3], v[4:5], v[26:27] op_sel_hi:[1,0,1]
	v_pk_fma_f32 v[10:11], v[0:1], v[34:35], v[10:11] op_sel_hi:[0,1,1]
	v_pk_fma_f32 v[32:33], v[2:3], v[36:37], v[32:33] op_sel_hi:[1,0,1]
	ds_read_b128 v[0:3], v42 offset:1088
	ds_read_b128 v[4:7], v43 offset:1088
	s_waitcnt lgkmcnt(0)
	v_mov_b32_e32 v34, v5
	v_mov_b32_e32 v35, v6
	v_mov_b32_e32 v36, v7
	v_pk_fma_f32 v[8:9], v[0:1], v[34:35], v[8:9] op_sel_hi:[0,1,1]
	v_pk_fma_f32 v[24:25], v[0:1], v[4:5], v[24:25] op_sel_hi:[1,0,1]
	v_pk_fma_f32 v[38:39], v[0:1], v[36:37], v[38:39] op_sel_hi:[1,0,1]
	v_mov_b32_e32 v0, v1
	v_mov_b32_e32 v1, v2
	v_pk_fma_f32 v[28:29], v[0:1], v[4:5], v[28:29] op_sel:[0,1,0]
	v_pk_fma_f32 v[30:31], v[0:1], v[6:7], v[30:31] op_sel_hi:[1,0,1]
	v_mov_b32_e32 v0, v3
	v_pk_fma_f32 v[26:27], v[2:3], v[4:5], v[26:27] op_sel_hi:[1,0,1]
	v_pk_fma_f32 v[10:11], v[0:1], v[34:35], v[10:11] op_sel_hi:[0,1,1]
	v_pk_fma_f32 v[32:33], v[2:3], v[36:37], v[32:33] op_sel_hi:[1,0,1]
	ds_read_b128 v[0:3], v42 offset:1360
	ds_read_b128 v[4:7], v43 offset:1360
	s_waitcnt lgkmcnt(0)
	v_mov_b32_e32 v34, v5
	v_mov_b32_e32 v35, v6
	v_mov_b32_e32 v36, v7
	v_pk_fma_f32 v[8:9], v[0:1], v[34:35], v[8:9] op_sel_hi:[0,1,1]
	v_pk_fma_f32 v[24:25], v[0:1], v[4:5], v[24:25] op_sel_hi:[1,0,1]
	v_pk_fma_f32 v[38:39], v[0:1], v[36:37], v[38:39] op_sel_hi:[1,0,1]
	v_mov_b32_e32 v0, v1
	v_mov_b32_e32 v1, v2
	v_pk_fma_f32 v[28:29], v[0:1], v[4:5], v[28:29] op_sel:[0,1,0]
	v_pk_fma_f32 v[30:31], v[0:1], v[6:7], v[30:31] op_sel_hi:[1,0,1]
	v_mov_b32_e32 v0, v3
	v_pk_fma_f32 v[26:27], v[2:3], v[4:5], v[26:27] op_sel_hi:[1,0,1]
	v_pk_fma_f32 v[10:11], v[0:1], v[34:35], v[10:11] op_sel_hi:[0,1,1]
	v_pk_fma_f32 v[32:33], v[2:3], v[36:37], v[32:33] op_sel_hi:[1,0,1]
	ds_read_b128 v[0:3], v42 offset:1632
	ds_read_b128 v[4:7], v43 offset:1632
	s_waitcnt lgkmcnt(0)
	v_mov_b32_e32 v34, v5
	v_mov_b32_e32 v35, v6
	v_mov_b32_e32 v36, v7
	v_pk_fma_f32 v[8:9], v[0:1], v[34:35], v[8:9] op_sel_hi:[0,1,1]
	v_pk_fma_f32 v[24:25], v[0:1], v[4:5], v[24:25] op_sel_hi:[1,0,1]
	v_pk_fma_f32 v[38:39], v[0:1], v[36:37], v[38:39] op_sel_hi:[1,0,1]
	v_mov_b32_e32 v0, v1
	v_mov_b32_e32 v1, v2
	v_pk_fma_f32 v[40:41], v[0:1], v[4:5], v[28:29] op_sel:[0,1,0]
	v_pk_fma_f32 v[26:27], v[2:3], v[4:5], v[26:27] op_sel_hi:[1,0,1]
	v_mov_b32_e32 v4, v3
	v_pk_fma_f32 v[0:1], v[0:1], v[6:7], v[30:31] op_sel_hi:[1,0,1]
	v_pk_fma_f32 v[10:11], v[4:5], v[34:35], v[10:11] op_sel_hi:[0,1,1]
	ds_read_b128 v[28:31], v42 offset:1904
	ds_read_b128 v[4:7], v43 offset:1904
	v_pk_fma_f32 v[32:33], v[2:3], v[36:37], v[32:33] op_sel_hi:[1,0,1]
	s_waitcnt lgkmcnt(0)
	v_mov_b32_e32 v36, v7
	v_pk_fma_f32 v[2:3], v[28:29], v[36:37], v[38:39] op_sel_hi:[1,0,1]
	v_mov_b32_e32 v38, v29
	v_mov_b32_e32 v39, v30
	v_mov_b32_e32 v34, v5
	v_mov_b32_e32 v35, v6
	v_pk_fma_f32 v[6:7], v[38:39], v[6:7], v[0:1] op_sel_hi:[1,0,1]
	v_mov_b32_e32 v0, v31
	v_pk_fma_f32 v[8:9], v[28:29], v[34:35], v[8:9] op_sel_hi:[0,1,1]
	v_pk_fma_f32 v[24:25], v[28:29], v[4:5], v[24:25] op_sel_hi:[1,0,1]
	v_pk_fma_f32 v[28:29], v[38:39], v[4:5], v[40:41] op_sel:[0,1,0]
	v_pk_fma_f32 v[26:27], v[30:31], v[4:5], v[26:27] op_sel_hi:[1,0,1]
	v_pk_fma_f32 v[10:11], v[0:1], v[34:35], v[10:11] op_sel_hi:[0,1,1]
	v_pk_fma_f32 v[4:5], v[30:31], v[36:37], v[32:33] op_sel_hi:[1,0,1]
	s_cbranch_scc0 .LBB0_1325
; DI float bflo(unsigned w) { return __uint_as_float(w << 16); }
; DI float bfhi(unsigned w) { return __uint_as_float(w & 0xffff0000u); }
; DI void gla3_phase(const P& p, int l, const bf16_t* PROJ, const float* US, bf16_t* OGLA, char* smem, int bid, int nb) {
;     ...
;       __syncthreads();
; #pragma unroll
;       for (int j = 0; j < 4; ++j) {
;         f32x4 v;
; #pragma unroll
;         for (int i = 0; i < 4; ++i) v[i] = (tx * 4 + j <= ty * 4 + i) ? a[i][j] : 0.f;
;         *(f32x4*)(KT + (tx * 4 + j) * LS + ty * 4) = v;
;       }
;     }
;     __syncthreads();
;     {
;       const int ty = tid >> 5, tx = tid & 31;
;       float o[8][8];
; #pragma unroll
;       for (int i = 0; i < 8; ++i)
; #pragma unroll
;         for (int j = 0; j < 8; ++j) o[i][j] = 0.f;
; #pragma unroll 2
;       for (int s = 0; s < 64; ++s) {
;         const f32x4 a0 = *(const f32x4*)(KT + s * LS + ty * 8), a1 = *(const f32x4*)(KT + s * LS + ty * 8 + 4);
;         const uint4 wv = *(const uint4*)(PROJ + (size_t)(c * 64 + s) * NP + C_GV + h * 256 + tx * 8);
;         const float a[8] = {a0[0], a0[1], a0[2], a0[3], a1[0], a1[1], a1[2], a1[3]};
;         const float b[8] = {bflo(wv.x), bfhi(wv.x), bflo(wv.y), bfhi(wv.y), bflo(wv.z), bfhi(wv.z), bflo(wv.w), bfhi(wv.w)};
; #pragma unroll
;         for (int i = 0; i < 8; ++i)
; #pragma unroll
;           for (int j = 0; j < 8; ++j) o[i][j] += a[i] * b[j];
	s_mul_hi_i32 s1, s12, 0x4200
	s_mulk_i32 s12, 0x4200
	s_lshl_b32 s0, s13, 9
	v_cndmask_b32_e64 v25, v25, 0, s[54:55]
	v_cndmask_b32_e64 v24, v24, 0, s[40:41]
	v_cndmask_b32_e64 v26, v26, 0, s[52:53]
	v_cndmask_b32_e64 v27, v27, 0, s[50:51]
	s_add_u32 s0, s12, s0
	s_barrier
	ds_write_b128 v103, v[24:27] offset:34816
	v_cndmask_b32_e64 v24, 0, v8, s[42:43]
	v_cndmask_b32_e64 v25, v28, 0, s[40:41]
	v_cndmask_b32_e64 v26, v29, 0, s[40:41]
	v_cndmask_b32_e64 v27, 0, v10, s[44:45]
	s_addc_u32 s1, s1, 0
	ds_write_b128 v103, v[24:27] offset:35088
	v_cndmask_b32_e64 v8, 0, v9, s[42:43]
	v_cndmask_b32_e64 v10, v7, 0, s[40:41]
	v_cndmask_b32_e64 v9, v6, 0, s[46:47]
	v_cndmask_b32_e64 v11, v11, 0, s[48:49]
	v_cndmask_b32_e64 v3, v3, 0, s[60:61]
	v_cndmask_b32_e64 v2, v2, 0, s[62:63]
	v_cndmask_b32_e64 v4, v4, 0, s[58:59]
	v_cndmask_b32_e64 v5, v5, 0, s[56:57]
	v_mov_b32_e32 v26, 0
	v_lshl_add_u64 v[0:1], v[20:21], 0, s[0:1]
	ds_write_b128 v104, v[8:11] offset:34816
	ds_write_b128 v104, v[2:5] offset:35088
	s_mov_b64 s[0:1], 0
	v_mov_b32_e32 v2, v102
	v_mov_b32_e32 v27, v26
	v_mov_b32_e32 v24, v26
	v_mov_b32_e32 v25, v26
	v_mov_b32_e32 v30, v26
	v_mov_b32_e32 v31, v26
	v_mov_b32_e32 v28, v26
	v_mov_b32_e32 v29, v26
	v_mov_b32_e32 v34, v26
	v_mov_b32_e32 v35, v26
	v_mov_b32_e32 v32, v26
	v_mov_b32_e32 v33, v26
	v_mov_b32_e32 v38, v26
	v_mov_b32_e32 v39, v26
	v_mov_b32_e32 v36, v26
	v_mov_b32_e32 v37, v26
	v_mov_b32_e32 v42, v26
	v_mov_b32_e32 v43, v26
	v_mov_b32_e32 v40, v26
	v_mov_b32_e32 v41, v26
	v_mov_b32_e32 v46, v26
	v_mov_b32_e32 v47, v26
	v_mov_b32_e32 v44, v26
	v_mov_b32_e32 v45, v26
	v_mov_b32_e32 v58, v26
	v_mov_b32_e32 v59, v26
	v_mov_b32_e32 v56, v26
	v_mov_b32_e32 v57, v26
	v_mov_b32_e32 v62, v26
	v_mov_b32_e32 v63, v26
	v_mov_b32_e32 v60, v26
	v_mov_b32_e32 v61, v26
	v_mov_b32_e32 v66, v26
	v_mov_b32_e32 v67, v26
	v_mov_b32_e32 v64, v26
	v_mov_b32_e32 v65, v26
	v_mov_b32_e32 v70, v26
	v_mov_b32_e32 v71, v26
	v_mov_b32_e32 v68, v26
	v_mov_b32_e32 v69, v26
	v_mov_b32_e32 v74, v26
	v_mov_b32_e32 v75, v26
	v_mov_b32_e32 v72, v26
	v_mov_b32_e32 v73, v26
	v_mov_b32_e32 v78, v26
	v_mov_b32_e32 v79, v26
	v_mov_b32_e32 v76, v26
	v_mov_b32_e32 v77, v26
	v_mov_b32_e32 v82, v26
	v_mov_b32_e32 v83, v26
	v_mov_b32_e32 v80, v26
	v_mov_b32_e32 v81, v26
	v_mov_b32_e32 v86, v26
	v_mov_b32_e32 v87, v26
	v_mov_b32_e32 v84, v26
	v_mov_b32_e32 v85, v26
	v_mov_b32_e32 v10, v26
	v_mov_b32_e32 v11, v26
	v_mov_b32_e32 v8, v26
	v_mov_b32_e32 v9, v26
	v_mov_b32_e32 v48, v26
	v_mov_b32_e32 v49, v26
	v_mov_b32_e32 v88, v26
	v_mov_b32_e32 v89, v26
	s_waitcnt lgkmcnt(0)
	s_barrier
	v_lshl_add_u64 v[182:183], v[0:1], 0, s[0:1]
	s_mov_b32 s12, 0x11803000
	v_add_co_u32_e32 v178, vcc, s12, v182
	s_nop 1
	v_addc_co_u32_e32 v179, vcc, 0, v183, vcc
	s_mov_b32 s12, 0x11807000
	v_add_co_u32_e32 v180, vcc, s12, v182
	s_nop 1
	v_addc_co_u32_e32 v181, vcc, 0, v183, vcc
	global_load_dwordx4 v[114:117], v[178:179], off offset:288
	global_load_dwordx4 v[118:121], v[180:181], off offset:800
	v_add_co_u32_e32 v178, vcc, 0x8400, v178
	s_nop 1
	v_addc_co_u32_e32 v179, vcc, 0, v179, vcc
	v_add_co_u32_e32 v180, vcc, 0x8400, v180
	s_nop 1
	v_addc_co_u32_e32 v181, vcc, 0, v181, vcc
	global_load_dwordx4 v[122:125], v[178:179], off offset:288
	global_load_dwordx4 v[126:129], v[180:181], off offset:800
	v_add_co_u32_e32 v178, vcc, 0x8400, v178
	s_nop 1
	v_addc_co_u32_e32 v179, vcc, 0, v179, vcc
	v_add_co_u32_e32 v180, vcc, 0x8400, v180
	s_nop 1
	v_addc_co_u32_e32 v181, vcc, 0, v181, vcc
	global_load_dwordx4 v[130:133], v[178:179], off offset:288
	global_load_dwordx4 v[134:137], v[180:181], off offset:800
	v_add_co_u32_e32 v178, vcc, 0x8400, v178
	s_nop 1
	v_addc_co_u32_e32 v179, vcc, 0, v179, vcc
	v_add_co_u32_e32 v180, vcc, 0x8400, v180
	s_nop 1
	v_addc_co_u32_e32 v181, vcc, 0, v181, vcc
	global_load_dwordx4 v[138:141], v[178:179], off offset:288
	global_load_dwordx4 v[142:145], v[180:181], off offset:800
	v_add_co_u32_e32 v178, vcc, 0x8400, v178
	s_nop 1
	v_addc_co_u32_e32 v179, vcc, 0, v179, vcc
	v_add_co_u32_e32 v180, vcc, 0x8400, v180
	s_nop 1
	v_addc_co_u32_e32 v181, vcc, 0, v181, vcc
.LBB0_1327:
	v_lshl_add_u64 v[54:55], v[0:1], 0, s[0:1]
	s_mov_b32 s12, 0x11803000
	v_add_co_u32_e32 v90, vcc, s12, v54
	ds_read_b128 v[4:7], v2
	ds_read_b128 v[50:53], v2 offset:16
	v_addc_co_u32_e32 v91, vcc, 0, v55, vcc
	s_waitcnt vmcnt(7)
	v_mov_b32_e32 v106, v114
	v_mov_b32_e32 v107, v115
	v_mov_b32_e32 v108, v116
	v_mov_b32_e32 v109, v117
	global_load_dwordx4 v[114:117], v[178:179], off offset:288
	s_waitcnt lgkmcnt(1)
	v_mov_b32_e32 v110, v7
	s_waitcnt lgkmcnt(0)
; DI float bflo(unsigned w) { return __uint_as_float(w << 16); }
; DI float bfhi(unsigned w) { return __uint_as_float(w & 0xffff0000u); }
; DI void gla3_phase(const P& p, int l, const bf16_t* PROJ, const float* US, bf16_t* OGLA, char* smem, int bid, int nb) {
;     ...
;       for (int s = 0; s < 64; ++s) {
;         const f32x4 a0 = *(const f32x4*)(KT + s * LS + ty * 8), a1 = *(const f32x4*)(KT + s * LS + ty * 8 + 4);
;         const uint4 wv = *(const uint4*)(PROJ + (size_t)(c * 64 + s) * NP + C_GV + h * 256 + tx * 8);
;         const float a[8] = {a0[0], a0[1], a0[2], a0[3], a1[0], a1[1], a1[2], a1[3]};
;         const float b[8] = {bflo(wv.x), bfhi(wv.x), bflo(wv.y), bfhi(wv.y), bflo(wv.z), bfhi(wv.z), bflo(wv.w), bfhi(wv.w)};
; #pragma unroll
;         for (int i = 0; i < 8; ++i)
; #pragma unroll
;           for (int j = 0; j < 8; ++j) o[i][j] += a[i] * b[j];
;       }
	v_mov_b32_e32 v112, v53
	s_mov_b32 s12, 0x11807000
	v_add_co_u32_e32 v54, vcc, s12, v54
	s_add_u32 s0, s0, 0x8400
	s_nop 0
	v_addc_co_u32_e32 v55, vcc, 0, v55, vcc
	s_addc_u32 s1, s1, 0
	s_cmp_eq_u32 s0, 0x108000
	s_nop 0
	v_lshlrev_b32_e32 v91, 16, v107
	v_lshlrev_b32_e32 v90, 16, v106
	v_pk_fma_f32 v[48:49], v[4:5], v[90:91], v[48:49] op_sel_hi:[0,1,1]
	v_pk_fma_f32 v[86:87], v[4:5], v[90:91], v[86:87] op_sel:[1,0,0]
	v_pk_fma_f32 v[78:79], v[6:7], v[90:91], v[78:79] op_sel_hi:[0,1,1]
	v_pk_fma_f32 v[70:71], v[110:111], v[90:91], v[70:71] op_sel_hi:[0,1,1]
	v_pk_fma_f32 v[62:63], v[50:51], v[90:91], v[62:63] op_sel_hi:[0,1,1]
	v_pk_fma_f32 v[46:47], v[50:51], v[90:91], v[46:47] op_sel:[1,0,0]
	v_pk_fma_f32 v[38:39], v[52:53], v[90:91], v[38:39] op_sel_hi:[0,1,1]
	v_pk_fma_f32 v[30:31], v[112:113], v[90:91], v[30:31] op_sel_hi:[0,1,1]
	v_and_b32_e32 v91, 0xffff0000, v107
	v_and_b32_e32 v90, 0xffff0000, v106
	v_pk_fma_f32 v[88:89], v[4:5], v[90:91], v[88:89] op_sel_hi:[0,1,1]
	v_pk_fma_f32 v[84:85], v[4:5], v[90:91], v[84:85] op_sel:[1,0,0]
	v_pk_fma_f32 v[76:77], v[6:7], v[90:91], v[76:77] op_sel_hi:[0,1,1]
	v_pk_fma_f32 v[68:69], v[110:111], v[90:91], v[68:69] op_sel_hi:[0,1,1]
	v_pk_fma_f32 v[60:61], v[50:51], v[90:91], v[60:61] op_sel_hi:[0,1,1]
	v_pk_fma_f32 v[44:45], v[50:51], v[90:91], v[44:45] op_sel:[1,0,0]
	v_pk_fma_f32 v[36:37], v[52:53], v[90:91], v[36:37] op_sel_hi:[0,1,1]
	v_pk_fma_f32 v[28:29], v[112:113], v[90:91], v[28:29] op_sel_hi:[0,1,1]
	v_lshlrev_b32_e32 v91, 16, v109
	v_lshlrev_b32_e32 v90, 16, v108
	v_pk_fma_f32 v[10:11], v[4:5], v[90:91], v[10:11] op_sel_hi:[0,1,1]
	v_pk_fma_f32 v[82:83], v[4:5], v[90:91], v[82:83] op_sel:[1,0,0]
	v_pk_fma_f32 v[74:75], v[6:7], v[90:91], v[74:75] op_sel_hi:[0,1,1]
	v_pk_fma_f32 v[66:67], v[110:111], v[90:91], v[66:67] op_sel_hi:[0,1,1]
	v_pk_fma_f32 v[58:59], v[50:51], v[90:91], v[58:59] op_sel_hi:[0,1,1]
	v_pk_fma_f32 v[42:43], v[50:51], v[90:91], v[42:43] op_sel:[1,0,0]
	v_pk_fma_f32 v[34:35], v[52:53], v[90:91], v[34:35] op_sel_hi:[0,1,1]
	v_pk_fma_f32 v[26:27], v[112:113], v[90:91], v[26:27] op_sel_hi:[0,1,1]
	v_and_b32_e32 v91, 0xffff0000, v109
	v_and_b32_e32 v90, 0xffff0000, v108
	v_pk_fma_f32 v[8:9], v[4:5], v[90:91], v[8:9] op_sel_hi:[0,1,1]
	v_pk_fma_f32 v[80:81], v[4:5], v[90:91], v[80:81] op_sel:[1,0,0]
	v_pk_fma_f32 v[72:73], v[6:7], v[90:91], v[72:73] op_sel_hi:[0,1,1]
	v_pk_fma_f32 v[106:107], v[50:51], v[90:91], v[56:57] op_sel_hi:[0,1,1]
	v_pk_fma_f32 v[40:41], v[50:51], v[90:91], v[40:41] op_sel:[1,0,0]
	v_pk_fma_f32 v[32:33], v[52:53], v[90:91], v[32:33] op_sel_hi:[0,1,1]
	ds_read_b128 v[4:7], v2 offset:272
	ds_read_b128 v[50:53], v2 offset:288
	s_waitcnt vmcnt(7)
	v_mov_b32_e32 v54, v118
	v_mov_b32_e32 v55, v119
	v_mov_b32_e32 v56, v120
	v_mov_b32_e32 v57, v121
	global_load_dwordx4 v[118:121], v[180:181], off offset:800
	v_pk_fma_f32 v[64:65], v[110:111], v[90:91], v[64:65] op_sel_hi:[0,1,1]
	v_pk_fma_f32 v[24:25], v[112:113], v[90:91], v[24:25] op_sel_hi:[0,1,1]
	s_waitcnt lgkmcnt(1)
	v_mov_b32_e32 v108, v7
	s_waitcnt lgkmcnt(0)
	v_mov_b32_e32 v110, v53
	v_add_u32_e32 v2, 0x220, v2
	s_nop 0
	v_lshlrev_b32_e32 v91, 16, v55
	v_lshlrev_b32_e32 v90, 16, v54
	v_and_b32_e32 v55, 0xffff0000, v55
	v_and_b32_e32 v54, 0xffff0000, v54
	v_pk_fma_f32 v[88:89], v[4:5], v[54:55], v[88:89] op_sel_hi:[0,1,1]
	v_pk_fma_f32 v[84:85], v[4:5], v[54:55], v[84:85] op_sel:[1,0,0]
	v_pk_fma_f32 v[76:77], v[6:7], v[54:55], v[76:77] op_sel_hi:[0,1,1]
	v_pk_fma_f32 v[68:69], v[108:109], v[54:55], v[68:69] op_sel_hi:[0,1,1]
	v_pk_fma_f32 v[60:61], v[50:51], v[54:55], v[60:61] op_sel_hi:[0,1,1]
	v_pk_fma_f32 v[44:45], v[50:51], v[54:55], v[44:45] op_sel:[1,0,0]
	v_pk_fma_f32 v[36:37], v[52:53], v[54:55], v[36:37] op_sel_hi:[0,1,1]
	v_pk_fma_f32 v[28:29], v[110:111], v[54:55], v[28:29] op_sel_hi:[0,1,1]
	v_lshlrev_b32_e32 v55, 16, v57
	v_lshlrev_b32_e32 v54, 16, v56
	v_pk_fma_f32 v[10:11], v[4:5], v[54:55], v[10:11] op_sel_hi:[0,1,1]
	v_pk_fma_f32 v[82:83], v[4:5], v[54:55], v[82:83] op_sel:[1,0,0]
	v_pk_fma_f32 v[74:75], v[6:7], v[54:55], v[74:75] op_sel_hi:[0,1,1]
	v_pk_fma_f32 v[66:67], v[108:109], v[54:55], v[66:67] op_sel_hi:[0,1,1]
	v_pk_fma_f32 v[58:59], v[50:51], v[54:55], v[58:59] op_sel_hi:[0,1,1]
	v_pk_fma_f32 v[42:43], v[50:51], v[54:55], v[42:43] op_sel:[1,0,0]
	v_pk_fma_f32 v[34:35], v[52:53], v[54:55], v[34:35] op_sel_hi:[0,1,1]
	v_pk_fma_f32 v[26:27], v[110:111], v[54:55], v[26:27] op_sel_hi:[0,1,1]
	v_and_b32_e32 v55, 0xffff0000, v57
	v_and_b32_e32 v54, 0xffff0000, v56
	v_pk_fma_f32 v[48:49], v[4:5], v[90:91], v[48:49] op_sel_hi:[0,1,1]
	v_pk_fma_f32 v[86:87], v[4:5], v[90:91], v[86:87] op_sel:[1,0,0]
	v_pk_fma_f32 v[78:79], v[6:7], v[90:91], v[78:79] op_sel_hi:[0,1,1]
	v_pk_fma_f32 v[70:71], v[108:109], v[90:91], v[70:71] op_sel_hi:[0,1,1]
	v_pk_fma_f32 v[62:63], v[50:51], v[90:91], v[62:63] op_sel_hi:[0,1,1]
	v_pk_fma_f32 v[46:47], v[50:51], v[90:91], v[46:47] op_sel:[1,0,0]
	v_pk_fma_f32 v[38:39], v[52:53], v[90:91], v[38:39] op_sel_hi:[0,1,1]
	v_pk_fma_f32 v[30:31], v[110:111], v[90:91], v[30:31] op_sel_hi:[0,1,1]
	v_pk_fma_f32 v[8:9], v[4:5], v[54:55], v[8:9] op_sel_hi:[0,1,1]
	v_pk_fma_f32 v[80:81], v[4:5], v[54:55], v[80:81] op_sel:[1,0,0]
	v_pk_fma_f32 v[72:73], v[6:7], v[54:55], v[72:73] op_sel_hi:[0,1,1]
	v_pk_fma_f32 v[64:65], v[108:109], v[54:55], v[64:65] op_sel_hi:[0,1,1]
	v_pk_fma_f32 v[56:57], v[50:51], v[54:55], v[106:107] op_sel_hi:[0,1,1]
	v_pk_fma_f32 v[40:41], v[50:51], v[54:55], v[40:41] op_sel:[1,0,0]
	v_pk_fma_f32 v[32:33], v[52:53], v[54:55], v[32:33] op_sel_hi:[0,1,1]
	v_pk_fma_f32 v[24:25], v[110:111], v[54:55], v[24:25] op_sel_hi:[0,1,1]
	v_add_co_u32_e32 v178, vcc, 0x8400, v178
	s_nop 1
	v_addc_co_u32_e32 v179, vcc, 0, v179, vcc
	v_add_co_u32_e32 v180, vcc, 0x8400, v180
	s_nop 1
	v_addc_co_u32_e32 v181, vcc, 0, v181, vcc
	v_lshl_add_u64 v[54:55], v[0:1], 0, s[0:1]
	s_mov_b32 s12, 0x11803000
	v_add_co_u32_e32 v90, vcc, s12, v54
	ds_read_b128 v[4:7], v2
	ds_read_b128 v[50:53], v2 offset:16
	v_addc_co_u32_e32 v91, vcc, 0, v55, vcc
	s_waitcnt vmcnt(7)
; DI float bflo(unsigned w) { return __uint_as_float(w << 16); }
; DI float bfhi(unsigned w) { return __uint_as_float(w & 0xffff0000u); }
; DI void gla3_phase(const P& p, int l, const bf16_t* PROJ, const float* US, bf16_t* OGLA, char* smem, int bid, int nb) {
;     ...
;       for (int s = 0; s < 64; ++s) {
;         const f32x4 a0 = *(const f32x4*)(KT + s * LS + ty * 8), a1 = *(const f32x4*)(KT + s * LS + ty * 8 + 4);
;         const uint4 wv = *(const uint4*)(PROJ + (size_t)(c * 64 + s) * NP + C_GV + h * 256 + tx * 8);
;         const float a[8] = {a0[0], a0[1], a0[2], a0[3], a1[0], a1[1], a1[2], a1[3]};
;         const float b[8] = {bflo(wv.x), bfhi(wv.x), bflo(wv.y), bfhi(wv.y), bflo(wv.z), bfhi(wv.z), bflo(wv.w), bfhi(wv.w)};
; #pragma unroll
;         for (int i = 0; i < 8; ++i)
; #pragma unroll
;           for (int j = 0; j < 8; ++j) o[i][j] += a[i] * b[j];
;       }
	v_mov_b32_e32 v106, v122
	v_mov_b32_e32 v107, v123
	v_mov_b32_e32 v108, v124
	v_mov_b32_e32 v109, v125
	global_load_dwordx4 v[122:125], v[178:179], off offset:288
	s_waitcnt lgkmcnt(1)
	v_mov_b32_e32 v110, v7
	s_waitcnt lgkmcnt(0)
	v_mov_b32_e32 v112, v53
	s_mov_b32 s12, 0x11807000
	v_add_co_u32_e32 v54, vcc, s12, v54
	s_add_u32 s0, s0, 0x8400
	s_nop 0
	v_addc_co_u32_e32 v55, vcc, 0, v55, vcc
	s_addc_u32 s1, s1, 0
	s_cmp_eq_u32 s0, 0x108000
	s_nop 0
	v_lshlrev_b32_e32 v91, 16, v107
	v_lshlrev_b32_e32 v90, 16, v106
	v_pk_fma_f32 v[48:49], v[4:5], v[90:91], v[48:49] op_sel_hi:[0,1,1]
	v_pk_fma_f32 v[86:87], v[4:5], v[90:91], v[86:87] op_sel:[1,0,0]
	v_pk_fma_f32 v[78:79], v[6:7], v[90:91], v[78:79] op_sel_hi:[0,1,1]
	v_pk_fma_f32 v[70:71], v[110:111], v[90:91], v[70:71] op_sel_hi:[0,1,1]
	v_pk_fma_f32 v[62:63], v[50:51], v[90:91], v[62:63] op_sel_hi:[0,1,1]
	v_pk_fma_f32 v[46:47], v[50:51], v[90:91], v[46:47] op_sel:[1,0,0]
	v_pk_fma_f32 v[38:39], v[52:53], v[90:91], v[38:39] op_sel_hi:[0,1,1]
	v_pk_fma_f32 v[30:31], v[112:113], v[90:91], v[30:31] op_sel_hi:[0,1,1]
	v_and_b32_e32 v91, 0xffff0000, v107
	v_and_b32_e32 v90, 0xffff0000, v106
	v_pk_fma_f32 v[88:89], v[4:5], v[90:91], v[88:89] op_sel_hi:[0,1,1]
	v_pk_fma_f32 v[84:85], v[4:5], v[90:91], v[84:85] op_sel:[1,0,0]
	v_pk_fma_f32 v[76:77], v[6:7], v[90:91], v[76:77] op_sel_hi:[0,1,1]
	v_pk_fma_f32 v[68:69], v[110:111], v[90:91], v[68:69] op_sel_hi:[0,1,1]
	v_pk_fma_f32 v[60:61], v[50:51], v[90:91], v[60:61] op_sel_hi:[0,1,1]
	v_pk_fma_f32 v[44:45], v[50:51], v[90:91], v[44:45] op_sel:[1,0,0]
	v_pk_fma_f32 v[36:37], v[52:53], v[90:91], v[36:37] op_sel_hi:[0,1,1]
	v_pk_fma_f32 v[28:29], v[112:113], v[90:91], v[28:29] op_sel_hi:[0,1,1]
	v_lshlrev_b32_e32 v91, 16, v109
	v_lshlrev_b32_e32 v90, 16, v108
	v_pk_fma_f32 v[10:11], v[4:5], v[90:91], v[10:11] op_sel_hi:[0,1,1]
	v_pk_fma_f32 v[82:83], v[4:5], v[90:91], v[82:83] op_sel:[1,0,0]
	v_pk_fma_f32 v[74:75], v[6:7], v[90:91], v[74:75] op_sel_hi:[0,1,1]
	v_pk_fma_f32 v[66:67], v[110:111], v[90:91], v[66:67] op_sel_hi:[0,1,1]
	v_pk_fma_f32 v[58:59], v[50:51], v[90:91], v[58:59] op_sel_hi:[0,1,1]
	v_pk_fma_f32 v[42:43], v[50:51], v[90:91], v[42:43] op_sel:[1,0,0]
	v_pk_fma_f32 v[34:35], v[52:53], v[90:91], v[34:35] op_sel_hi:[0,1,1]
	v_pk_fma_f32 v[26:27], v[112:113], v[90:91], v[26:27] op_sel_hi:[0,1,1]
	v_and_b32_e32 v91, 0xffff0000, v109
	v_and_b32_e32 v90, 0xffff0000, v108
	v_pk_fma_f32 v[8:9], v[4:5], v[90:91], v[8:9] op_sel_hi:[0,1,1]
	v_pk_fma_f32 v[80:81], v[4:5], v[90:91], v[80:81] op_sel:[1,0,0]
	v_pk_fma_f32 v[72:73], v[6:7], v[90:91], v[72:73] op_sel_hi:[0,1,1]
	v_pk_fma_f32 v[106:107], v[50:51], v[90:91], v[56:57] op_sel_hi:[0,1,1]
	v_pk_fma_f32 v[40:41], v[50:51], v[90:91], v[40:41] op_sel:[1,0,0]
	v_pk_fma_f32 v[32:33], v[52:53], v[90:91], v[32:33] op_sel_hi:[0,1,1]
	ds_read_b128 v[4:7], v2 offset:272
	ds_read_b128 v[50:53], v2 offset:288
	s_waitcnt vmcnt(7)
	v_mov_b32_e32 v54, v126
	v_mov_b32_e32 v55, v127
	v_mov_b32_e32 v56, v128
	v_mov_b32_e32 v57, v129
	global_load_dwordx4 v[126:129], v[180:181], off offset:800
	v_pk_fma_f32 v[64:65], v[110:111], v[90:91], v[64:65] op_sel_hi:[0,1,1]
	v_pk_fma_f32 v[24:25], v[112:113], v[90:91], v[24:25] op_sel_hi:[0,1,1]
	s_waitcnt lgkmcnt(1)
	v_mov_b32_e32 v108, v7
	s_waitcnt lgkmcnt(0)
	v_mov_b32_e32 v110, v53
	v_add_u32_e32 v2, 0x220, v2
	s_nop 0
	v_lshlrev_b32_e32 v91, 16, v55
	v_lshlrev_b32_e32 v90, 16, v54
	v_and_b32_e32 v55, 0xffff0000, v55
	v_and_b32_e32 v54, 0xffff0000, v54
	v_pk_fma_f32 v[88:89], v[4:5], v[54:55], v[88:89] op_sel_hi:[0,1,1]
	v_pk_fma_f32 v[84:85], v[4:5], v[54:55], v[84:85] op_sel:[1,0,0]
	v_pk_fma_f32 v[76:77], v[6:7], v[54:55], v[76:77] op_sel_hi:[0,1,1]
	v_pk_fma_f32 v[68:69], v[108:109], v[54:55], v[68:69] op_sel_hi:[0,1,1]
	v_pk_fma_f32 v[60:61], v[50:51], v[54:55], v[60:61] op_sel_hi:[0,1,1]
	v_pk_fma_f32 v[44:45], v[50:51], v[54:55], v[44:45] op_sel:[1,0,0]
	v_pk_fma_f32 v[36:37], v[52:53], v[54:55], v[36:37] op_sel_hi:[0,1,1]
	v_pk_fma_f32 v[28:29], v[110:111], v[54:55], v[28:29] op_sel_hi:[0,1,1]
	v_lshlrev_b32_e32 v55, 16, v57
	v_lshlrev_b32_e32 v54, 16, v56
	v_pk_fma_f32 v[10:11], v[4:5], v[54:55], v[10:11] op_sel_hi:[0,1,1]
	v_pk_fma_f32 v[82:83], v[4:5], v[54:55], v[82:83] op_sel:[1,0,0]
	v_pk_fma_f32 v[74:75], v[6:7], v[54:55], v[74:75] op_sel_hi:[0,1,1]
	v_pk_fma_f32 v[66:67], v[108:109], v[54:55], v[66:67] op_sel_hi:[0,1,1]
	v_pk_fma_f32 v[58:59], v[50:51], v[54:55], v[58:59] op_sel_hi:[0,1,1]
	v_pk_fma_f32 v[42:43], v[50:51], v[54:55], v[42:43] op_sel:[1,0,0]
	v_pk_fma_f32 v[34:35], v[52:53], v[54:55], v[34:35] op_sel_hi:[0,1,1]
	v_pk_fma_f32 v[26:27], v[110:111], v[54:55], v[26:27] op_sel_hi:[0,1,1]
	v_and_b32_e32 v55, 0xffff0000, v57
	v_and_b32_e32 v54, 0xffff0000, v56
	v_pk_fma_f32 v[48:49], v[4:5], v[90:91], v[48:49] op_sel_hi:[0,1,1]
	v_pk_fma_f32 v[86:87], v[4:5], v[90:91], v[86:87] op_sel:[1,0,0]
	v_pk_fma_f32 v[78:79], v[6:7], v[90:91], v[78:79] op_sel_hi:[0,1,1]
	v_pk_fma_f32 v[70:71], v[108:109], v[90:91], v[70:71] op_sel_hi:[0,1,1]
	v_pk_fma_f32 v[62:63], v[50:51], v[90:91], v[62:63] op_sel_hi:[0,1,1]
	v_pk_fma_f32 v[46:47], v[50:51], v[90:91], v[46:47] op_sel:[1,0,0]
	v_pk_fma_f32 v[38:39], v[52:53], v[90:91], v[38:39] op_sel_hi:[0,1,1]
	v_pk_fma_f32 v[30:31], v[110:111], v[90:91], v[30:31] op_sel_hi:[0,1,1]
	v_pk_fma_f32 v[8:9], v[4:5], v[54:55], v[8:9] op_sel_hi:[0,1,1]
	v_pk_fma_f32 v[80:81], v[4:5], v[54:55], v[80:81] op_sel:[1,0,0]
	v_pk_fma_f32 v[72:73], v[6:7], v[54:55], v[72:73] op_sel_hi:[0,1,1]
	v_pk_fma_f32 v[64:65], v[108:109], v[54:55], v[64:65] op_sel_hi:[0,1,1]
	v_pk_fma_f32 v[56:57], v[50:51], v[54:55], v[106:107] op_sel_hi:[0,1,1]
	v_pk_fma_f32 v[40:41], v[50:51], v[54:55], v[40:41] op_sel:[1,0,0]
	v_pk_fma_f32 v[32:33], v[52:53], v[54:55], v[32:33] op_sel_hi:[0,1,1]
	v_pk_fma_f32 v[24:25], v[110:111], v[54:55], v[24:25] op_sel_hi:[0,1,1]
	v_add_co_u32_e32 v178, vcc, 0x8400, v178
	s_nop 1
	v_addc_co_u32_e32 v179, vcc, 0, v179, vcc
	v_add_co_u32_e32 v180, vcc, 0x8400, v180
	s_nop 1
	v_addc_co_u32_e32 v181, vcc, 0, v181, vcc
	v_lshl_add_u64 v[54:55], v[0:1], 0, s[0:1]
	s_mov_b32 s12, 0x11803000
	v_add_co_u32_e32 v90, vcc, s12, v54
	ds_read_b128 v[4:7], v2
	ds_read_b128 v[50:53], v2 offset:16
	v_addc_co_u32_e32 v91, vcc, 0, v55, vcc
	s_waitcnt vmcnt(7)
; DI float bflo(unsigned w) { return __uint_as_float(w << 16); }
; DI float bfhi(unsigned w) { return __uint_as_float(w & 0xffff0000u); }
; DI void gla3_phase(const P& p, int l, const bf16_t* PROJ, const float* US, bf16_t* OGLA, char* smem, int bid, int nb) {
;     ...
;       for (int s = 0; s < 64; ++s) {
;         const f32x4 a0 = *(const f32x4*)(KT + s * LS + ty * 8), a1 = *(const f32x4*)(KT + s * LS + ty * 8 + 4);
;         const uint4 wv = *(const uint4*)(PROJ + (size_t)(c * 64 + s) * NP + C_GV + h * 256 + tx * 8);
;         const float a[8] = {a0[0], a0[1], a0[2], a0[3], a1[0], a1[1], a1[2], a1[3]};
;         const float b[8] = {bflo(wv.x), bfhi(wv.x), bflo(wv.y), bfhi(wv.y), bflo(wv.z), bfhi(wv.z), bflo(wv.w), bfhi(wv.w)};
; #pragma unroll
;         for (int i = 0; i < 8; ++i)
; #pragma unroll
;           for (int j = 0; j < 8; ++j) o[i][j] += a[i] * b[j];
;       }
	v_mov_b32_e32 v106, v130
	v_mov_b32_e32 v107, v131
	v_mov_b32_e32 v108, v132
	v_mov_b32_e32 v109, v133
	global_load_dwordx4 v[130:133], v[178:179], off offset:288
	s_waitcnt lgkmcnt(1)
	v_mov_b32_e32 v110, v7
	s_waitcnt lgkmcnt(0)
	v_mov_b32_e32 v112, v53
	s_mov_b32 s12, 0x11807000
	v_add_co_u32_e32 v54, vcc, s12, v54
	s_add_u32 s0, s0, 0x8400
	s_nop 0
	v_addc_co_u32_e32 v55, vcc, 0, v55, vcc
	s_addc_u32 s1, s1, 0
	s_cmp_eq_u32 s0, 0x108000
	s_nop 0
	v_lshlrev_b32_e32 v91, 16, v107
	v_lshlrev_b32_e32 v90, 16, v106
	v_pk_fma_f32 v[48:49], v[4:5], v[90:91], v[48:49] op_sel_hi:[0,1,1]
	v_pk_fma_f32 v[86:87], v[4:5], v[90:91], v[86:87] op_sel:[1,0,0]
	v_pk_fma_f32 v[78:79], v[6:7], v[90:91], v[78:79] op_sel_hi:[0,1,1]
	v_pk_fma_f32 v[70:71], v[110:111], v[90:91], v[70:71] op_sel_hi:[0,1,1]
	v_pk_fma_f32 v[62:63], v[50:51], v[90:91], v[62:63] op_sel_hi:[0,1,1]
	v_pk_fma_f32 v[46:47], v[50:51], v[90:91], v[46:47] op_sel:[1,0,0]
	v_pk_fma_f32 v[38:39], v[52:53], v[90:91], v[38:39] op_sel_hi:[0,1,1]
	v_pk_fma_f32 v[30:31], v[112:113], v[90:91], v[30:31] op_sel_hi:[0,1,1]
	v_and_b32_e32 v91, 0xffff0000, v107
	v_and_b32_e32 v90, 0xffff0000, v106
	v_pk_fma_f32 v[88:89], v[4:5], v[90:91], v[88:89] op_sel_hi:[0,1,1]
	v_pk_fma_f32 v[84:85], v[4:5], v[90:91], v[84:85] op_sel:[1,0,0]
	v_pk_fma_f32 v[76:77], v[6:7], v[90:91], v[76:77] op_sel_hi:[0,1,1]
	v_pk_fma_f32 v[68:69], v[110:111], v[90:91], v[68:69] op_sel_hi:[0,1,1]
	v_pk_fma_f32 v[60:61], v[50:51], v[90:91], v[60:61] op_sel_hi:[0,1,1]
	v_pk_fma_f32 v[44:45], v[50:51], v[90:91], v[44:45] op_sel:[1,0,0]
	v_pk_fma_f32 v[36:37], v[52:53], v[90:91], v[36:37] op_sel_hi:[0,1,1]
	v_pk_fma_f32 v[28:29], v[112:113], v[90:91], v[28:29] op_sel_hi:[0,1,1]
	v_lshlrev_b32_e32 v91, 16, v109
	v_lshlrev_b32_e32 v90, 16, v108
	v_pk_fma_f32 v[10:11], v[4:5], v[90:91], v[10:11] op_sel_hi:[0,1,1]
	v_pk_fma_f32 v[82:83], v[4:5], v[90:91], v[82:83] op_sel:[1,0,0]
	v_pk_fma_f32 v[74:75], v[6:7], v[90:91], v[74:75] op_sel_hi:[0,1,1]
	v_pk_fma_f32 v[66:67], v[110:111], v[90:91], v[66:67] op_sel_hi:[0,1,1]
	v_pk_fma_f32 v[58:59], v[50:51], v[90:91], v[58:59] op_sel_hi:[0,1,1]
	v_pk_fma_f32 v[42:43], v[50:51], v[90:91], v[42:43] op_sel:[1,0,0]
	v_pk_fma_f32 v[34:35], v[52:53], v[90:91], v[34:35] op_sel_hi:[0,1,1]
	v_pk_fma_f32 v[26:27], v[112:113], v[90:91], v[26:27] op_sel_hi:[0,1,1]
	v_and_b32_e32 v91, 0xffff0000, v109
	v_and_b32_e32 v90, 0xffff0000, v108
	v_pk_fma_f32 v[8:9], v[4:5], v[90:91], v[8:9] op_sel_hi:[0,1,1]
	v_pk_fma_f32 v[80:81], v[4:5], v[90:91], v[80:81] op_sel:[1,0,0]
	v_pk_fma_f32 v[72:73], v[6:7], v[90:91], v[72:73] op_sel_hi:[0,1,1]
	v_pk_fma_f32 v[106:107], v[50:51], v[90:91], v[56:57] op_sel_hi:[0,1,1]
	v_pk_fma_f32 v[40:41], v[50:51], v[90:91], v[40:41] op_sel:[1,0,0]
	v_pk_fma_f32 v[32:33], v[52:53], v[90:91], v[32:33] op_sel_hi:[0,1,1]
	ds_read_b128 v[4:7], v2 offset:272
	ds_read_b128 v[50:53], v2 offset:288
	s_waitcnt vmcnt(7)
	v_mov_b32_e32 v54, v134
	v_mov_b32_e32 v55, v135
	v_mov_b32_e32 v56, v136
	v_mov_b32_e32 v57, v137
	global_load_dwordx4 v[134:137], v[180:181], off offset:800
	v_pk_fma_f32 v[64:65], v[110:111], v[90:91], v[64:65] op_sel_hi:[0,1,1]
	v_pk_fma_f32 v[24:25], v[112:113], v[90:91], v[24:25] op_sel_hi:[0,1,1]
	s_waitcnt lgkmcnt(1)
	v_mov_b32_e32 v108, v7
	s_waitcnt lgkmcnt(0)
	v_mov_b32_e32 v110, v53
	v_add_u32_e32 v2, 0x220, v2
	s_nop 0
	v_lshlrev_b32_e32 v91, 16, v55
	v_lshlrev_b32_e32 v90, 16, v54
	v_and_b32_e32 v55, 0xffff0000, v55
	v_and_b32_e32 v54, 0xffff0000, v54
	v_pk_fma_f32 v[88:89], v[4:5], v[54:55], v[88:89] op_sel_hi:[0,1,1]
	v_pk_fma_f32 v[84:85], v[4:5], v[54:55], v[84:85] op_sel:[1,0,0]
	v_pk_fma_f32 v[76:77], v[6:7], v[54:55], v[76:77] op_sel_hi:[0,1,1]
	v_pk_fma_f32 v[68:69], v[108:109], v[54:55], v[68:69] op_sel_hi:[0,1,1]
	v_pk_fma_f32 v[60:61], v[50:51], v[54:55], v[60:61] op_sel_hi:[0,1,1]
	v_pk_fma_f32 v[44:45], v[50:51], v[54:55], v[44:45] op_sel:[1,0,0]
	v_pk_fma_f32 v[36:37], v[52:53], v[54:55], v[36:37] op_sel_hi:[0,1,1]
	v_pk_fma_f32 v[28:29], v[110:111], v[54:55], v[28:29] op_sel_hi:[0,1,1]
	v_lshlrev_b32_e32 v55, 16, v57
	v_lshlrev_b32_e32 v54, 16, v56
	v_pk_fma_f32 v[10:11], v[4:5], v[54:55], v[10:11] op_sel_hi:[0,1,1]
	v_pk_fma_f32 v[82:83], v[4:5], v[54:55], v[82:83] op_sel:[1,0,0]
	v_pk_fma_f32 v[74:75], v[6:7], v[54:55], v[74:75] op_sel_hi:[0,1,1]
	v_pk_fma_f32 v[66:67], v[108:109], v[54:55], v[66:67] op_sel_hi:[0,1,1]
	v_pk_fma_f32 v[58:59], v[50:51], v[54:55], v[58:59] op_sel_hi:[0,1,1]
	v_pk_fma_f32 v[42:43], v[50:51], v[54:55], v[42:43] op_sel:[1,0,0]
	v_pk_fma_f32 v[34:35], v[52:53], v[54:55], v[34:35] op_sel_hi:[0,1,1]
	v_pk_fma_f32 v[26:27], v[110:111], v[54:55], v[26:27] op_sel_hi:[0,1,1]
	v_and_b32_e32 v55, 0xffff0000, v57
	v_and_b32_e32 v54, 0xffff0000, v56
	v_pk_fma_f32 v[48:49], v[4:5], v[90:91], v[48:49] op_sel_hi:[0,1,1]
	v_pk_fma_f32 v[86:87], v[4:5], v[90:91], v[86:87] op_sel:[1,0,0]
	v_pk_fma_f32 v[78:79], v[6:7], v[90:91], v[78:79] op_sel_hi:[0,1,1]
	v_pk_fma_f32 v[70:71], v[108:109], v[90:91], v[70:71] op_sel_hi:[0,1,1]
	v_pk_fma_f32 v[62:63], v[50:51], v[90:91], v[62:63] op_sel_hi:[0,1,1]
	v_pk_fma_f32 v[46:47], v[50:51], v[90:91], v[46:47] op_sel:[1,0,0]
	v_pk_fma_f32 v[38:39], v[52:53], v[90:91], v[38:39] op_sel_hi:[0,1,1]
	v_pk_fma_f32 v[30:31], v[110:111], v[90:91], v[30:31] op_sel_hi:[0,1,1]
	v_pk_fma_f32 v[8:9], v[4:5], v[54:55], v[8:9] op_sel_hi:[0,1,1]
	v_pk_fma_f32 v[80:81], v[4:5], v[54:55], v[80:81] op_sel:[1,0,0]
	v_pk_fma_f32 v[72:73], v[6:7], v[54:55], v[72:73] op_sel_hi:[0,1,1]
	v_pk_fma_f32 v[64:65], v[108:109], v[54:55], v[64:65] op_sel_hi:[0,1,1]
	v_pk_fma_f32 v[56:57], v[50:51], v[54:55], v[106:107] op_sel_hi:[0,1,1]
	v_pk_fma_f32 v[40:41], v[50:51], v[54:55], v[40:41] op_sel:[1,0,0]
	v_pk_fma_f32 v[32:33], v[52:53], v[54:55], v[32:33] op_sel_hi:[0,1,1]
	v_pk_fma_f32 v[24:25], v[110:111], v[54:55], v[24:25] op_sel_hi:[0,1,1]
	v_add_co_u32_e32 v178, vcc, 0x8400, v178
	s_nop 1
	v_addc_co_u32_e32 v179, vcc, 0, v179, vcc
	v_add_co_u32_e32 v180, vcc, 0x8400, v180
	s_nop 1
	v_addc_co_u32_e32 v181, vcc, 0, v181, vcc
	v_lshl_add_u64 v[54:55], v[0:1], 0, s[0:1]
	s_mov_b32 s12, 0x11803000
	v_add_co_u32_e32 v90, vcc, s12, v54
	ds_read_b128 v[4:7], v2
	ds_read_b128 v[50:53], v2 offset:16
	v_addc_co_u32_e32 v91, vcc, 0, v55, vcc
	s_waitcnt vmcnt(7)
; DI float bflo(unsigned w) { return __uint_as_float(w << 16); }
; DI float bfhi(unsigned w) { return __uint_as_float(w & 0xffff0000u); }
; DI void gla3_phase(const P& p, int l, const bf16_t* PROJ, const float* US, bf16_t* OGLA, char* smem, int bid, int nb) {
;     ...
;       for (int s = 0; s < 64; ++s) {
;         const f32x4 a0 = *(const f32x4*)(KT + s * LS + ty * 8), a1 = *(const f32x4*)(KT + s * LS + ty * 8 + 4);
;         const uint4 wv = *(const uint4*)(PROJ + (size_t)(c * 64 + s) * NP + C_GV + h * 256 + tx * 8);
;         const float a[8] = {a0[0], a0[1], a0[2], a0[3], a1[0], a1[1], a1[2], a1[3]};
;         const float b[8] = {bflo(wv.x), bfhi(wv.x), bflo(wv.y), bfhi(wv.y), bflo(wv.z), bfhi(wv.z), bflo(wv.w), bfhi(wv.w)};
; #pragma unroll
;         for (int i = 0; i < 8; ++i)
; #pragma unroll
;           for (int j = 0; j < 8; ++j) o[i][j] += a[i] * b[j];
;       }
	v_mov_b32_e32 v106, v138
	v_mov_b32_e32 v107, v139
	v_mov_b32_e32 v108, v140
	v_mov_b32_e32 v109, v141
	global_load_dwordx4 v[138:141], v[178:179], off offset:288
	s_waitcnt lgkmcnt(1)
	v_mov_b32_e32 v110, v7
	s_waitcnt lgkmcnt(0)
	v_mov_b32_e32 v112, v53
	s_mov_b32 s12, 0x11807000
	v_add_co_u32_e32 v54, vcc, s12, v54
	s_add_u32 s0, s0, 0x8400
	s_nop 0
	v_addc_co_u32_e32 v55, vcc, 0, v55, vcc
	s_addc_u32 s1, s1, 0
	s_cmp_eq_u32 s0, 0x108000
	s_nop 0
	v_lshlrev_b32_e32 v91, 16, v107
	v_lshlrev_b32_e32 v90, 16, v106
	v_pk_fma_f32 v[48:49], v[4:5], v[90:91], v[48:49] op_sel_hi:[0,1,1]
	v_pk_fma_f32 v[86:87], v[4:5], v[90:91], v[86:87] op_sel:[1,0,0]
	v_pk_fma_f32 v[78:79], v[6:7], v[90:91], v[78:79] op_sel_hi:[0,1,1]
	v_pk_fma_f32 v[70:71], v[110:111], v[90:91], v[70:71] op_sel_hi:[0,1,1]
	v_pk_fma_f32 v[62:63], v[50:51], v[90:91], v[62:63] op_sel_hi:[0,1,1]
	v_pk_fma_f32 v[46:47], v[50:51], v[90:91], v[46:47] op_sel:[1,0,0]
	v_pk_fma_f32 v[38:39], v[52:53], v[90:91], v[38:39] op_sel_hi:[0,1,1]
	v_pk_fma_f32 v[30:31], v[112:113], v[90:91], v[30:31] op_sel_hi:[0,1,1]
	v_and_b32_e32 v91, 0xffff0000, v107
	v_and_b32_e32 v90, 0xffff0000, v106
	v_pk_fma_f32 v[88:89], v[4:5], v[90:91], v[88:89] op_sel_hi:[0,1,1]
	v_pk_fma_f32 v[84:85], v[4:5], v[90:91], v[84:85] op_sel:[1,0,0]
	v_pk_fma_f32 v[76:77], v[6:7], v[90:91], v[76:77] op_sel_hi:[0,1,1]
	v_pk_fma_f32 v[68:69], v[110:111], v[90:91], v[68:69] op_sel_hi:[0,1,1]
	v_pk_fma_f32 v[60:61], v[50:51], v[90:91], v[60:61] op_sel_hi:[0,1,1]
	v_pk_fma_f32 v[44:45], v[50:51], v[90:91], v[44:45] op_sel:[1,0,0]
	v_pk_fma_f32 v[36:37], v[52:53], v[90:91], v[36:37] op_sel_hi:[0,1,1]
	v_pk_fma_f32 v[28:29], v[112:113], v[90:91], v[28:29] op_sel_hi:[0,1,1]
	v_lshlrev_b32_e32 v91, 16, v109
	v_lshlrev_b32_e32 v90, 16, v108
	v_pk_fma_f32 v[10:11], v[4:5], v[90:91], v[10:11] op_sel_hi:[0,1,1]
	v_pk_fma_f32 v[82:83], v[4:5], v[90:91], v[82:83] op_sel:[1,0,0]
	v_pk_fma_f32 v[74:75], v[6:7], v[90:91], v[74:75] op_sel_hi:[0,1,1]
	v_pk_fma_f32 v[66:67], v[110:111], v[90:91], v[66:67] op_sel_hi:[0,1,1]
	v_pk_fma_f32 v[58:59], v[50:51], v[90:91], v[58:59] op_sel_hi:[0,1,1]
	v_pk_fma_f32 v[42:43], v[50:51], v[90:91], v[42:43] op_sel:[1,0,0]
	v_pk_fma_f32 v[34:35], v[52:53], v[90:91], v[34:35] op_sel_hi:[0,1,1]
	v_pk_fma_f32 v[26:27], v[112:113], v[90:91], v[26:27] op_sel_hi:[0,1,1]
	v_and_b32_e32 v91, 0xffff0000, v109
	v_and_b32_e32 v90, 0xffff0000, v108
	v_pk_fma_f32 v[8:9], v[4:5], v[90:91], v[8:9] op_sel_hi:[0,1,1]
	v_pk_fma_f32 v[80:81], v[4:5], v[90:91], v[80:81] op_sel:[1,0,0]
	v_pk_fma_f32 v[72:73], v[6:7], v[90:91], v[72:73] op_sel_hi:[0,1,1]
	v_pk_fma_f32 v[106:107], v[50:51], v[90:91], v[56:57] op_sel_hi:[0,1,1]
	v_pk_fma_f32 v[40:41], v[50:51], v[90:91], v[40:41] op_sel:[1,0,0]
	v_pk_fma_f32 v[32:33], v[52:53], v[90:91], v[32:33] op_sel_hi:[0,1,1]
	ds_read_b128 v[4:7], v2 offset:272
	ds_read_b128 v[50:53], v2 offset:288
	s_waitcnt vmcnt(7)
	v_mov_b32_e32 v54, v142
	v_mov_b32_e32 v55, v143
	v_mov_b32_e32 v56, v144
	v_mov_b32_e32 v57, v145
	global_load_dwordx4 v[142:145], v[180:181], off offset:800
	v_pk_fma_f32 v[64:65], v[110:111], v[90:91], v[64:65] op_sel_hi:[0,1,1]
	v_pk_fma_f32 v[24:25], v[112:113], v[90:91], v[24:25] op_sel_hi:[0,1,1]
	s_waitcnt lgkmcnt(1)
	v_mov_b32_e32 v108, v7
	s_waitcnt lgkmcnt(0)
	v_mov_b32_e32 v110, v53
	v_add_u32_e32 v2, 0x220, v2
	s_nop 0
	v_lshlrev_b32_e32 v91, 16, v55
	v_lshlrev_b32_e32 v90, 16, v54
	v_and_b32_e32 v55, 0xffff0000, v55
	v_and_b32_e32 v54, 0xffff0000, v54
	v_pk_fma_f32 v[88:89], v[4:5], v[54:55], v[88:89] op_sel_hi:[0,1,1]
	v_pk_fma_f32 v[84:85], v[4:5], v[54:55], v[84:85] op_sel:[1,0,0]
	v_pk_fma_f32 v[76:77], v[6:7], v[54:55], v[76:77] op_sel_hi:[0,1,1]
	v_pk_fma_f32 v[68:69], v[108:109], v[54:55], v[68:69] op_sel_hi:[0,1,1]
	v_pk_fma_f32 v[60:61], v[50:51], v[54:55], v[60:61] op_sel_hi:[0,1,1]
	v_pk_fma_f32 v[44:45], v[50:51], v[54:55], v[44:45] op_sel:[1,0,0]
	v_pk_fma_f32 v[36:37], v[52:53], v[54:55], v[36:37] op_sel_hi:[0,1,1]
	v_pk_fma_f32 v[28:29], v[110:111], v[54:55], v[28:29] op_sel_hi:[0,1,1]
	v_lshlrev_b32_e32 v55, 16, v57
	v_lshlrev_b32_e32 v54, 16, v56
	v_pk_fma_f32 v[10:11], v[4:5], v[54:55], v[10:11] op_sel_hi:[0,1,1]
	v_pk_fma_f32 v[82:83], v[4:5], v[54:55], v[82:83] op_sel:[1,0,0]
	v_pk_fma_f32 v[74:75], v[6:7], v[54:55], v[74:75] op_sel_hi:[0,1,1]
	v_pk_fma_f32 v[66:67], v[108:109], v[54:55], v[66:67] op_sel_hi:[0,1,1]
	v_pk_fma_f32 v[58:59], v[50:51], v[54:55], v[58:59] op_sel_hi:[0,1,1]
	v_pk_fma_f32 v[42:43], v[50:51], v[54:55], v[42:43] op_sel:[1,0,0]
	v_pk_fma_f32 v[34:35], v[52:53], v[54:55], v[34:35] op_sel_hi:[0,1,1]
	v_pk_fma_f32 v[26:27], v[110:111], v[54:55], v[26:27] op_sel_hi:[0,1,1]
	v_and_b32_e32 v55, 0xffff0000, v57
	v_and_b32_e32 v54, 0xffff0000, v56
	v_pk_fma_f32 v[48:49], v[4:5], v[90:91], v[48:49] op_sel_hi:[0,1,1]
	v_pk_fma_f32 v[86:87], v[4:5], v[90:91], v[86:87] op_sel:[1,0,0]
	v_pk_fma_f32 v[78:79], v[6:7], v[90:91], v[78:79] op_sel_hi:[0,1,1]
	v_pk_fma_f32 v[70:71], v[108:109], v[90:91], v[70:71] op_sel_hi:[0,1,1]
	v_pk_fma_f32 v[62:63], v[50:51], v[90:91], v[62:63] op_sel_hi:[0,1,1]
	v_pk_fma_f32 v[46:47], v[50:51], v[90:91], v[46:47] op_sel:[1,0,0]
	v_pk_fma_f32 v[38:39], v[52:53], v[90:91], v[38:39] op_sel_hi:[0,1,1]
	v_pk_fma_f32 v[30:31], v[110:111], v[90:91], v[30:31] op_sel_hi:[0,1,1]
	v_pk_fma_f32 v[8:9], v[4:5], v[54:55], v[8:9] op_sel_hi:[0,1,1]
	v_pk_fma_f32 v[80:81], v[4:5], v[54:55], v[80:81] op_sel:[1,0,0]
	v_pk_fma_f32 v[72:73], v[6:7], v[54:55], v[72:73] op_sel_hi:[0,1,1]
	v_pk_fma_f32 v[64:65], v[108:109], v[54:55], v[64:65] op_sel_hi:[0,1,1]
	v_pk_fma_f32 v[56:57], v[50:51], v[54:55], v[106:107] op_sel_hi:[0,1,1]
	v_pk_fma_f32 v[40:41], v[50:51], v[54:55], v[40:41] op_sel:[1,0,0]
	v_pk_fma_f32 v[32:33], v[52:53], v[54:55], v[32:33] op_sel_hi:[0,1,1]
	v_pk_fma_f32 v[24:25], v[110:111], v[54:55], v[24:25] op_sel_hi:[0,1,1]
	v_add_co_u32_e32 v178, vcc, 0x8400, v178
	s_nop 1
	v_addc_co_u32_e32 v179, vcc, 0, v179, vcc
	v_add_co_u32_e32 v180, vcc, 0x8400, v180
	s_nop 1
	v_addc_co_u32_e32 v181, vcc, 0, v181, vcc
	s_cbranch_scc0 .LBB0_1327
; DI void gla3_phase(const P& p, int l, const bf16_t* PROJ, const float* US, bf16_t* OGLA, char* smem, int bid, int nb) {
;     ...
;       const float* Sp = US + (size_t)(c * 4 + h) * 128 * 256 + tx * 8;
; #pragma unroll 2
;       for (int kk = 0; kk < 128; ++kk) {
;         const f32x4 a0 = *(const f32x4*)(QT + kk * LS + ty * 8), a1 = *(const f32x4*)(QT + kk * LS + ty * 8 + 4);
;         const f32x4 b0 = *(const f32x4*)(Sp + (size_t)kk * 256), b1 = *(const f32x4*)(Sp + (size_t)kk * 256 + 4);
;         const float a[8] = {a0[0], a0[1], a0[2], a0[3], a1[0], a1[1], a1[2], a1[3]}, b[8] = {b0[0], b0[1], b0[2], b0[3], b1[0], b1[1], b1[2], b1[3]};
; #pragma unroll
;         for (int i = 0; i < 8; ++i)
; #pragma unroll
;           for (int j = 0; j < 8; ++j) o[i][j] += a[i] * b[j];
;       }
	s_waitcnt vmcnt(0)
	s_mov_b32 s0, 0
	v_mov_b64_e32 v[0:1], v[22:23]
	s_mov_b64 s[12:13], 0x800
	v_mov_b64_e32 v[178:179], v[0:1]
	global_load_dwordx4 v[114:117], v[178:179], off offset:-1008
	global_load_dwordx4 v[118:121], v[178:179], off offset:-1024
	global_load_dwordx4 v[122:125], v[178:179], off offset:16
	global_load_dwordx4 v[126:129], v[178:179], off
	v_lshl_add_u64 v[178:179], v[178:179], 0, s[12:13]
	global_load_dwordx4 v[130:133], v[178:179], off offset:-1008
	global_load_dwordx4 v[134:137], v[178:179], off offset:-1024
	global_load_dwordx4 v[138:141], v[178:179], off offset:16
	global_load_dwordx4 v[142:145], v[178:179], off
	v_lshl_add_u64 v[178:179], v[178:179], 0, s[12:13]
	global_load_dwordx4 v[146:149], v[178:179], off offset:-1008
	global_load_dwordx4 v[150:153], v[178:179], off offset:-1024
	global_load_dwordx4 v[154:157], v[178:179], off offset:16
	global_load_dwordx4 v[158:161], v[178:179], off
	v_lshl_add_u64 v[178:179], v[178:179], 0, s[12:13]
	global_load_dwordx4 v[162:165], v[178:179], off offset:-1008
	global_load_dwordx4 v[166:169], v[178:179], off offset:-1024
	global_load_dwordx4 v[170:173], v[178:179], off offset:16
	global_load_dwordx4 v[174:177], v[178:179], off
	v_lshl_add_u64 v[178:179], v[178:179], 0, s[12:13]
.LBB0_1329:
	v_add_u32_e32 v90, s0, v95
	ds_read_b128 v[2:5], v90
	ds_read_b128 v[50:53], v90 offset:16
	s_waitcnt vmcnt(14)
	v_mov_b32_e32 v106, v114
	v_mov_b32_e32 v107, v115
	v_mov_b32_e32 v108, v116
	v_mov_b32_e32 v109, v117
	v_mov_b32_e32 v110, v118
	v_mov_b32_e32 v111, v119
	v_mov_b32_e32 v112, v120
	v_mov_b32_e32 v113, v121
	global_load_dwordx4 v[114:117], v[178:179], off offset:-1008
	global_load_dwordx4 v[118:121], v[178:179], off offset:-1024
	s_addk_i32 s0, 0x220
	s_mov_b64 s[12:13], 0x800
	s_cmpk_eq_u32 s0, 0x8800
	s_nop 0
	v_mov_b32_e32 v7, v112
	v_mov_b32_e32 v112, v111
	v_mov_b32_e32 v6, v110
	s_waitcnt lgkmcnt(1)
	v_pk_fma_f32 v[54:55], v[2:3], v[112:113], v[88:89] op_sel_hi:[0,1,1]
	v_mov_b32_e32 v88, v106
	v_mov_b32_e32 v89, v108
	v_mov_b32_e32 v108, v107
	v_pk_fma_f32 v[48:49], v[2:3], v[6:7], v[48:49] op_sel_hi:[0,1,1]
	v_pk_fma_f32 v[10:11], v[2:3], v[88:89], v[10:11] op_sel_hi:[0,1,1]
	v_pk_fma_f32 v[8:9], v[2:3], v[108:109], v[8:9] op_sel_hi:[0,1,1]
	v_pk_fma_f32 v[86:87], v[2:3], v[6:7], v[86:87] op_sel:[1,0,0]
	v_pk_fma_f32 v[84:85], v[2:3], v[112:113], v[84:85] op_sel:[1,0,0]
	v_pk_fma_f32 v[82:83], v[2:3], v[88:89], v[82:83] op_sel:[1,0,0]
	v_pk_fma_f32 v[80:81], v[2:3], v[108:109], v[80:81] op_sel:[1,0,0]
	v_mov_b32_e32 v2, v5
	v_pk_fma_f32 v[70:71], v[2:3], v[6:7], v[70:71] op_sel_hi:[0,1,1]
	v_pk_fma_f32 v[68:69], v[2:3], v[112:113], v[68:69] op_sel_hi:[0,1,1]
	v_pk_fma_f32 v[66:67], v[2:3], v[88:89], v[66:67] op_sel_hi:[0,1,1]
	v_pk_fma_f32 v[64:65], v[2:3], v[108:109], v[64:65] op_sel_hi:[0,1,1]
	s_waitcnt lgkmcnt(0)
	v_mov_b32_e32 v2, v53
	v_pk_fma_f32 v[78:79], v[4:5], v[6:7], v[78:79] op_sel_hi:[0,1,1]
	v_pk_fma_f32 v[76:77], v[4:5], v[112:113], v[76:77] op_sel_hi:[0,1,1]
	v_pk_fma_f32 v[74:75], v[4:5], v[88:89], v[74:75] op_sel_hi:[0,1,1]
	v_pk_fma_f32 v[72:73], v[4:5], v[108:109], v[72:73] op_sel_hi:[0,1,1]
	v_pk_fma_f32 v[62:63], v[50:51], v[6:7], v[62:63] op_sel_hi:[0,1,1]
	v_pk_fma_f32 v[60:61], v[50:51], v[112:113], v[60:61] op_sel_hi:[0,1,1]
	v_pk_fma_f32 v[58:59], v[50:51], v[88:89], v[58:59] op_sel_hi:[0,1,1]
	v_pk_fma_f32 v[56:57], v[50:51], v[108:109], v[56:57] op_sel_hi:[0,1,1]
	v_pk_fma_f32 v[46:47], v[50:51], v[6:7], v[46:47] op_sel:[1,0,0]
	v_pk_fma_f32 v[44:45], v[50:51], v[112:113], v[44:45] op_sel:[1,0,0]
	v_pk_fma_f32 v[42:43], v[50:51], v[88:89], v[42:43] op_sel:[1,0,0]
	v_pk_fma_f32 v[40:41], v[50:51], v[108:109], v[40:41] op_sel:[1,0,0]
	v_pk_fma_f32 v[38:39], v[52:53], v[6:7], v[38:39] op_sel_hi:[0,1,1]
	v_pk_fma_f32 v[36:37], v[52:53], v[112:113], v[36:37] op_sel_hi:[0,1,1]
	v_pk_fma_f32 v[34:35], v[52:53], v[88:89], v[34:35] op_sel_hi:[0,1,1]
	v_pk_fma_f32 v[32:33], v[52:53], v[108:109], v[32:33] op_sel_hi:[0,1,1]
	v_pk_fma_f32 v[6:7], v[2:3], v[6:7], v[30:31] op_sel_hi:[0,1,1]
	v_pk_fma_f32 v[28:29], v[2:3], v[112:113], v[28:29] op_sel_hi:[0,1,1]
	v_pk_fma_f32 v[106:107], v[2:3], v[88:89], v[26:27] op_sel_hi:[0,1,1]
	v_pk_fma_f32 v[108:109], v[2:3], v[108:109], v[24:25] op_sel_hi:[0,1,1]
	ds_read_b128 v[2:5], v90 offset:272
	ds_read_b128 v[24:27], v90 offset:288
	s_waitcnt vmcnt(14)
	v_mov_b32_e32 v50, v122
	v_mov_b32_e32 v51, v123
	v_mov_b32_e32 v52, v124
	v_mov_b32_e32 v53, v125
	v_mov_b32_e32 v88, v126
	v_mov_b32_e32 v89, v127
	v_mov_b32_e32 v90, v128
	v_mov_b32_e32 v91, v129
	global_load_dwordx4 v[122:125], v[178:179], off offset:16
	global_load_dwordx4 v[126:129], v[178:179], off
	v_lshl_add_u64 v[178:179], v[178:179], 0, s[12:13]
	v_lshl_add_u64 v[0:1], v[0:1], 0, s[12:13]
	s_nop 0
	v_mov_b32_e32 v31, v90
	v_mov_b32_e32 v90, v89
	v_mov_b32_e32 v30, v88
	s_waitcnt lgkmcnt(1)
	v_pk_fma_f32 v[88:89], v[2:3], v[90:91], v[54:55] op_sel_hi:[0,1,1]
	v_mov_b32_e32 v54, v50
	v_mov_b32_e32 v55, v52
	v_mov_b32_e32 v52, v51
	v_pk_fma_f32 v[48:49], v[2:3], v[30:31], v[48:49] op_sel_hi:[0,1,1]
	v_pk_fma_f32 v[10:11], v[2:3], v[54:55], v[10:11] op_sel_hi:[0,1,1]
	v_pk_fma_f32 v[8:9], v[2:3], v[52:53], v[8:9] op_sel_hi:[0,1,1]
	v_pk_fma_f32 v[86:87], v[2:3], v[30:31], v[86:87] op_sel:[1,0,0]
	v_pk_fma_f32 v[84:85], v[2:3], v[90:91], v[84:85] op_sel:[1,0,0]
	v_pk_fma_f32 v[82:83], v[2:3], v[54:55], v[82:83] op_sel:[1,0,0]
	v_pk_fma_f32 v[80:81], v[2:3], v[52:53], v[80:81] op_sel:[1,0,0]
	v_mov_b32_e32 v2, v5
	v_pk_fma_f32 v[70:71], v[2:3], v[30:31], v[70:71] op_sel_hi:[0,1,1]
	v_pk_fma_f32 v[68:69], v[2:3], v[90:91], v[68:69] op_sel_hi:[0,1,1]
	v_pk_fma_f32 v[66:67], v[2:3], v[54:55], v[66:67] op_sel_hi:[0,1,1]
	v_pk_fma_f32 v[64:65], v[2:3], v[52:53], v[64:65] op_sel_hi:[0,1,1]
	s_waitcnt lgkmcnt(0)
; DI void gla3_phase(const P& p, int l, const bf16_t* PROJ, const float* US, bf16_t* OGLA, char* smem, int bid, int nb) {
;     ...
;       for (int kk = 0; kk < 128; ++kk) {
;         const f32x4 a0 = *(const f32x4*)(QT + kk * LS + ty * 8), a1 = *(const f32x4*)(QT + kk * LS + ty * 8 + 4);
;         const f32x4 b0 = *(const f32x4*)(Sp + (size_t)kk * 256), b1 = *(const f32x4*)(Sp + (size_t)kk * 256 + 4);
;         const float a[8] = {a0[0], a0[1], a0[2], a0[3], a1[0], a1[1], a1[2], a1[3]}, b[8] = {b0[0], b0[1], b0[2], b0[3], b1[0], b1[1], b1[2], b1[3]};
; #pragma unroll
;         for (int i = 0; i < 8; ++i)
; #pragma unroll
;           for (int j = 0; j < 8; ++j) o[i][j] += a[i] * b[j];
;       }
	v_mov_b32_e32 v2, v27
	v_pk_fma_f32 v[78:79], v[4:5], v[30:31], v[78:79] op_sel_hi:[0,1,1]
	v_pk_fma_f32 v[76:77], v[4:5], v[90:91], v[76:77] op_sel_hi:[0,1,1]
	v_pk_fma_f32 v[74:75], v[4:5], v[54:55], v[74:75] op_sel_hi:[0,1,1]
	v_pk_fma_f32 v[72:73], v[4:5], v[52:53], v[72:73] op_sel_hi:[0,1,1]
	v_pk_fma_f32 v[62:63], v[24:25], v[30:31], v[62:63] op_sel_hi:[0,1,1]
	v_pk_fma_f32 v[60:61], v[24:25], v[90:91], v[60:61] op_sel_hi:[0,1,1]
	v_pk_fma_f32 v[58:59], v[24:25], v[54:55], v[58:59] op_sel_hi:[0,1,1]
	v_pk_fma_f32 v[56:57], v[24:25], v[52:53], v[56:57] op_sel_hi:[0,1,1]
	v_pk_fma_f32 v[46:47], v[24:25], v[30:31], v[46:47] op_sel:[1,0,0]
	v_pk_fma_f32 v[44:45], v[24:25], v[90:91], v[44:45] op_sel:[1,0,0]
	v_pk_fma_f32 v[42:43], v[24:25], v[54:55], v[42:43] op_sel:[1,0,0]
	v_pk_fma_f32 v[40:41], v[24:25], v[52:53], v[40:41] op_sel:[1,0,0]
	v_pk_fma_f32 v[38:39], v[26:27], v[30:31], v[38:39] op_sel_hi:[0,1,1]
	v_pk_fma_f32 v[36:37], v[26:27], v[90:91], v[36:37] op_sel_hi:[0,1,1]
	v_pk_fma_f32 v[34:35], v[26:27], v[54:55], v[34:35] op_sel_hi:[0,1,1]
	v_pk_fma_f32 v[32:33], v[26:27], v[52:53], v[32:33] op_sel_hi:[0,1,1]
	v_pk_fma_f32 v[30:31], v[2:3], v[30:31], v[6:7] op_sel_hi:[0,1,1]
	v_pk_fma_f32 v[28:29], v[2:3], v[90:91], v[28:29] op_sel_hi:[0,1,1]
	v_pk_fma_f32 v[26:27], v[2:3], v[54:55], v[106:107] op_sel_hi:[0,1,1]
	v_pk_fma_f32 v[24:25], v[2:3], v[52:53], v[108:109] op_sel_hi:[0,1,1]
	v_add_u32_e32 v90, s0, v95
	ds_read_b128 v[2:5], v90
	ds_read_b128 v[50:53], v90 offset:16
	s_waitcnt vmcnt(14)
	v_mov_b32_e32 v106, v130
	v_mov_b32_e32 v107, v131
	v_mov_b32_e32 v108, v132
	v_mov_b32_e32 v109, v133
	v_mov_b32_e32 v110, v134
	v_mov_b32_e32 v111, v135
	v_mov_b32_e32 v112, v136
	v_mov_b32_e32 v113, v137
	global_load_dwordx4 v[130:133], v[178:179], off offset:-1008
	global_load_dwordx4 v[134:137], v[178:179], off offset:-1024
	s_addk_i32 s0, 0x220
	s_mov_b64 s[12:13], 0x800
	s_cmpk_eq_u32 s0, 0x8800
	s_nop 0
	v_mov_b32_e32 v7, v112
	v_mov_b32_e32 v112, v111
	v_mov_b32_e32 v6, v110
	s_waitcnt lgkmcnt(1)
	v_pk_fma_f32 v[54:55], v[2:3], v[112:113], v[88:89] op_sel_hi:[0,1,1]
	v_mov_b32_e32 v88, v106
	v_mov_b32_e32 v89, v108
	v_mov_b32_e32 v108, v107
	v_pk_fma_f32 v[48:49], v[2:3], v[6:7], v[48:49] op_sel_hi:[0,1,1]
	v_pk_fma_f32 v[10:11], v[2:3], v[88:89], v[10:11] op_sel_hi:[0,1,1]
	v_pk_fma_f32 v[8:9], v[2:3], v[108:109], v[8:9] op_sel_hi:[0,1,1]
	v_pk_fma_f32 v[86:87], v[2:3], v[6:7], v[86:87] op_sel:[1,0,0]
	v_pk_fma_f32 v[84:85], v[2:3], v[112:113], v[84:85] op_sel:[1,0,0]
	v_pk_fma_f32 v[82:83], v[2:3], v[88:89], v[82:83] op_sel:[1,0,0]
	v_pk_fma_f32 v[80:81], v[2:3], v[108:109], v[80:81] op_sel:[1,0,0]
	v_mov_b32_e32 v2, v5
	v_pk_fma_f32 v[70:71], v[2:3], v[6:7], v[70:71] op_sel_hi:[0,1,1]
	v_pk_fma_f32 v[68:69], v[2:3], v[112:113], v[68:69] op_sel_hi:[0,1,1]
	v_pk_fma_f32 v[66:67], v[2:3], v[88:89], v[66:67] op_sel_hi:[0,1,1]
	v_pk_fma_f32 v[64:65], v[2:3], v[108:109], v[64:65] op_sel_hi:[0,1,1]
	s_waitcnt lgkmcnt(0)
	v_mov_b32_e32 v2, v53
	v_pk_fma_f32 v[78:79], v[4:5], v[6:7], v[78:79] op_sel_hi:[0,1,1]
	v_pk_fma_f32 v[76:77], v[4:5], v[112:113], v[76:77] op_sel_hi:[0,1,1]
	v_pk_fma_f32 v[74:75], v[4:5], v[88:89], v[74:75] op_sel_hi:[0,1,1]
	v_pk_fma_f32 v[72:73], v[4:5], v[108:109], v[72:73] op_sel_hi:[0,1,1]
	v_pk_fma_f32 v[62:63], v[50:51], v[6:7], v[62:63] op_sel_hi:[0,1,1]
	v_pk_fma_f32 v[60:61], v[50:51], v[112:113], v[60:61] op_sel_hi:[0,1,1]
	v_pk_fma_f32 v[58:59], v[50:51], v[88:89], v[58:59] op_sel_hi:[0,1,1]
	v_pk_fma_f32 v[56:57], v[50:51], v[108:109], v[56:57] op_sel_hi:[0,1,1]
	v_pk_fma_f32 v[46:47], v[50:51], v[6:7], v[46:47] op_sel:[1,0,0]
	v_pk_fma_f32 v[44:45], v[50:51], v[112:113], v[44:45] op_sel:[1,0,0]
	v_pk_fma_f32 v[42:43], v[50:51], v[88:89], v[42:43] op_sel:[1,0,0]
	v_pk_fma_f32 v[40:41], v[50:51], v[108:109], v[40:41] op_sel:[1,0,0]
	v_pk_fma_f32 v[38:39], v[52:53], v[6:7], v[38:39] op_sel_hi:[0,1,1]
	v_pk_fma_f32 v[36:37], v[52:53], v[112:113], v[36:37] op_sel_hi:[0,1,1]
	v_pk_fma_f32 v[34:35], v[52:53], v[88:89], v[34:35] op_sel_hi:[0,1,1]
	v_pk_fma_f32 v[32:33], v[52:53], v[108:109], v[32:33] op_sel_hi:[0,1,1]
	v_pk_fma_f32 v[6:7], v[2:3], v[6:7], v[30:31] op_sel_hi:[0,1,1]
	v_pk_fma_f32 v[28:29], v[2:3], v[112:113], v[28:29] op_sel_hi:[0,1,1]
	v_pk_fma_f32 v[106:107], v[2:3], v[88:89], v[26:27] op_sel_hi:[0,1,1]
	v_pk_fma_f32 v[108:109], v[2:3], v[108:109], v[24:25] op_sel_hi:[0,1,1]
	ds_read_b128 v[2:5], v90 offset:272
	ds_read_b128 v[24:27], v90 offset:288
	s_waitcnt vmcnt(14)
	v_mov_b32_e32 v50, v138
	v_mov_b32_e32 v51, v139
	v_mov_b32_e32 v52, v140
	v_mov_b32_e32 v53, v141
	v_mov_b32_e32 v88, v142
	v_mov_b32_e32 v89, v143
	v_mov_b32_e32 v90, v144
	v_mov_b32_e32 v91, v145
	global_load_dwordx4 v[138:141], v[178:179], off offset:16
	global_load_dwordx4 v[142:145], v[178:179], off
	v_lshl_add_u64 v[178:179], v[178:179], 0, s[12:13]
	v_lshl_add_u64 v[0:1], v[0:1], 0, s[12:13]
	s_nop 0
	v_mov_b32_e32 v31, v90
	v_mov_b32_e32 v90, v89
	v_mov_b32_e32 v30, v88
	s_waitcnt lgkmcnt(1)
	v_pk_fma_f32 v[88:89], v[2:3], v[90:91], v[54:55] op_sel_hi:[0,1,1]
	v_mov_b32_e32 v54, v50
	v_mov_b32_e32 v55, v52
	v_mov_b32_e32 v52, v51
	v_pk_fma_f32 v[48:49], v[2:3], v[30:31], v[48:49] op_sel_hi:[0,1,1]
	v_pk_fma_f32 v[10:11], v[2:3], v[54:55], v[10:11] op_sel_hi:[0,1,1]
	v_pk_fma_f32 v[8:9], v[2:3], v[52:53], v[8:9] op_sel_hi:[0,1,1]
	v_pk_fma_f32 v[86:87], v[2:3], v[30:31], v[86:87] op_sel:[1,0,0]
	v_pk_fma_f32 v[84:85], v[2:3], v[90:91], v[84:85] op_sel:[1,0,0]
	v_pk_fma_f32 v[82:83], v[2:3], v[54:55], v[82:83] op_sel:[1,0,0]
	v_pk_fma_f32 v[80:81], v[2:3], v[52:53], v[80:81] op_sel:[1,0,0]
	v_mov_b32_e32 v2, v5
	v_pk_fma_f32 v[70:71], v[2:3], v[30:31], v[70:71] op_sel_hi:[0,1,1]
	v_pk_fma_f32 v[68:69], v[2:3], v[90:91], v[68:69] op_sel_hi:[0,1,1]
	v_pk_fma_f32 v[66:67], v[2:3], v[54:55], v[66:67] op_sel_hi:[0,1,1]
	v_pk_fma_f32 v[64:65], v[2:3], v[52:53], v[64:65] op_sel_hi:[0,1,1]
	s_waitcnt lgkmcnt(0)
; DI void gla3_phase(const P& p, int l, const bf16_t* PROJ, const float* US, bf16_t* OGLA, char* smem, int bid, int nb) {
;     ...
;       const float* Sp = US + (size_t)(c * 4 + h) * 128 * 256 + tx * 8;
; #pragma unroll 2
;       for (int kk = 0; kk < 128; ++kk) {
;         const f32x4 a0 = *(const f32x4*)(QT + kk * LS + ty * 8), a1 = *(const f32x4*)(QT + kk * LS + ty * 8 + 4);
;         const f32x4 b0 = *(const f32x4*)(Sp + (size_t)kk * 256), b1 = *(const f32x4*)(Sp + (size_t)kk * 256 + 4);
;         const float a[8] = {a0[0], a0[1], a0[2], a0[3], a1[0], a1[1], a1[2], a1[3]}, b[8] = {b0[0], b0[1], b0[2], b0[3], b1[0], b1[1], b1[2], b1[3]};
; #pragma unroll
;         for (int i = 0; i < 8; ++i)
; #pragma unroll
;           for (int j = 0; j < 8; ++j) o[i][j] += a[i] * b[j];
;       }
	v_mov_b32_e32 v2, v27
	v_pk_fma_f32 v[78:79], v[4:5], v[30:31], v[78:79] op_sel_hi:[0,1,1]
	v_pk_fma_f32 v[76:77], v[4:5], v[90:91], v[76:77] op_sel_hi:[0,1,1]
	v_pk_fma_f32 v[74:75], v[4:5], v[54:55], v[74:75] op_sel_hi:[0,1,1]
	v_pk_fma_f32 v[72:73], v[4:5], v[52:53], v[72:73] op_sel_hi:[0,1,1]
	v_pk_fma_f32 v[62:63], v[24:25], v[30:31], v[62:63] op_sel_hi:[0,1,1]
	v_pk_fma_f32 v[60:61], v[24:25], v[90:91], v[60:61] op_sel_hi:[0,1,1]
	v_pk_fma_f32 v[58:59], v[24:25], v[54:55], v[58:59] op_sel_hi:[0,1,1]
	v_pk_fma_f32 v[56:57], v[24:25], v[52:53], v[56:57] op_sel_hi:[0,1,1]
	v_pk_fma_f32 v[46:47], v[24:25], v[30:31], v[46:47] op_sel:[1,0,0]
	v_pk_fma_f32 v[44:45], v[24:25], v[90:91], v[44:45] op_sel:[1,0,0]
	v_pk_fma_f32 v[42:43], v[24:25], v[54:55], v[42:43] op_sel:[1,0,0]
	v_pk_fma_f32 v[40:41], v[24:25], v[52:53], v[40:41] op_sel:[1,0,0]
	v_pk_fma_f32 v[38:39], v[26:27], v[30:31], v[38:39] op_sel_hi:[0,1,1]
	v_pk_fma_f32 v[36:37], v[26:27], v[90:91], v[36:37] op_sel_hi:[0,1,1]
	v_pk_fma_f32 v[34:35], v[26:27], v[54:55], v[34:35] op_sel_hi:[0,1,1]
	v_pk_fma_f32 v[32:33], v[26:27], v[52:53], v[32:33] op_sel_hi:[0,1,1]
	v_pk_fma_f32 v[30:31], v[2:3], v[30:31], v[6:7] op_sel_hi:[0,1,1]
	v_pk_fma_f32 v[28:29], v[2:3], v[90:91], v[28:29] op_sel_hi:[0,1,1]
	v_pk_fma_f32 v[26:27], v[2:3], v[54:55], v[106:107] op_sel_hi:[0,1,1]
	v_pk_fma_f32 v[24:25], v[2:3], v[52:53], v[108:109] op_sel_hi:[0,1,1]
	v_add_u32_e32 v90, s0, v95
	ds_read_b128 v[2:5], v90
	ds_read_b128 v[50:53], v90 offset:16
	s_waitcnt vmcnt(14)
	v_mov_b32_e32 v106, v146
	v_mov_b32_e32 v107, v147
	v_mov_b32_e32 v108, v148
	v_mov_b32_e32 v109, v149
	v_mov_b32_e32 v110, v150
	v_mov_b32_e32 v111, v151
	v_mov_b32_e32 v112, v152
	v_mov_b32_e32 v113, v153
	global_load_dwordx4 v[146:149], v[178:179], off offset:-1008
	global_load_dwordx4 v[150:153], v[178:179], off offset:-1024
	s_addk_i32 s0, 0x220
	s_mov_b64 s[12:13], 0x800
	s_cmpk_eq_u32 s0, 0x8800
	s_nop 0
	v_mov_b32_e32 v7, v112
	v_mov_b32_e32 v112, v111
	v_mov_b32_e32 v6, v110
	s_waitcnt lgkmcnt(1)
	v_pk_fma_f32 v[54:55], v[2:3], v[112:113], v[88:89] op_sel_hi:[0,1,1]
	v_mov_b32_e32 v88, v106
	v_mov_b32_e32 v89, v108
	v_mov_b32_e32 v108, v107
	v_pk_fma_f32 v[48:49], v[2:3], v[6:7], v[48:49] op_sel_hi:[0,1,1]
	v_pk_fma_f32 v[10:11], v[2:3], v[88:89], v[10:11] op_sel_hi:[0,1,1]
	v_pk_fma_f32 v[8:9], v[2:3], v[108:109], v[8:9] op_sel_hi:[0,1,1]
	v_pk_fma_f32 v[86:87], v[2:3], v[6:7], v[86:87] op_sel:[1,0,0]
	v_pk_fma_f32 v[84:85], v[2:3], v[112:113], v[84:85] op_sel:[1,0,0]
	v_pk_fma_f32 v[82:83], v[2:3], v[88:89], v[82:83] op_sel:[1,0,0]
	v_pk_fma_f32 v[80:81], v[2:3], v[108:109], v[80:81] op_sel:[1,0,0]
	v_mov_b32_e32 v2, v5
	v_pk_fma_f32 v[70:71], v[2:3], v[6:7], v[70:71] op_sel_hi:[0,1,1]
	v_pk_fma_f32 v[68:69], v[2:3], v[112:113], v[68:69] op_sel_hi:[0,1,1]
	v_pk_fma_f32 v[66:67], v[2:3], v[88:89], v[66:67] op_sel_hi:[0,1,1]
	v_pk_fma_f32 v[64:65], v[2:3], v[108:109], v[64:65] op_sel_hi:[0,1,1]
	s_waitcnt lgkmcnt(0)
	v_mov_b32_e32 v2, v53
	v_pk_fma_f32 v[78:79], v[4:5], v[6:7], v[78:79] op_sel_hi:[0,1,1]
	v_pk_fma_f32 v[76:77], v[4:5], v[112:113], v[76:77] op_sel_hi:[0,1,1]
	v_pk_fma_f32 v[74:75], v[4:5], v[88:89], v[74:75] op_sel_hi:[0,1,1]
	v_pk_fma_f32 v[72:73], v[4:5], v[108:109], v[72:73] op_sel_hi:[0,1,1]
	v_pk_fma_f32 v[62:63], v[50:51], v[6:7], v[62:63] op_sel_hi:[0,1,1]
	v_pk_fma_f32 v[60:61], v[50:51], v[112:113], v[60:61] op_sel_hi:[0,1,1]
	v_pk_fma_f32 v[58:59], v[50:51], v[88:89], v[58:59] op_sel_hi:[0,1,1]
	v_pk_fma_f32 v[56:57], v[50:51], v[108:109], v[56:57] op_sel_hi:[0,1,1]
	v_pk_fma_f32 v[46:47], v[50:51], v[6:7], v[46:47] op_sel:[1,0,0]
	v_pk_fma_f32 v[44:45], v[50:51], v[112:113], v[44:45] op_sel:[1,0,0]
	v_pk_fma_f32 v[42:43], v[50:51], v[88:89], v[42:43] op_sel:[1,0,0]
	v_pk_fma_f32 v[40:41], v[50:51], v[108:109], v[40:41] op_sel:[1,0,0]
	v_pk_fma_f32 v[38:39], v[52:53], v[6:7], v[38:39] op_sel_hi:[0,1,1]
	v_pk_fma_f32 v[36:37], v[52:53], v[112:113], v[36:37] op_sel_hi:[0,1,1]
	v_pk_fma_f32 v[34:35], v[52:53], v[88:89], v[34:35] op_sel_hi:[0,1,1]
	v_pk_fma_f32 v[32:33], v[52:53], v[108:109], v[32:33] op_sel_hi:[0,1,1]
	v_pk_fma_f32 v[6:7], v[2:3], v[6:7], v[30:31] op_sel_hi:[0,1,1]
	v_pk_fma_f32 v[28:29], v[2:3], v[112:113], v[28:29] op_sel_hi:[0,1,1]
	v_pk_fma_f32 v[106:107], v[2:3], v[88:89], v[26:27] op_sel_hi:[0,1,1]
	v_pk_fma_f32 v[108:109], v[2:3], v[108:109], v[24:25] op_sel_hi:[0,1,1]
	ds_read_b128 v[2:5], v90 offset:272
	ds_read_b128 v[24:27], v90 offset:288
	s_waitcnt vmcnt(14)
	v_mov_b32_e32 v50, v154
	v_mov_b32_e32 v51, v155
	v_mov_b32_e32 v52, v156
	v_mov_b32_e32 v53, v157
	v_mov_b32_e32 v88, v158
	v_mov_b32_e32 v89, v159
	v_mov_b32_e32 v90, v160
	v_mov_b32_e32 v91, v161
	global_load_dwordx4 v[154:157], v[178:179], off offset:16
	global_load_dwordx4 v[158:161], v[178:179], off
	v_lshl_add_u64 v[178:179], v[178:179], 0, s[12:13]
	v_lshl_add_u64 v[0:1], v[0:1], 0, s[12:13]
	s_nop 0
	v_mov_b32_e32 v31, v90
	v_mov_b32_e32 v90, v89
	v_mov_b32_e32 v30, v88
	s_waitcnt lgkmcnt(1)
	v_pk_fma_f32 v[88:89], v[2:3], v[90:91], v[54:55] op_sel_hi:[0,1,1]
	v_mov_b32_e32 v54, v50
	v_mov_b32_e32 v55, v52
	v_mov_b32_e32 v52, v51
	v_pk_fma_f32 v[48:49], v[2:3], v[30:31], v[48:49] op_sel_hi:[0,1,1]
	v_pk_fma_f32 v[10:11], v[2:3], v[54:55], v[10:11] op_sel_hi:[0,1,1]
	v_pk_fma_f32 v[8:9], v[2:3], v[52:53], v[8:9] op_sel_hi:[0,1,1]
	v_pk_fma_f32 v[86:87], v[2:3], v[30:31], v[86:87] op_sel:[1,0,0]
	v_pk_fma_f32 v[84:85], v[2:3], v[90:91], v[84:85] op_sel:[1,0,0]
	v_pk_fma_f32 v[82:83], v[2:3], v[54:55], v[82:83] op_sel:[1,0,0]
	v_pk_fma_f32 v[80:81], v[2:3], v[52:53], v[80:81] op_sel:[1,0,0]
	v_mov_b32_e32 v2, v5
	v_pk_fma_f32 v[70:71], v[2:3], v[30:31], v[70:71] op_sel_hi:[0,1,1]
	v_pk_fma_f32 v[68:69], v[2:3], v[90:91], v[68:69] op_sel_hi:[0,1,1]
	v_pk_fma_f32 v[66:67], v[2:3], v[54:55], v[66:67] op_sel_hi:[0,1,1]
	v_pk_fma_f32 v[64:65], v[2:3], v[52:53], v[64:65] op_sel_hi:[0,1,1]
	s_waitcnt lgkmcnt(0)
; DI void gla3_phase(const P& p, int l, const bf16_t* PROJ, const float* US, bf16_t* OGLA, char* smem, int bid, int nb) {
;     ...
;       const float* Sp = US + (size_t)(c * 4 + h) * 128 * 256 + tx * 8;
; #pragma unroll 2
;       for (int kk = 0; kk < 128; ++kk) {
;         const f32x4 a0 = *(const f32x4*)(QT + kk * LS + ty * 8), a1 = *(const f32x4*)(QT + kk * LS + ty * 8 + 4);
;         const f32x4 b0 = *(const f32x4*)(Sp + (size_t)kk * 256), b1 = *(const f32x4*)(Sp + (size_t)kk * 256 + 4);
;         const float a[8] = {a0[0], a0[1], a0[2], a0[3], a1[0], a1[1], a1[2], a1[3]}, b[8] = {b0[0], b0[1], b0[2], b0[3], b1[0], b1[1], b1[2], b1[3]};
; #pragma unroll
;         for (int i = 0; i < 8; ++i)
; #pragma unroll
;           for (int j = 0; j < 8; ++j) o[i][j] += a[i] * b[j];
;       }
	v_mov_b32_e32 v2, v27
	v_pk_fma_f32 v[78:79], v[4:5], v[30:31], v[78:79] op_sel_hi:[0,1,1]
	v_pk_fma_f32 v[76:77], v[4:5], v[90:91], v[76:77] op_sel_hi:[0,1,1]
	v_pk_fma_f32 v[74:75], v[4:5], v[54:55], v[74:75] op_sel_hi:[0,1,1]
	v_pk_fma_f32 v[72:73], v[4:5], v[52:53], v[72:73] op_sel_hi:[0,1,1]
	v_pk_fma_f32 v[62:63], v[24:25], v[30:31], v[62:63] op_sel_hi:[0,1,1]
	v_pk_fma_f32 v[60:61], v[24:25], v[90:91], v[60:61] op_sel_hi:[0,1,1]
	v_pk_fma_f32 v[58:59], v[24:25], v[54:55], v[58:59] op_sel_hi:[0,1,1]
	v_pk_fma_f32 v[56:57], v[24:25], v[52:53], v[56:57] op_sel_hi:[0,1,1]
	v_pk_fma_f32 v[46:47], v[24:25], v[30:31], v[46:47] op_sel:[1,0,0]
	v_pk_fma_f32 v[44:45], v[24:25], v[90:91], v[44:45] op_sel:[1,0,0]
	v_pk_fma_f32 v[42:43], v[24:25], v[54:55], v[42:43] op_sel:[1,0,0]
	v_pk_fma_f32 v[40:41], v[24:25], v[52:53], v[40:41] op_sel:[1,0,0]
	v_pk_fma_f32 v[38:39], v[26:27], v[30:31], v[38:39] op_sel_hi:[0,1,1]
	v_pk_fma_f32 v[36:37], v[26:27], v[90:91], v[36:37] op_sel_hi:[0,1,1]
	v_pk_fma_f32 v[34:35], v[26:27], v[54:55], v[34:35] op_sel_hi:[0,1,1]
	v_pk_fma_f32 v[32:33], v[26:27], v[52:53], v[32:33] op_sel_hi:[0,1,1]
	v_pk_fma_f32 v[30:31], v[2:3], v[30:31], v[6:7] op_sel_hi:[0,1,1]
	v_pk_fma_f32 v[28:29], v[2:3], v[90:91], v[28:29] op_sel_hi:[0,1,1]
	v_pk_fma_f32 v[26:27], v[2:3], v[54:55], v[106:107] op_sel_hi:[0,1,1]
	v_pk_fma_f32 v[24:25], v[2:3], v[52:53], v[108:109] op_sel_hi:[0,1,1]
	v_add_u32_e32 v90, s0, v95
	ds_read_b128 v[2:5], v90
	ds_read_b128 v[50:53], v90 offset:16
	s_waitcnt vmcnt(14)
	v_mov_b32_e32 v106, v162
	v_mov_b32_e32 v107, v163
	v_mov_b32_e32 v108, v164
	v_mov_b32_e32 v109, v165
	v_mov_b32_e32 v110, v166
	v_mov_b32_e32 v111, v167
	v_mov_b32_e32 v112, v168
	v_mov_b32_e32 v113, v169
	global_load_dwordx4 v[162:165], v[178:179], off offset:-1008
	global_load_dwordx4 v[166:169], v[178:179], off offset:-1024
	s_addk_i32 s0, 0x220
	s_mov_b64 s[12:13], 0x800
	s_cmpk_eq_u32 s0, 0x8800
	s_nop 0
	v_mov_b32_e32 v7, v112
	v_mov_b32_e32 v112, v111
	v_mov_b32_e32 v6, v110
	s_waitcnt lgkmcnt(1)
	v_pk_fma_f32 v[54:55], v[2:3], v[112:113], v[88:89] op_sel_hi:[0,1,1]
	v_mov_b32_e32 v88, v106
	v_mov_b32_e32 v89, v108
	v_mov_b32_e32 v108, v107
	v_pk_fma_f32 v[48:49], v[2:3], v[6:7], v[48:49] op_sel_hi:[0,1,1]
	v_pk_fma_f32 v[10:11], v[2:3], v[88:89], v[10:11] op_sel_hi:[0,1,1]
	v_pk_fma_f32 v[8:9], v[2:3], v[108:109], v[8:9] op_sel_hi:[0,1,1]
	v_pk_fma_f32 v[86:87], v[2:3], v[6:7], v[86:87] op_sel:[1,0,0]
	v_pk_fma_f32 v[84:85], v[2:3], v[112:113], v[84:85] op_sel:[1,0,0]
	v_pk_fma_f32 v[82:83], v[2:3], v[88:89], v[82:83] op_sel:[1,0,0]
	v_pk_fma_f32 v[80:81], v[2:3], v[108:109], v[80:81] op_sel:[1,0,0]
	v_mov_b32_e32 v2, v5
	v_pk_fma_f32 v[70:71], v[2:3], v[6:7], v[70:71] op_sel_hi:[0,1,1]
	v_pk_fma_f32 v[68:69], v[2:3], v[112:113], v[68:69] op_sel_hi:[0,1,1]
	v_pk_fma_f32 v[66:67], v[2:3], v[88:89], v[66:67] op_sel_hi:[0,1,1]
	v_pk_fma_f32 v[64:65], v[2:3], v[108:109], v[64:65] op_sel_hi:[0,1,1]
	s_waitcnt lgkmcnt(0)
	v_mov_b32_e32 v2, v53
	v_pk_fma_f32 v[78:79], v[4:5], v[6:7], v[78:79] op_sel_hi:[0,1,1]
	v_pk_fma_f32 v[76:77], v[4:5], v[112:113], v[76:77] op_sel_hi:[0,1,1]
	v_pk_fma_f32 v[74:75], v[4:5], v[88:89], v[74:75] op_sel_hi:[0,1,1]
	v_pk_fma_f32 v[72:73], v[4:5], v[108:109], v[72:73] op_sel_hi:[0,1,1]
	v_pk_fma_f32 v[62:63], v[50:51], v[6:7], v[62:63] op_sel_hi:[0,1,1]
	v_pk_fma_f32 v[60:61], v[50:51], v[112:113], v[60:61] op_sel_hi:[0,1,1]
	v_pk_fma_f32 v[58:59], v[50:51], v[88:89], v[58:59] op_sel_hi:[0,1,1]
	v_pk_fma_f32 v[56:57], v[50:51], v[108:109], v[56:57] op_sel_hi:[0,1,1]
	v_pk_fma_f32 v[46:47], v[50:51], v[6:7], v[46:47] op_sel:[1,0,0]
	v_pk_fma_f32 v[44:45], v[50:51], v[112:113], v[44:45] op_sel:[1,0,0]
	v_pk_fma_f32 v[42:43], v[50:51], v[88:89], v[42:43] op_sel:[1,0,0]
	v_pk_fma_f32 v[40:41], v[50:51], v[108:109], v[40:41] op_sel:[1,0,0]
	v_pk_fma_f32 v[38:39], v[52:53], v[6:7], v[38:39] op_sel_hi:[0,1,1]
	v_pk_fma_f32 v[36:37], v[52:53], v[112:113], v[36:37] op_sel_hi:[0,1,1]
	v_pk_fma_f32 v[34:35], v[52:53], v[88:89], v[34:35] op_sel_hi:[0,1,1]
	v_pk_fma_f32 v[32:33], v[52:53], v[108:109], v[32:33] op_sel_hi:[0,1,1]
	v_pk_fma_f32 v[6:7], v[2:3], v[6:7], v[30:31] op_sel_hi:[0,1,1]
	v_pk_fma_f32 v[28:29], v[2:3], v[112:113], v[28:29] op_sel_hi:[0,1,1]
	v_pk_fma_f32 v[106:107], v[2:3], v[88:89], v[26:27] op_sel_hi:[0,1,1]
	v_pk_fma_f32 v[108:109], v[2:3], v[108:109], v[24:25] op_sel_hi:[0,1,1]
	ds_read_b128 v[2:5], v90 offset:272
	ds_read_b128 v[24:27], v90 offset:288
	s_waitcnt vmcnt(14)
	v_mov_b32_e32 v50, v170
	v_mov_b32_e32 v51, v171
	v_mov_b32_e32 v52, v172
	v_mov_b32_e32 v53, v173
	v_mov_b32_e32 v88, v174
	v_mov_b32_e32 v89, v175
	v_mov_b32_e32 v90, v176
	v_mov_b32_e32 v91, v177
	global_load_dwordx4 v[170:173], v[178:179], off offset:16
	global_load_dwordx4 v[174:177], v[178:179], off
	v_lshl_add_u64 v[178:179], v[178:179], 0, s[12:13]
	v_lshl_add_u64 v[0:1], v[0:1], 0, s[12:13]
	s_nop 0
	v_mov_b32_e32 v31, v90
	v_mov_b32_e32 v90, v89
	v_mov_b32_e32 v30, v88
	s_waitcnt lgkmcnt(1)
	v_pk_fma_f32 v[88:89], v[2:3], v[90:91], v[54:55] op_sel_hi:[0,1,1]
	v_mov_b32_e32 v54, v50
	v_mov_b32_e32 v55, v52
	v_mov_b32_e32 v52, v51
	v_pk_fma_f32 v[48:49], v[2:3], v[30:31], v[48:49] op_sel_hi:[0,1,1]
	v_pk_fma_f32 v[10:11], v[2:3], v[54:55], v[10:11] op_sel_hi:[0,1,1]
	v_pk_fma_f32 v[8:9], v[2:3], v[52:53], v[8:9] op_sel_hi:[0,1,1]
	v_pk_fma_f32 v[86:87], v[2:3], v[30:31], v[86:87] op_sel:[1,0,0]
	v_pk_fma_f32 v[84:85], v[2:3], v[90:91], v[84:85] op_sel:[1,0,0]
	v_pk_fma_f32 v[82:83], v[2:3], v[54:55], v[82:83] op_sel:[1,0,0]
	v_pk_fma_f32 v[80:81], v[2:3], v[52:53], v[80:81] op_sel:[1,0,0]
	v_mov_b32_e32 v2, v5
	v_pk_fma_f32 v[70:71], v[2:3], v[30:31], v[70:71] op_sel_hi:[0,1,1]
	v_pk_fma_f32 v[68:69], v[2:3], v[90:91], v[68:69] op_sel_hi:[0,1,1]
	v_pk_fma_f32 v[66:67], v[2:3], v[54:55], v[66:67] op_sel_hi:[0,1,1]
	v_pk_fma_f32 v[64:65], v[2:3], v[52:53], v[64:65] op_sel_hi:[0,1,1]
	s_waitcnt lgkmcnt(0)
; #define DPPF(v, ctrl) __builtin_bit_cast(float, __builtin_amdgcn_update_dpp(0, __builtin_bit_cast(int, (v)), (ctrl), 0xf, 0xf, true))
; DI float sum8(float v) { v += DPPF(v, 0xB1); v += DPPF(v, 0x4E); v += DPPF(v, 0x141); return v; }
; DI unsigned pack2(float a, float b) { return (unsigned)f2bf(a) | ((unsigned)f2bf(b) << 16); }
; DI float bflo(unsigned w) { return __uint_as_float(w << 16); }
; DI float bfhi(unsigned w) { return __uint_as_float(w & 0xffff0000u); }
; DI void gla3_phase(const P& p, int l, const bf16_t* PROJ, const float* US, bf16_t* OGLA, char* smem, int bid, int nb) {
;     ...
;       for (int kk = 0; kk < 128; ++kk) {
;         const f32x4 a0 = *(const f32x4*)(QT + kk * LS + ty * 8), a1 = *(const f32x4*)(QT + kk * LS + ty * 8 + 4);
;         const f32x4 b0 = *(const f32x4*)(Sp + (size_t)kk * 256), b1 = *(const f32x4*)(Sp + (size_t)kk * 256 + 4);
;         const float a[8] = {a0[0], a0[1], a0[2], a0[3], a1[0], a1[1], a1[2], a1[3]}, b[8] = {b0[0], b0[1], b0[2], b0[3], b1[0], b1[1], b1[2], b1[3]};
; #pragma unroll
;         for (int i = 0; i < 8; ++i)
; #pragma unroll
;           for (int j = 0; j < 8; ++j) o[i][j] += a[i] * b[j];
;       }
;       float gn[8];
; #pragma unroll
;       for (int j = 0; j < 8; ++j) gn[j] = GN[h * 256 + tx * 8 + j];
; #pragma unroll
;       for (int i = 0; i < 8; ++i) {
;         float ss = 0.f;
; #pragma unroll
;         for (int j = 0; j < 8; ++j) ss += o[i][j] * o[i][j];
;         ss = sum8(ss); ss += DPPF(ss, 0x140);
;         { const unsigned w = __builtin_bit_cast(unsigned, ss); auto pr = __builtin_amdgcn_permlane16_swap(w, w, false, false);
;           ss = __builtin_bit_cast(float, (unsigned)pr[0]) + __builtin_bit_cast(float, (unsigned)pr[1]); }
;         const float rstd = __builtin_amdgcn_rsqf(ss * (1.0f / 256.f) + 1e-5f);
;         const int t = c * 64 + ty * 8 + i;
;         const uint4 rw = *(const uint4*)(PROJ + (size_t)t * NP + C_GR + h * 256 + tx * 8);
;         const float rr[8] = {bflo(rw.x), bfhi(rw.x), bflo(rw.y), bfhi(rw.y), bflo(rw.z), bfhi(rw.z), bflo(rw.w), bfhi(rw.w)};
;         float y[8];
; #pragma unroll
;         for (int j = 0; j < 8; ++j) y[j] = o[i][j] * rstd * gn[j] * rr[j] * sigmoidf_(rr[j]);
;         uint4 w; w.x = pack2(y[0], y[1]); w.y = pack2(y[2], y[3]); w.z = pack2(y[4], y[5]); w.w = pack2(y[6], y[7]);
;         *(uint4*)(OGLA + (size_t)t * 1024 + h * 256 + tx * 8) = w;
	v_mov_b32_e32 v2, v27
	v_pk_fma_f32 v[78:79], v[4:5], v[30:31], v[78:79] op_sel_hi:[0,1,1]
	v_pk_fma_f32 v[76:77], v[4:5], v[90:91], v[76:77] op_sel_hi:[0,1,1]
	v_pk_fma_f32 v[74:75], v[4:5], v[54:55], v[74:75] op_sel_hi:[0,1,1]
	v_pk_fma_f32 v[72:73], v[4:5], v[52:53], v[72:73] op_sel_hi:[0,1,1]
	v_pk_fma_f32 v[62:63], v[24:25], v[30:31], v[62:63] op_sel_hi:[0,1,1]
	v_pk_fma_f32 v[60:61], v[24:25], v[90:91], v[60:61] op_sel_hi:[0,1,1]
	v_pk_fma_f32 v[58:59], v[24:25], v[54:55], v[58:59] op_sel_hi:[0,1,1]
	v_pk_fma_f32 v[56:57], v[24:25], v[52:53], v[56:57] op_sel_hi:[0,1,1]
	v_pk_fma_f32 v[46:47], v[24:25], v[30:31], v[46:47] op_sel:[1,0,0]
	v_pk_fma_f32 v[44:45], v[24:25], v[90:91], v[44:45] op_sel:[1,0,0]
	v_pk_fma_f32 v[42:43], v[24:25], v[54:55], v[42:43] op_sel:[1,0,0]
	v_pk_fma_f32 v[40:41], v[24:25], v[52:53], v[40:41] op_sel:[1,0,0]
	v_pk_fma_f32 v[38:39], v[26:27], v[30:31], v[38:39] op_sel_hi:[0,1,1]
	v_pk_fma_f32 v[36:37], v[26:27], v[90:91], v[36:37] op_sel_hi:[0,1,1]
	v_pk_fma_f32 v[34:35], v[26:27], v[54:55], v[34:35] op_sel_hi:[0,1,1]
	v_pk_fma_f32 v[32:33], v[26:27], v[52:53], v[32:33] op_sel_hi:[0,1,1]
	v_pk_fma_f32 v[30:31], v[2:3], v[30:31], v[6:7] op_sel_hi:[0,1,1]
	v_pk_fma_f32 v[28:29], v[2:3], v[90:91], v[28:29] op_sel_hi:[0,1,1]
	v_pk_fma_f32 v[26:27], v[2:3], v[54:55], v[106:107] op_sel_hi:[0,1,1]
	v_pk_fma_f32 v[24:25], v[2:3], v[52:53], v[108:109] op_sel_hi:[0,1,1]
	s_cbranch_scc0 .LBB0_1329
	s_waitcnt vmcnt(0)
	v_lshlrev_b32_e32 v0, 2, v14
	v_lshl_or_b32 v91, s10, 10, v0
	v_pk_mul_f32 v[0:1], v[48:49], v[48:49]
	v_pk_mul_f32 v[2:3], v[88:89], v[88:89]
	v_pk_mul_f32 v[4:5], v[10:11], v[10:11]
	v_add_f32_e32 v0, v0, v2
	v_add_f32_e32 v0, v1, v0
	v_add_f32_e32 v0, v3, v0
	v_pk_mul_f32 v[6:7], v[8:9], v[8:9]
	v_add_f32_e32 v0, v4, v0
	v_add_f32_e32 v0, v6, v0
	v_add_f32_e32 v0, v5, v0
	v_add_f32_e32 v0, v7, v0
	v_readlane_b32 s20, v248, 1
	v_readlane_b32 s21, v248, 2
	v_add_f32_dpp v0, v0, v0 quad_perm:[1,0,3,2] row_mask:0xf bank_mask:0xf bound_ctrl:1
	v_add_u32_e32 v52, s11, v96
	v_mov_b64_e32 v[54:55], s[20:21]
	v_add_f32_dpp v0, v0, v0 quad_perm:[2,3,0,1] row_mask:0xf bank_mask:0xf bound_ctrl:1
	s_movk_i32 s23, 0x4200
	s_mov_b32 s11, s17
	v_add_f32_dpp v0, v0, v0 row_half_mirror row_mask:0xf bank_mask:0xf bound_ctrl:1
	s_lshl_b32 s10, s10, 9
	v_lshlrev_b32_e32 v184, 1, v14
	v_add_f32_dpp v0, v0, v0 row_mirror row_mask:0xf bank_mask:0xf bound_ctrl:1
	v_mov_b32_e32 v1, v0
	s_nop 1
	v_permlane16_swap_b32_e32 v0, v1
	v_add_f32_e32 v0, v0, v1
	v_fmamk_f32 v0, v0, 0x3b800000, v218
	v_rsq_f32_e32 v90, v0
	v_mad_i64_i32 v[0:1], s[0:1], v52, s23, v[54:55]
	v_lshl_add_u64 v[0:1], v[0:1], 0, s[10:11]
	v_lshl_add_u64 v[106:107], v[0:1], 0, v[184:185]
	s_movk_i32 s22, 0x3000
	v_ashrrev_i32_e32 v53, 31, v52
	v_add_co_u32_e32 v106, vcc, s22, v106
	v_lshl_add_u64 v[50:51], v[16:17], 0, s[10:11]
	v_lshlrev_b64 v[0:1], 11, v[52:53]
	v_addc_co_u32_e32 v107, vcc, 0, v107, vcc
	v_lshl_add_u64 v[110:111], v[50:51], 0, v[0:1]
	global_load_dwordx4 v[0:3], v91, s[4:5] offset:16
	global_load_dwordx4 v[4:7], v91, s[4:5]
	v_pk_mul_f32 v[118:119], v[48:49], v[90:91] op_sel_hi:[1,0]
	global_load_dwordx4 v[106:109], v[106:107], off offset:2368
	v_pk_mul_f32 v[88:89], v[88:89], v[90:91] op_sel_hi:[1,0]
	s_movk_i32 s12, 0x7fff
	s_add_i32 s2, s2, s3
	v_lshl_add_u64 v[22:23], v[22:23], 0, s[6:7]
	s_waitcnt vmcnt(1)
	v_mov_b32_e32 v48, v4
	v_mov_b32_e32 v49, v6
	s_waitcnt vmcnt(0)
	v_lshlrev_b32_e32 v112, 16, v106
	v_mul_f32_e32 v53, 0xbfb8aa3b, v112
	v_exp_f32_e32 v53, v53
	v_and_b32_e32 v106, 0xffff0000, v106
	v_lshlrev_b32_e32 v113, 16, v107
	v_and_b32_e32 v107, 0xffff0000, v107
	v_add_f32_e32 v53, 1.0, v53
	v_rcp_f32_e32 v114, v53
	v_mul_f32_e32 v53, 0xbfb8aa3b, v106
	v_exp_f32_e32 v53, v53
	v_mul_f32_e32 v4, 0xbfb8aa3b, v113
	v_exp_f32_e32 v4, v4
	v_mov_b32_e32 v6, v5
	v_add_f32_e32 v53, 1.0, v53
	v_rcp_f32_e32 v116, v53
	v_mul_f32_e32 v53, 0xbfb8aa3b, v107
	v_exp_f32_e32 v53, v53
	v_add_f32_e32 v4, 1.0, v4
	v_rcp_f32_e32 v115, v4
	v_pk_mul_f32 v[4:5], v[6:7], v[88:89]
	v_add_f32_e32 v53, 1.0, v53
	v_rcp_f32_e32 v117, v53
	v_pk_mul_f32 v[118:119], v[48:49], v[118:119]
	v_pk_mul_f32 v[4:5], v[4:5], v[106:107]
	v_pk_mul_f32 v[118:119], v[118:119], v[112:113]
	v_pk_mul_f32 v[4:5], v[116:117], v[4:5]
	v_pk_mul_f32 v[112:113], v[114:115], v[118:119]
	v_and_b32_sdwa v91, v4, v217 dst_sel:DWORD dst_unused:UNUSED_PAD src0_sel:WORD_1 src1_sel:DWORD
	v_and_b32_sdwa v88, v112, v217 dst_sel:DWORD dst_unused:UNUSED_PAD src0_sel:WORD_1 src1_sel:DWORD
	v_add3_u32 v4, v4, v91, s12
	v_add3_u32 v88, v112, v88, s12
	v_and_b32_e32 v4, 0xffff0000, v4
	v_lshlrev_b32_e32 v106, 16, v108
	v_or_b32_sdwa v88, v4, v88 dst_sel:DWORD dst_unused:UNUSED_PAD src0_sel:DWORD src1_sel:WORD_1
	v_mul_f32_e32 v4, 0xbfb8aa3b, v106
	v_exp_f32_e32 v4, v4
	v_and_b32_e32 v108, 0xffff0000, v108
	v_lshlrev_b32_e32 v107, 16, v109
	v_and_b32_sdwa v89, v5, v217 dst_sel:DWORD dst_unused:UNUSED_PAD src0_sel:WORD_1 src1_sel:DWORD
	v_add_f32_e32 v4, 1.0, v4
	v_rcp_f32_e32 v112, v4
	v_mul_f32_e32 v4, 0xbfb8aa3b, v108
	v_exp_f32_e32 v4, v4
	v_and_b32_sdwa v53, v113, v217 dst_sel:DWORD dst_unused:UNUSED_PAD src0_sel:WORD_1 src1_sel:DWORD
	v_add3_u32 v5, v5, v89, s12
	v_add3_u32 v53, v113, v53, s12
	v_add_f32_e32 v4, 1.0, v4
	v_rcp_f32_e32 v114, v4
	v_mov_b32_e32 v4, v0
	v_mul_f32_e32 v0, 0xbfb8aa3b, v107
	v_exp_f32_e32 v0, v0
	v_and_b32_e32 v5, 0xffff0000, v5
	v_or_b32_sdwa v89, v5, v53 dst_sel:DWORD dst_unused:UNUSED_PAD src0_sel:DWORD src1_sel:WORD_1
	v_and_b32_e32 v109, 0xffff0000, v109
	v_mov_b32_e32 v5, v2
	v_add_f32_e32 v0, 1.0, v0
	v_pk_mul_f32 v[8:9], v[8:9], v[90:91] op_sel_hi:[1,0]
; #define DPPF(v, ctrl) __builtin_bit_cast(float, __builtin_amdgcn_update_dpp(0, __builtin_bit_cast(int, (v)), (ctrl), 0xf, 0xf, true))
; DI float sum8(float v) { v += DPPF(v, 0xB1); v += DPPF(v, 0x4E); v += DPPF(v, 0x141); return v; }
; DI unsigned pack2(float a, float b) { return (unsigned)f2bf(a) | ((unsigned)f2bf(b) << 16); }
; DI float bflo(unsigned w) { return __uint_as_float(w << 16); }
; DI float bfhi(unsigned w) { return __uint_as_float(w & 0xffff0000u); }
; DI float sigmoidf_(float x) { return __builtin_amdgcn_rcpf(1.0f + __expf(-x)); }
; DI void gla3_phase(const P& p, int l, const bf16_t* PROJ, const float* US, bf16_t* OGLA, char* smem, int bid, int nb) {
;     ...
;       for (int i = 0; i < 8; ++i) {
;         float ss = 0.f;
; #pragma unroll
;         for (int j = 0; j < 8; ++j) ss += o[i][j] * o[i][j];
;         ss = sum8(ss); ss += DPPF(ss, 0x140);
;         { const unsigned w = __builtin_bit_cast(unsigned, ss); auto pr = __builtin_amdgcn_permlane16_swap(w, w, false, false);
;           ss = __builtin_bit_cast(float, (unsigned)pr[0]) + __builtin_bit_cast(float, (unsigned)pr[1]); }
;         const float rstd = __builtin_amdgcn_rsqf(ss * (1.0f / 256.f) + 1e-5f);
;         const int t = c * 64 + ty * 8 + i;
;         const uint4 rw = *(const uint4*)(PROJ + (size_t)t * NP + C_GR + h * 256 + tx * 8);
;         const float rr[8] = {bflo(rw.x), bfhi(rw.x), bflo(rw.y), bfhi(rw.y), bflo(rw.z), bfhi(rw.z), bflo(rw.w), bfhi(rw.w)};
;         float y[8];
; #pragma unroll
;         for (int j = 0; j < 8; ++j) y[j] = o[i][j] * rstd * gn[j] * rr[j] * sigmoidf_(rr[j]);
;         uint4 w; w.x = pack2(y[0], y[1]); w.y = pack2(y[2], y[3]); w.z = pack2(y[4], y[5]); w.w = pack2(y[6], y[7]);
;         *(uint4*)(OGLA + (size_t)t * 1024 + h * 256 + tx * 8) = w;
	v_mov_b32_e32 v2, v1
	v_rcp_f32_e32 v113, v0
	v_pk_mul_f32 v[0:1], v[2:3], v[8:9]
	v_mul_f32_e32 v8, 0xbfb8aa3b, v109
	v_exp_f32_e32 v8, v8
	v_pk_mul_f32 v[10:11], v[10:11], v[90:91] op_sel_hi:[1,0]
	v_pk_mul_f32 v[0:1], v[0:1], v[108:109]
	v_pk_mul_f32 v[10:11], v[4:5], v[10:11]
	v_add_f32_e32 v8, 1.0, v8
	v_rcp_f32_e32 v115, v8
	v_pk_mul_f32 v[10:11], v[10:11], v[106:107]
	v_pk_mul_f32 v[0:1], v[0:1], v[114:115]
	v_pk_mul_f32 v[10:11], v[10:11], v[112:113]
	s_nop 0
	v_and_b32_sdwa v8, v11, v217 dst_sel:DWORD dst_unused:UNUSED_PAD src0_sel:WORD_1 src1_sel:DWORD
	v_and_b32_sdwa v9, v10, v217 dst_sel:DWORD dst_unused:UNUSED_PAD src0_sel:WORD_1 src1_sel:DWORD
	v_add3_u32 v9, v10, v9, s12
	v_add3_u32 v8, v11, v8, s12
	v_and_b32_sdwa v10, v1, v217 dst_sel:DWORD dst_unused:UNUSED_PAD src0_sel:WORD_1 src1_sel:DWORD
	v_and_b32_sdwa v11, v0, v217 dst_sel:DWORD dst_unused:UNUSED_PAD src0_sel:WORD_1 src1_sel:DWORD
	v_add3_u32 v1, v1, v10, s12
	v_add3_u32 v0, v0, v11, s12
	v_and_b32_e32 v1, 0xffff0000, v1
	v_and_b32_e32 v0, 0xffff0000, v0
	v_or_b32_sdwa v91, v1, v8 dst_sel:DWORD dst_unused:UNUSED_PAD src0_sel:DWORD src1_sel:WORD_1
	v_or_b32_sdwa v90, v0, v9 dst_sel:DWORD dst_unused:UNUSED_PAD src0_sel:DWORD src1_sel:WORD_1
	v_pk_mul_f32 v[0:1], v[86:87], v[86:87]
	v_pk_mul_f32 v[8:9], v[84:85], v[84:85]
	v_pk_mul_f32 v[10:11], v[82:83], v[82:83]
	v_add_f32_e32 v0, v0, v8
	v_add_f32_e32 v0, v1, v0
	v_add_f32_e32 v0, v9, v0
	global_store_dwordx4 v[110:111], v[88:91], off
	v_add_f32_e32 v0, v10, v0
	v_or_b32_e32 v8, 1, v52
	v_pk_mul_f32 v[88:89], v[80:81], v[80:81]
	v_ashrrev_i32_e32 v9, 31, v8
	v_add_f32_e32 v0, v88, v0
	v_add_f32_e32 v0, v11, v0
	v_mad_i64_i32 v[10:11], s[0:1], v8, s23, v[54:55]
	v_lshl_add_u64 v[10:11], v[10:11], 0, s[10:11]
	v_lshl_add_u64 v[10:11], v[10:11], 0, v[184:185]
	v_lshlrev_b64 v[8:9], 11, v[8:9]
	v_add_f32_e32 v0, v89, v0
	v_lshl_add_u64 v[88:89], v[50:51], 0, v[8:9]
	v_add_co_u32_e32 v8, vcc, s22, v10
	v_add_f32_dpp v0, v0, v0 quad_perm:[1,0,3,2] row_mask:0xf bank_mask:0xf bound_ctrl:1
	s_nop 0
	v_addc_co_u32_e32 v9, vcc, 0, v11, vcc
	global_load_dwordx4 v[8:11], v[8:9], off offset:2368
	v_add_f32_dpp v0, v0, v0 quad_perm:[2,3,0,1] row_mask:0xf bank_mask:0xf bound_ctrl:1
	s_waitcnt vmcnt(0)
	v_lshlrev_b32_e32 v90, 16, v8
	v_add_f32_dpp v0, v0, v0 row_half_mirror row_mask:0xf bank_mask:0xf bound_ctrl:1
	v_and_b32_e32 v8, 0xffff0000, v8
	v_lshlrev_b32_e32 v91, 16, v9
	v_add_f32_dpp v0, v0, v0 row_mirror row_mask:0xf bank_mask:0xf bound_ctrl:1
	v_mov_b32_e32 v1, v0
	s_nop 1
	v_permlane16_swap_b32_e32 v0, v1
	v_add_f32_e32 v0, v0, v1
	v_mul_f32_e32 v1, 0xbfb8aa3b, v90
	v_exp_f32_e32 v1, v1
	v_fmamk_f32 v0, v0, 0x3b800000, v218
	v_rsq_f32_e32 v0, v0
	v_and_b32_e32 v9, 0xffff0000, v9
	v_add_f32_e32 v1, 1.0, v1
	v_rcp_f32_e32 v106, v1
	v_mul_f32_e32 v1, 0xbfb8aa3b, v8
	v_exp_f32_e32 v1, v1
	s_nop 0
	v_add_f32_e32 v1, 1.0, v1
	v_rcp_f32_e32 v108, v1
	v_pk_mul_f32 v[86:87], v[86:87], v[0:1] op_sel_hi:[1,0]
	v_mul_f32_e32 v1, 0xbfb8aa3b, v91
	v_exp_f32_e32 v1, v1
	v_pk_mul_f32 v[86:87], v[48:49], v[86:87]
	v_add_f32_e32 v1, 1.0, v1
	v_rcp_f32_e32 v107, v1
	v_pk_mul_f32 v[84:85], v[84:85], v[0:1] op_sel_hi:[1,0]
	v_mul_f32_e32 v1, 0xbfb8aa3b, v9
	v_exp_f32_e32 v1, v1
	v_pk_mul_f32 v[84:85], v[6:7], v[84:85]
	v_pk_mul_f32 v[86:87], v[86:87], v[90:91]
	v_pk_mul_f32 v[84:85], v[84:85], v[8:9]
	v_add_f32_e32 v1, 1.0, v1
	v_rcp_f32_e32 v109, v1
	v_pk_mul_f32 v[86:87], v[106:107], v[86:87]
	v_pk_mul_f32 v[8:9], v[108:109], v[84:85]
	s_nop 0
	v_and_b32_sdwa v84, v9, v217 dst_sel:DWORD dst_unused:UNUSED_PAD src0_sel:WORD_1 src1_sel:DWORD
	v_and_b32_sdwa v1, v87, v217 dst_sel:DWORD dst_unused:UNUSED_PAD src0_sel:WORD_1 src1_sel:DWORD
	v_add3_u32 v9, v9, v84, s12
	v_add3_u32 v1, v87, v1, s12
	v_and_b32_e32 v9, 0xffff0000, v9
	v_lshlrev_b32_e32 v84, 16, v10
	v_or_b32_sdwa v9, v9, v1 dst_sel:DWORD dst_unused:UNUSED_PAD src0_sel:DWORD src1_sel:WORD_1
	v_mul_f32_e32 v1, 0xbfb8aa3b, v84
	v_exp_f32_e32 v1, v1
	v_and_b32_sdwa v53, v86, v217 dst_sel:DWORD dst_unused:UNUSED_PAD src0_sel:WORD_1 src1_sel:DWORD
	v_and_b32_e32 v10, 0xffff0000, v10
	v_add3_u32 v53, v86, v53, s12
	v_add_f32_e32 v1, 1.0, v1
	v_rcp_f32_e32 v86, v1
	v_mul_f32_e32 v1, 0xbfb8aa3b, v10
	v_exp_f32_e32 v1, v1
	v_and_b32_sdwa v85, v8, v217 dst_sel:DWORD dst_unused:UNUSED_PAD src0_sel:WORD_1 src1_sel:DWORD
	v_add3_u32 v8, v8, v85, s12
	v_lshlrev_b32_e32 v85, 16, v11
	v_add_f32_e32 v1, 1.0, v1
	v_rcp_f32_e32 v90, v1
	v_pk_mul_f32 v[82:83], v[82:83], v[0:1] op_sel_hi:[1,0]
	v_mul_f32_e32 v1, 0xbfb8aa3b, v85
	v_exp_f32_e32 v1, v1
	v_and_b32_e32 v11, 0xffff0000, v11
	v_pk_mul_f32 v[82:83], v[4:5], v[82:83]
	v_and_b32_e32 v8, 0xffff0000, v8
	v_add_f32_e32 v1, 1.0, v1
	v_rcp_f32_e32 v87, v1
	v_pk_mul_f32 v[0:1], v[80:81], v[0:1] op_sel_hi:[1,0]
	v_pk_mul_f32 v[82:83], v[82:83], v[84:85]
	v_pk_mul_f32 v[0:1], v[2:3], v[0:1]
	v_pk_mul_f32 v[82:83], v[82:83], v[86:87]
	v_pk_mul_f32 v[0:1], v[0:1], v[10:11]
	v_mul_f32_e32 v10, 0xbfb8aa3b, v11
	v_exp_f32_e32 v10, v10
	v_and_b32_sdwa v11, v82, v217 dst_sel:DWORD dst_unused:UNUSED_PAD src0_sel:WORD_1 src1_sel:DWORD
	v_or_b32_sdwa v8, v8, v53 dst_sel:DWORD dst_unused:UNUSED_PAD src0_sel:DWORD src1_sel:WORD_1
	v_add3_u32 v53, v82, v11, s12
	v_add_f32_e32 v10, 1.0, v10
	v_rcp_f32_e32 v91, v10
	v_and_b32_sdwa v10, v83, v217 dst_sel:DWORD dst_unused:UNUSED_PAD src0_sel:WORD_1 src1_sel:DWORD
	v_add3_u32 v10, v83, v10, s12
	v_pk_mul_f32 v[0:1], v[0:1], v[90:91]
	s_nop 0
	v_and_b32_sdwa v11, v1, v217 dst_sel:DWORD dst_unused:UNUSED_PAD src0_sel:WORD_1 src1_sel:DWORD
	v_and_b32_sdwa v80, v0, v217 dst_sel:DWORD dst_unused:UNUSED_PAD src0_sel:WORD_1 src1_sel:DWORD
	v_add3_u32 v1, v1, v11, s12
	v_add3_u32 v0, v0, v80, s12
	v_and_b32_e32 v1, 0xffff0000, v1
	v_and_b32_e32 v0, 0xffff0000, v0
	v_or_b32_sdwa v11, v1, v10 dst_sel:DWORD dst_unused:UNUSED_PAD src0_sel:DWORD src1_sel:WORD_1
	v_or_b32_sdwa v10, v0, v53 dst_sel:DWORD dst_unused:UNUSED_PAD src0_sel:DWORD src1_sel:WORD_1
	global_store_dwordx4 v[88:89], v[8:11], off
	v_pk_mul_f32 v[0:1], v[78:79], v[78:79]
	v_pk_mul_f32 v[80:81], v[72:73], v[72:73]
	v_pk_mul_f32 v[8:9], v[76:77], v[76:77]
	v_pk_mul_f32 v[10:11], v[74:75], v[74:75]
	v_add_f32_e32 v0, v0, v8
	v_add_f32_e32 v0, v1, v0
	v_add_f32_e32 v0, v9, v0
	v_add_f32_e32 v0, v10, v0
	v_add_f32_e32 v0, v80, v0
	v_or_b32_e32 v8, 2, v52
	v_add_f32_e32 v0, v11, v0
	v_mad_i64_i32 v[10:11], s[0:1], v8, s23, v[54:55]
	v_ashrrev_i32_e32 v9, 31, v8
	v_lshl_add_u64 v[10:11], v[10:11], 0, s[10:11]
	v_lshl_add_u64 v[10:11], v[10:11], 0, v[184:185]
	v_lshlrev_b64 v[8:9], 11, v[8:9]
	v_add_f32_e32 v0, v81, v0
	v_lshl_add_u64 v[80:81], v[50:51], 0, v[8:9]
	v_add_co_u32_e32 v8, vcc, s22, v10
	v_add_f32_dpp v0, v0, v0 quad_perm:[1,0,3,2] row_mask:0xf bank_mask:0xf bound_ctrl:1
	s_nop 0
	v_addc_co_u32_e32 v9, vcc, 0, v11, vcc
	global_load_dwordx4 v[8:11], v[8:9], off offset:2368
	v_add_f32_dpp v0, v0, v0 quad_perm:[2,3,0,1] row_mask:0xf bank_mask:0xf bound_ctrl:1
	s_waitcnt vmcnt(0)
; #define DPPF(v, ctrl) __builtin_bit_cast(float, __builtin_amdgcn_update_dpp(0, __builtin_bit_cast(int, (v)), (ctrl), 0xf, 0xf, true))
; DI float sum8(float v) { v += DPPF(v, 0xB1); v += DPPF(v, 0x4E); v += DPPF(v, 0x141); return v; }
; DI unsigned pack2(float a, float b) { return (unsigned)f2bf(a) | ((unsigned)f2bf(b) << 16); }
; DI float bflo(unsigned w) { return __uint_as_float(w << 16); }
; DI float bfhi(unsigned w) { return __uint_as_float(w & 0xffff0000u); }
; DI float sigmoidf_(float x) { return __builtin_amdgcn_rcpf(1.0f + __expf(-x)); }
; DI void gla3_phase(const P& p, int l, const bf16_t* PROJ, const float* US, bf16_t* OGLA, char* smem, int bid, int nb) {
;     ...
;       for (int i = 0; i < 8; ++i) {
;         float ss = 0.f;
; #pragma unroll
;         for (int j = 0; j < 8; ++j) ss += o[i][j] * o[i][j];
;         ss = sum8(ss); ss += DPPF(ss, 0x140);
;         { const unsigned w = __builtin_bit_cast(unsigned, ss); auto pr = __builtin_amdgcn_permlane16_swap(w, w, false, false);
;           ss = __builtin_bit_cast(float, (unsigned)pr[0]) + __builtin_bit_cast(float, (unsigned)pr[1]); }
;         const float rstd = __builtin_amdgcn_rsqf(ss * (1.0f / 256.f) + 1e-5f);
;         const int t = c * 64 + ty * 8 + i;
;         const uint4 rw = *(const uint4*)(PROJ + (size_t)t * NP + C_GR + h * 256 + tx * 8);
;         const float rr[8] = {bflo(rw.x), bfhi(rw.x), bflo(rw.y), bfhi(rw.y), bflo(rw.z), bfhi(rw.z), bflo(rw.w), bfhi(rw.w)};
;         float y[8];
; #pragma unroll
;         for (int j = 0; j < 8; ++j) y[j] = o[i][j] * rstd * gn[j] * rr[j] * sigmoidf_(rr[j]);
;         uint4 w; w.x = pack2(y[0], y[1]); w.y = pack2(y[2], y[3]); w.z = pack2(y[4], y[5]); w.w = pack2(y[6], y[7]);
;         *(uint4*)(OGLA + (size_t)t * 1024 + h * 256 + tx * 8) = w;
	v_lshlrev_b32_e32 v82, 16, v8
	v_add_f32_dpp v0, v0, v0 row_half_mirror row_mask:0xf bank_mask:0xf bound_ctrl:1
	v_and_b32_e32 v8, 0xffff0000, v8
	v_lshlrev_b32_e32 v83, 16, v9
	v_add_f32_dpp v0, v0, v0 row_mirror row_mask:0xf bank_mask:0xf bound_ctrl:1
	v_mov_b32_e32 v1, v0
	s_nop 1
	v_permlane16_swap_b32_e32 v0, v1
	v_add_f32_e32 v0, v0, v1
	v_mul_f32_e32 v1, 0xbfb8aa3b, v82
	v_exp_f32_e32 v1, v1
	v_fmamk_f32 v0, v0, 0x3b800000, v218
	v_rsq_f32_e32 v0, v0
	v_and_b32_e32 v9, 0xffff0000, v9
	v_add_f32_e32 v1, 1.0, v1
	v_rcp_f32_e32 v84, v1
	v_mul_f32_e32 v1, 0xbfb8aa3b, v8
	v_exp_f32_e32 v1, v1
	s_nop 0
	v_add_f32_e32 v1, 1.0, v1
	v_rcp_f32_e32 v86, v1
	v_pk_mul_f32 v[78:79], v[78:79], v[0:1] op_sel_hi:[1,0]
	v_mul_f32_e32 v1, 0xbfb8aa3b, v83
	v_exp_f32_e32 v1, v1
	v_pk_mul_f32 v[78:79], v[48:49], v[78:79]
	v_add_f32_e32 v1, 1.0, v1
	v_rcp_f32_e32 v85, v1
	v_pk_mul_f32 v[76:77], v[76:77], v[0:1] op_sel_hi:[1,0]
	v_mul_f32_e32 v1, 0xbfb8aa3b, v9
	v_exp_f32_e32 v1, v1
	v_pk_mul_f32 v[76:77], v[6:7], v[76:77]
	v_pk_mul_f32 v[78:79], v[78:79], v[82:83]
	v_pk_mul_f32 v[76:77], v[76:77], v[8:9]
	v_add_f32_e32 v1, 1.0, v1
	v_rcp_f32_e32 v87, v1
	v_pk_mul_f32 v[78:79], v[84:85], v[78:79]
	v_pk_mul_f32 v[8:9], v[86:87], v[76:77]
	s_nop 0
	v_and_b32_sdwa v76, v9, v217 dst_sel:DWORD dst_unused:UNUSED_PAD src0_sel:WORD_1 src1_sel:DWORD
	v_and_b32_sdwa v1, v79, v217 dst_sel:DWORD dst_unused:UNUSED_PAD src0_sel:WORD_1 src1_sel:DWORD
	v_add3_u32 v9, v9, v76, s12
	v_add3_u32 v1, v79, v1, s12
	v_and_b32_e32 v9, 0xffff0000, v9
	v_lshlrev_b32_e32 v76, 16, v10
	v_or_b32_sdwa v9, v9, v1 dst_sel:DWORD dst_unused:UNUSED_PAD src0_sel:DWORD src1_sel:WORD_1
	v_mul_f32_e32 v1, 0xbfb8aa3b, v76
	v_exp_f32_e32 v1, v1
	v_and_b32_sdwa v53, v78, v217 dst_sel:DWORD dst_unused:UNUSED_PAD src0_sel:WORD_1 src1_sel:DWORD
	v_and_b32_e32 v10, 0xffff0000, v10
	v_add3_u32 v53, v78, v53, s12
	v_add_f32_e32 v1, 1.0, v1
	v_rcp_f32_e32 v78, v1
	v_mul_f32_e32 v1, 0xbfb8aa3b, v10
	v_exp_f32_e32 v1, v1
	v_and_b32_sdwa v77, v8, v217 dst_sel:DWORD dst_unused:UNUSED_PAD src0_sel:WORD_1 src1_sel:DWORD
	v_add3_u32 v8, v8, v77, s12
	v_lshlrev_b32_e32 v77, 16, v11
	v_add_f32_e32 v1, 1.0, v1
	v_rcp_f32_e32 v82, v1
	v_pk_mul_f32 v[74:75], v[74:75], v[0:1] op_sel_hi:[1,0]
	v_mul_f32_e32 v1, 0xbfb8aa3b, v77
	v_exp_f32_e32 v1, v1
	v_and_b32_e32 v11, 0xffff0000, v11
	v_pk_mul_f32 v[74:75], v[4:5], v[74:75]
	v_and_b32_e32 v8, 0xffff0000, v8
	v_add_f32_e32 v1, 1.0, v1
	v_rcp_f32_e32 v79, v1
	v_pk_mul_f32 v[0:1], v[72:73], v[0:1] op_sel_hi:[1,0]
	v_pk_mul_f32 v[74:75], v[74:75], v[76:77]
	v_pk_mul_f32 v[0:1], v[2:3], v[0:1]
	v_pk_mul_f32 v[74:75], v[74:75], v[78:79]
	v_pk_mul_f32 v[0:1], v[0:1], v[10:11]
	v_mul_f32_e32 v10, 0xbfb8aa3b, v11
	v_exp_f32_e32 v10, v10
	v_and_b32_sdwa v11, v74, v217 dst_sel:DWORD dst_unused:UNUSED_PAD src0_sel:WORD_1 src1_sel:DWORD
	v_or_b32_sdwa v8, v8, v53 dst_sel:DWORD dst_unused:UNUSED_PAD src0_sel:DWORD src1_sel:WORD_1
	v_add3_u32 v53, v74, v11, s12
	v_add_f32_e32 v10, 1.0, v10
	v_rcp_f32_e32 v83, v10
	v_and_b32_sdwa v10, v75, v217 dst_sel:DWORD dst_unused:UNUSED_PAD src0_sel:WORD_1 src1_sel:DWORD
	v_add3_u32 v10, v75, v10, s12
	v_pk_mul_f32 v[0:1], v[0:1], v[82:83]
	s_nop 0
	v_and_b32_sdwa v11, v1, v217 dst_sel:DWORD dst_unused:UNUSED_PAD src0_sel:WORD_1 src1_sel:DWORD
	v_and_b32_sdwa v72, v0, v217 dst_sel:DWORD dst_unused:UNUSED_PAD src0_sel:WORD_1 src1_sel:DWORD
	v_add3_u32 v1, v1, v11, s12
	v_add3_u32 v0, v0, v72, s12
	v_and_b32_e32 v1, 0xffff0000, v1
	v_and_b32_e32 v0, 0xffff0000, v0
	v_or_b32_sdwa v11, v1, v10 dst_sel:DWORD dst_unused:UNUSED_PAD src0_sel:DWORD src1_sel:WORD_1
	v_or_b32_sdwa v10, v0, v53 dst_sel:DWORD dst_unused:UNUSED_PAD src0_sel:DWORD src1_sel:WORD_1
	global_store_dwordx4 v[80:81], v[8:11], off
	v_pk_mul_f32 v[0:1], v[70:71], v[70:71]
	v_pk_mul_f32 v[72:73], v[64:65], v[64:65]
	v_pk_mul_f32 v[8:9], v[68:69], v[68:69]
	v_pk_mul_f32 v[10:11], v[66:67], v[66:67]
	v_add_f32_e32 v0, v0, v8
	v_add_f32_e32 v0, v1, v0
	v_add_f32_e32 v0, v9, v0
	v_add_f32_e32 v0, v10, v0
	v_add_f32_e32 v0, v72, v0
	v_or_b32_e32 v8, 3, v52
	v_add_f32_e32 v0, v11, v0
	v_mad_i64_i32 v[10:11], s[0:1], v8, s23, v[54:55]
	v_ashrrev_i32_e32 v9, 31, v8
	v_lshl_add_u64 v[10:11], v[10:11], 0, s[10:11]
	v_lshl_add_u64 v[10:11], v[10:11], 0, v[184:185]
	v_lshlrev_b64 v[8:9], 11, v[8:9]
	v_add_f32_e32 v0, v73, v0
	v_lshl_add_u64 v[72:73], v[50:51], 0, v[8:9]
	v_add_co_u32_e32 v8, vcc, s22, v10
	v_add_f32_dpp v0, v0, v0 quad_perm:[1,0,3,2] row_mask:0xf bank_mask:0xf bound_ctrl:1
	s_nop 0
	v_addc_co_u32_e32 v9, vcc, 0, v11, vcc
	global_load_dwordx4 v[8:11], v[8:9], off offset:2368
	v_add_f32_dpp v0, v0, v0 quad_perm:[2,3,0,1] row_mask:0xf bank_mask:0xf bound_ctrl:1
	s_waitcnt vmcnt(0)
; #define DPPF(v, ctrl) __builtin_bit_cast(float, __builtin_amdgcn_update_dpp(0, __builtin_bit_cast(int, (v)), (ctrl), 0xf, 0xf, true))
; DI float sum8(float v) { v += DPPF(v, 0xB1); v += DPPF(v, 0x4E); v += DPPF(v, 0x141); return v; }
; DI unsigned pack2(float a, float b) { return (unsigned)f2bf(a) | ((unsigned)f2bf(b) << 16); }
; DI float bflo(unsigned w) { return __uint_as_float(w << 16); }
; DI float bfhi(unsigned w) { return __uint_as_float(w & 0xffff0000u); }
; DI float sigmoidf_(float x) { return __builtin_amdgcn_rcpf(1.0f + __expf(-x)); }
; DI void gla3_phase(const P& p, int l, const bf16_t* PROJ, const float* US, bf16_t* OGLA, char* smem, int bid, int nb) {
;     ...
;       for (int i = 0; i < 8; ++i) {
;         float ss = 0.f;
; #pragma unroll
;         for (int j = 0; j < 8; ++j) ss += o[i][j] * o[i][j];
;         ss = sum8(ss); ss += DPPF(ss, 0x140);
;         { const unsigned w = __builtin_bit_cast(unsigned, ss); auto pr = __builtin_amdgcn_permlane16_swap(w, w, false, false);
;           ss = __builtin_bit_cast(float, (unsigned)pr[0]) + __builtin_bit_cast(float, (unsigned)pr[1]); }
;         const float rstd = __builtin_amdgcn_rsqf(ss * (1.0f / 256.f) + 1e-5f);
;         const int t = c * 64 + ty * 8 + i;
;         const uint4 rw = *(const uint4*)(PROJ + (size_t)t * NP + C_GR + h * 256 + tx * 8);
;         const float rr[8] = {bflo(rw.x), bfhi(rw.x), bflo(rw.y), bfhi(rw.y), bflo(rw.z), bfhi(rw.z), bflo(rw.w), bfhi(rw.w)};
;         float y[8];
; #pragma unroll
;         for (int j = 0; j < 8; ++j) y[j] = o[i][j] * rstd * gn[j] * rr[j] * sigmoidf_(rr[j]);
;         uint4 w; w.x = pack2(y[0], y[1]); w.y = pack2(y[2], y[3]); w.z = pack2(y[4], y[5]); w.w = pack2(y[6], y[7]);
;         *(uint4*)(OGLA + (size_t)t * 1024 + h * 256 + tx * 8) = w;
	v_lshlrev_b32_e32 v74, 16, v8
	v_add_f32_dpp v0, v0, v0 row_half_mirror row_mask:0xf bank_mask:0xf bound_ctrl:1
	v_and_b32_e32 v8, 0xffff0000, v8
	v_lshlrev_b32_e32 v75, 16, v9
	v_add_f32_dpp v0, v0, v0 row_mirror row_mask:0xf bank_mask:0xf bound_ctrl:1
	v_mov_b32_e32 v1, v0
	s_nop 1
	v_permlane16_swap_b32_e32 v0, v1
	v_add_f32_e32 v0, v0, v1
	v_mul_f32_e32 v1, 0xbfb8aa3b, v74
	v_exp_f32_e32 v1, v1
	v_fmamk_f32 v0, v0, 0x3b800000, v218
	v_rsq_f32_e32 v0, v0
	v_and_b32_e32 v9, 0xffff0000, v9
	v_add_f32_e32 v1, 1.0, v1
	v_rcp_f32_e32 v76, v1
	v_mul_f32_e32 v1, 0xbfb8aa3b, v8
	v_exp_f32_e32 v1, v1
	s_nop 0
	v_add_f32_e32 v1, 1.0, v1
	v_rcp_f32_e32 v78, v1
	v_pk_mul_f32 v[70:71], v[70:71], v[0:1] op_sel_hi:[1,0]
	v_mul_f32_e32 v1, 0xbfb8aa3b, v75
	v_exp_f32_e32 v1, v1
	v_pk_mul_f32 v[70:71], v[48:49], v[70:71]
	v_add_f32_e32 v1, 1.0, v1
	v_rcp_f32_e32 v77, v1
	v_pk_mul_f32 v[68:69], v[68:69], v[0:1] op_sel_hi:[1,0]
	v_mul_f32_e32 v1, 0xbfb8aa3b, v9
	v_exp_f32_e32 v1, v1
	v_pk_mul_f32 v[68:69], v[6:7], v[68:69]
	v_pk_mul_f32 v[70:71], v[70:71], v[74:75]
	v_pk_mul_f32 v[68:69], v[68:69], v[8:9]
	v_add_f32_e32 v1, 1.0, v1
	v_rcp_f32_e32 v79, v1
	v_pk_mul_f32 v[70:71], v[76:77], v[70:71]
	v_pk_mul_f32 v[8:9], v[78:79], v[68:69]
	s_nop 0
	v_and_b32_sdwa v68, v9, v217 dst_sel:DWORD dst_unused:UNUSED_PAD src0_sel:WORD_1 src1_sel:DWORD
	v_and_b32_sdwa v1, v71, v217 dst_sel:DWORD dst_unused:UNUSED_PAD src0_sel:WORD_1 src1_sel:DWORD
	v_add3_u32 v9, v9, v68, s12
	v_add3_u32 v1, v71, v1, s12
	v_and_b32_e32 v9, 0xffff0000, v9
	v_lshlrev_b32_e32 v68, 16, v10
	v_or_b32_sdwa v9, v9, v1 dst_sel:DWORD dst_unused:UNUSED_PAD src0_sel:DWORD src1_sel:WORD_1
	v_mul_f32_e32 v1, 0xbfb8aa3b, v68
	v_exp_f32_e32 v1, v1
	v_and_b32_sdwa v53, v70, v217 dst_sel:DWORD dst_unused:UNUSED_PAD src0_sel:WORD_1 src1_sel:DWORD
	v_and_b32_e32 v10, 0xffff0000, v10
	v_add3_u32 v53, v70, v53, s12
	v_add_f32_e32 v1, 1.0, v1
	v_rcp_f32_e32 v70, v1
	v_mul_f32_e32 v1, 0xbfb8aa3b, v10
	v_exp_f32_e32 v1, v1
	v_and_b32_sdwa v69, v8, v217 dst_sel:DWORD dst_unused:UNUSED_PAD src0_sel:WORD_1 src1_sel:DWORD
	v_add3_u32 v8, v8, v69, s12
	v_lshlrev_b32_e32 v69, 16, v11
	v_add_f32_e32 v1, 1.0, v1
	v_rcp_f32_e32 v74, v1
	v_pk_mul_f32 v[66:67], v[66:67], v[0:1] op_sel_hi:[1,0]
	v_mul_f32_e32 v1, 0xbfb8aa3b, v69
	v_exp_f32_e32 v1, v1
	v_and_b32_e32 v11, 0xffff0000, v11
	v_pk_mul_f32 v[66:67], v[4:5], v[66:67]
	v_and_b32_e32 v8, 0xffff0000, v8
	v_add_f32_e32 v1, 1.0, v1
	v_rcp_f32_e32 v71, v1
	v_pk_mul_f32 v[0:1], v[64:65], v[0:1] op_sel_hi:[1,0]
	v_pk_mul_f32 v[66:67], v[66:67], v[68:69]
	v_pk_mul_f32 v[0:1], v[2:3], v[0:1]
	v_pk_mul_f32 v[66:67], v[66:67], v[70:71]
	v_pk_mul_f32 v[0:1], v[0:1], v[10:11]
	v_mul_f32_e32 v10, 0xbfb8aa3b, v11
	v_exp_f32_e32 v10, v10
	v_and_b32_sdwa v11, v66, v217 dst_sel:DWORD dst_unused:UNUSED_PAD src0_sel:WORD_1 src1_sel:DWORD
	v_or_b32_sdwa v8, v8, v53 dst_sel:DWORD dst_unused:UNUSED_PAD src0_sel:DWORD src1_sel:WORD_1
	v_add3_u32 v53, v66, v11, s12
	v_add_f32_e32 v10, 1.0, v10
	v_rcp_f32_e32 v75, v10
	v_and_b32_sdwa v10, v67, v217 dst_sel:DWORD dst_unused:UNUSED_PAD src0_sel:WORD_1 src1_sel:DWORD
	v_add3_u32 v10, v67, v10, s12
	v_pk_mul_f32 v[0:1], v[0:1], v[74:75]
	s_nop 0
	v_and_b32_sdwa v11, v1, v217 dst_sel:DWORD dst_unused:UNUSED_PAD src0_sel:WORD_1 src1_sel:DWORD
	v_and_b32_sdwa v64, v0, v217 dst_sel:DWORD dst_unused:UNUSED_PAD src0_sel:WORD_1 src1_sel:DWORD
	v_add3_u32 v1, v1, v11, s12
	v_add3_u32 v0, v0, v64, s12
	v_and_b32_e32 v1, 0xffff0000, v1
	v_and_b32_e32 v0, 0xffff0000, v0
	v_or_b32_sdwa v11, v1, v10 dst_sel:DWORD dst_unused:UNUSED_PAD src0_sel:DWORD src1_sel:WORD_1
	v_or_b32_sdwa v10, v0, v53 dst_sel:DWORD dst_unused:UNUSED_PAD src0_sel:DWORD src1_sel:WORD_1
	global_store_dwordx4 v[72:73], v[8:11], off
	v_pk_mul_f32 v[0:1], v[62:63], v[62:63]
	v_pk_mul_f32 v[64:65], v[56:57], v[56:57]
	v_pk_mul_f32 v[8:9], v[60:61], v[60:61]
	v_pk_mul_f32 v[10:11], v[58:59], v[58:59]
	v_add_f32_e32 v0, v0, v8
	v_add_f32_e32 v0, v1, v0
	v_add_f32_e32 v0, v9, v0
	v_add_f32_e32 v0, v10, v0
	v_add_f32_e32 v0, v64, v0
	v_or_b32_e32 v8, 4, v52
	v_add_f32_e32 v0, v11, v0
	v_mad_i64_i32 v[10:11], s[0:1], v8, s23, v[54:55]
	v_ashrrev_i32_e32 v9, 31, v8
	v_lshl_add_u64 v[10:11], v[10:11], 0, s[10:11]
	v_lshl_add_u64 v[10:11], v[10:11], 0, v[184:185]
	v_lshlrev_b64 v[8:9], 11, v[8:9]
	v_add_f32_e32 v0, v65, v0
	v_lshl_add_u64 v[64:65], v[50:51], 0, v[8:9]
	v_add_co_u32_e32 v8, vcc, s22, v10
	v_add_f32_dpp v0, v0, v0 quad_perm:[1,0,3,2] row_mask:0xf bank_mask:0xf bound_ctrl:1
	s_nop 0
	v_addc_co_u32_e32 v9, vcc, 0, v11, vcc
	global_load_dwordx4 v[8:11], v[8:9], off offset:2368
	v_add_f32_dpp v0, v0, v0 quad_perm:[2,3,0,1] row_mask:0xf bank_mask:0xf bound_ctrl:1
	s_waitcnt vmcnt(0)
; #define DPPF(v, ctrl) __builtin_bit_cast(float, __builtin_amdgcn_update_dpp(0, __builtin_bit_cast(int, (v)), (ctrl), 0xf, 0xf, true))
; DI float sum8(float v) { v += DPPF(v, 0xB1); v += DPPF(v, 0x4E); v += DPPF(v, 0x141); return v; }
; DI unsigned pack2(float a, float b) { return (unsigned)f2bf(a) | ((unsigned)f2bf(b) << 16); }
; DI float bflo(unsigned w) { return __uint_as_float(w << 16); }
; DI float bfhi(unsigned w) { return __uint_as_float(w & 0xffff0000u); }
; DI float sigmoidf_(float x) { return __builtin_amdgcn_rcpf(1.0f + __expf(-x)); }
; DI void gla3_phase(const P& p, int l, const bf16_t* PROJ, const float* US, bf16_t* OGLA, char* smem, int bid, int nb) {
;     ...
;       for (int i = 0; i < 8; ++i) {
;         float ss = 0.f;
; #pragma unroll
;         for (int j = 0; j < 8; ++j) ss += o[i][j] * o[i][j];
;         ss = sum8(ss); ss += DPPF(ss, 0x140);
;         { const unsigned w = __builtin_bit_cast(unsigned, ss); auto pr = __builtin_amdgcn_permlane16_swap(w, w, false, false);
;           ss = __builtin_bit_cast(float, (unsigned)pr[0]) + __builtin_bit_cast(float, (unsigned)pr[1]); }
;         const float rstd = __builtin_amdgcn_rsqf(ss * (1.0f / 256.f) + 1e-5f);
;         const int t = c * 64 + ty * 8 + i;
;         const uint4 rw = *(const uint4*)(PROJ + (size_t)t * NP + C_GR + h * 256 + tx * 8);
;         const float rr[8] = {bflo(rw.x), bfhi(rw.x), bflo(rw.y), bfhi(rw.y), bflo(rw.z), bfhi(rw.z), bflo(rw.w), bfhi(rw.w)};
;         float y[8];
; #pragma unroll
;         for (int j = 0; j < 8; ++j) y[j] = o[i][j] * rstd * gn[j] * rr[j] * sigmoidf_(rr[j]);
;         uint4 w; w.x = pack2(y[0], y[1]); w.y = pack2(y[2], y[3]); w.z = pack2(y[4], y[5]); w.w = pack2(y[6], y[7]);
;         *(uint4*)(OGLA + (size_t)t * 1024 + h * 256 + tx * 8) = w;
	v_lshlrev_b32_e32 v66, 16, v8
	v_add_f32_dpp v0, v0, v0 row_half_mirror row_mask:0xf bank_mask:0xf bound_ctrl:1
	v_and_b32_e32 v8, 0xffff0000, v8
	v_lshlrev_b32_e32 v67, 16, v9
	v_add_f32_dpp v0, v0, v0 row_mirror row_mask:0xf bank_mask:0xf bound_ctrl:1
	v_mov_b32_e32 v1, v0
	s_nop 1
	v_permlane16_swap_b32_e32 v0, v1
	v_add_f32_e32 v0, v0, v1
	v_mul_f32_e32 v1, 0xbfb8aa3b, v66
	v_exp_f32_e32 v1, v1
	v_fmamk_f32 v0, v0, 0x3b800000, v218
	v_rsq_f32_e32 v0, v0
	v_and_b32_e32 v9, 0xffff0000, v9
	v_add_f32_e32 v1, 1.0, v1
	v_rcp_f32_e32 v68, v1
	v_mul_f32_e32 v1, 0xbfb8aa3b, v8
	v_exp_f32_e32 v1, v1
	s_nop 0
	v_add_f32_e32 v1, 1.0, v1
	v_rcp_f32_e32 v70, v1
	v_pk_mul_f32 v[62:63], v[62:63], v[0:1] op_sel_hi:[1,0]
	v_mul_f32_e32 v1, 0xbfb8aa3b, v67
	v_exp_f32_e32 v1, v1
	v_pk_mul_f32 v[62:63], v[48:49], v[62:63]
	v_add_f32_e32 v1, 1.0, v1
	v_rcp_f32_e32 v69, v1
	v_pk_mul_f32 v[60:61], v[60:61], v[0:1] op_sel_hi:[1,0]
	v_mul_f32_e32 v1, 0xbfb8aa3b, v9
	v_exp_f32_e32 v1, v1
	v_pk_mul_f32 v[60:61], v[6:7], v[60:61]
	v_pk_mul_f32 v[62:63], v[62:63], v[66:67]
	v_pk_mul_f32 v[60:61], v[60:61], v[8:9]
	v_add_f32_e32 v1, 1.0, v1
	v_rcp_f32_e32 v71, v1
	v_pk_mul_f32 v[62:63], v[68:69], v[62:63]
	v_pk_mul_f32 v[8:9], v[70:71], v[60:61]
	s_nop 0
	v_and_b32_sdwa v60, v9, v217 dst_sel:DWORD dst_unused:UNUSED_PAD src0_sel:WORD_1 src1_sel:DWORD
	v_and_b32_sdwa v1, v63, v217 dst_sel:DWORD dst_unused:UNUSED_PAD src0_sel:WORD_1 src1_sel:DWORD
	v_add3_u32 v9, v9, v60, s12
	v_add3_u32 v1, v63, v1, s12
	v_and_b32_e32 v9, 0xffff0000, v9
	v_lshlrev_b32_e32 v60, 16, v10
	v_or_b32_sdwa v9, v9, v1 dst_sel:DWORD dst_unused:UNUSED_PAD src0_sel:DWORD src1_sel:WORD_1
	v_mul_f32_e32 v1, 0xbfb8aa3b, v60
	v_exp_f32_e32 v1, v1
	v_and_b32_sdwa v53, v62, v217 dst_sel:DWORD dst_unused:UNUSED_PAD src0_sel:WORD_1 src1_sel:DWORD
	v_and_b32_e32 v10, 0xffff0000, v10
	v_add3_u32 v53, v62, v53, s12
	v_add_f32_e32 v1, 1.0, v1
	v_rcp_f32_e32 v62, v1
	v_mul_f32_e32 v1, 0xbfb8aa3b, v10
	v_exp_f32_e32 v1, v1
	v_and_b32_sdwa v61, v8, v217 dst_sel:DWORD dst_unused:UNUSED_PAD src0_sel:WORD_1 src1_sel:DWORD
	v_add3_u32 v8, v8, v61, s12
	v_lshlrev_b32_e32 v61, 16, v11
	v_add_f32_e32 v1, 1.0, v1
	v_rcp_f32_e32 v66, v1
	v_pk_mul_f32 v[58:59], v[58:59], v[0:1] op_sel_hi:[1,0]
	v_mul_f32_e32 v1, 0xbfb8aa3b, v61
	v_exp_f32_e32 v1, v1
	v_and_b32_e32 v11, 0xffff0000, v11
	v_pk_mul_f32 v[58:59], v[4:5], v[58:59]
	v_and_b32_e32 v8, 0xffff0000, v8
	v_add_f32_e32 v1, 1.0, v1
	v_rcp_f32_e32 v63, v1
	v_pk_mul_f32 v[0:1], v[56:57], v[0:1] op_sel_hi:[1,0]
	v_pk_mul_f32 v[58:59], v[58:59], v[60:61]
	v_pk_mul_f32 v[0:1], v[2:3], v[0:1]
	v_pk_mul_f32 v[58:59], v[58:59], v[62:63]
	v_pk_mul_f32 v[0:1], v[0:1], v[10:11]
	v_mul_f32_e32 v10, 0xbfb8aa3b, v11
	v_exp_f32_e32 v10, v10
	v_and_b32_sdwa v11, v58, v217 dst_sel:DWORD dst_unused:UNUSED_PAD src0_sel:WORD_1 src1_sel:DWORD
	v_or_b32_sdwa v8, v8, v53 dst_sel:DWORD dst_unused:UNUSED_PAD src0_sel:DWORD src1_sel:WORD_1
	v_add3_u32 v53, v58, v11, s12
	v_add_f32_e32 v10, 1.0, v10
	v_rcp_f32_e32 v67, v10
	v_and_b32_sdwa v10, v59, v217 dst_sel:DWORD dst_unused:UNUSED_PAD src0_sel:WORD_1 src1_sel:DWORD
	v_add3_u32 v10, v59, v10, s12
	v_pk_mul_f32 v[0:1], v[0:1], v[66:67]
	s_nop 0
	v_and_b32_sdwa v11, v1, v217 dst_sel:DWORD dst_unused:UNUSED_PAD src0_sel:WORD_1 src1_sel:DWORD
	v_and_b32_sdwa v56, v0, v217 dst_sel:DWORD dst_unused:UNUSED_PAD src0_sel:WORD_1 src1_sel:DWORD
	v_add3_u32 v1, v1, v11, s12
	v_add3_u32 v0, v0, v56, s12
	v_and_b32_e32 v1, 0xffff0000, v1
	v_and_b32_e32 v0, 0xffff0000, v0
	v_or_b32_sdwa v11, v1, v10 dst_sel:DWORD dst_unused:UNUSED_PAD src0_sel:DWORD src1_sel:WORD_1
	v_or_b32_sdwa v10, v0, v53 dst_sel:DWORD dst_unused:UNUSED_PAD src0_sel:DWORD src1_sel:WORD_1
	global_store_dwordx4 v[64:65], v[8:11], off
	v_pk_mul_f32 v[0:1], v[46:47], v[46:47]
	v_pk_mul_f32 v[56:57], v[40:41], v[40:41]
	v_pk_mul_f32 v[8:9], v[44:45], v[44:45]
	v_pk_mul_f32 v[10:11], v[42:43], v[42:43]
	v_add_f32_e32 v0, v0, v8
	v_add_f32_e32 v0, v1, v0
	v_add_f32_e32 v0, v9, v0
	v_add_f32_e32 v0, v10, v0
	v_add_f32_e32 v0, v56, v0
	v_or_b32_e32 v8, 5, v52
	v_add_f32_e32 v0, v11, v0
	v_mad_i64_i32 v[10:11], s[0:1], v8, s23, v[54:55]
	v_ashrrev_i32_e32 v9, 31, v8
	v_lshl_add_u64 v[10:11], v[10:11], 0, s[10:11]
	v_lshl_add_u64 v[10:11], v[10:11], 0, v[184:185]
	v_lshlrev_b64 v[8:9], 11, v[8:9]
	v_add_f32_e32 v0, v57, v0
	v_lshl_add_u64 v[56:57], v[50:51], 0, v[8:9]
	v_add_co_u32_e32 v8, vcc, s22, v10
	v_add_f32_dpp v0, v0, v0 quad_perm:[1,0,3,2] row_mask:0xf bank_mask:0xf bound_ctrl:1
	s_nop 0
	v_addc_co_u32_e32 v9, vcc, 0, v11, vcc
	global_load_dwordx4 v[8:11], v[8:9], off offset:2368
	v_add_f32_dpp v0, v0, v0 quad_perm:[2,3,0,1] row_mask:0xf bank_mask:0xf bound_ctrl:1
	s_waitcnt vmcnt(0)
; #define DPPF(v, ctrl) __builtin_bit_cast(float, __builtin_amdgcn_update_dpp(0, __builtin_bit_cast(int, (v)), (ctrl), 0xf, 0xf, true))
; DI float sum8(float v) { v += DPPF(v, 0xB1); v += DPPF(v, 0x4E); v += DPPF(v, 0x141); return v; }
; DI unsigned pack2(float a, float b) { return (unsigned)f2bf(a) | ((unsigned)f2bf(b) << 16); }
; DI float bflo(unsigned w) { return __uint_as_float(w << 16); }
; DI float bfhi(unsigned w) { return __uint_as_float(w & 0xffff0000u); }
; DI float sigmoidf_(float x) { return __builtin_amdgcn_rcpf(1.0f + __expf(-x)); }
; DI void gla3_phase(const P& p, int l, const bf16_t* PROJ, const float* US, bf16_t* OGLA, char* smem, int bid, int nb) {
;     ...
;       for (int i = 0; i < 8; ++i) {
;         float ss = 0.f;
; #pragma unroll
;         for (int j = 0; j < 8; ++j) ss += o[i][j] * o[i][j];
;         ss = sum8(ss); ss += DPPF(ss, 0x140);
;         { const unsigned w = __builtin_bit_cast(unsigned, ss); auto pr = __builtin_amdgcn_permlane16_swap(w, w, false, false);
;           ss = __builtin_bit_cast(float, (unsigned)pr[0]) + __builtin_bit_cast(float, (unsigned)pr[1]); }
;         const float rstd = __builtin_amdgcn_rsqf(ss * (1.0f / 256.f) + 1e-5f);
;         const int t = c * 64 + ty * 8 + i;
;         const uint4 rw = *(const uint4*)(PROJ + (size_t)t * NP + C_GR + h * 256 + tx * 8);
;         const float rr[8] = {bflo(rw.x), bfhi(rw.x), bflo(rw.y), bfhi(rw.y), bflo(rw.z), bfhi(rw.z), bflo(rw.w), bfhi(rw.w)};
;         float y[8];
; #pragma unroll
;         for (int j = 0; j < 8; ++j) y[j] = o[i][j] * rstd * gn[j] * rr[j] * sigmoidf_(rr[j]);
;         uint4 w; w.x = pack2(y[0], y[1]); w.y = pack2(y[2], y[3]); w.z = pack2(y[4], y[5]); w.w = pack2(y[6], y[7]);
;         *(uint4*)(OGLA + (size_t)t * 1024 + h * 256 + tx * 8) = w;
	v_lshlrev_b32_e32 v58, 16, v8
	v_add_f32_dpp v0, v0, v0 row_half_mirror row_mask:0xf bank_mask:0xf bound_ctrl:1
	v_and_b32_e32 v8, 0xffff0000, v8
	v_lshlrev_b32_e32 v59, 16, v9
	v_add_f32_dpp v0, v0, v0 row_mirror row_mask:0xf bank_mask:0xf bound_ctrl:1
	v_mov_b32_e32 v1, v0
	s_nop 1
	v_permlane16_swap_b32_e32 v0, v1
	v_add_f32_e32 v0, v0, v1
	v_mul_f32_e32 v1, 0xbfb8aa3b, v58
	v_exp_f32_e32 v1, v1
	v_fmamk_f32 v0, v0, 0x3b800000, v218
	v_rsq_f32_e32 v0, v0
	v_and_b32_e32 v9, 0xffff0000, v9
	v_add_f32_e32 v1, 1.0, v1
	v_rcp_f32_e32 v60, v1
	v_mul_f32_e32 v1, 0xbfb8aa3b, v8
	v_exp_f32_e32 v1, v1
	s_nop 0
	v_add_f32_e32 v1, 1.0, v1
	v_rcp_f32_e32 v62, v1
	v_pk_mul_f32 v[46:47], v[46:47], v[0:1] op_sel_hi:[1,0]
	v_mul_f32_e32 v1, 0xbfb8aa3b, v59
	v_exp_f32_e32 v1, v1
	v_pk_mul_f32 v[46:47], v[48:49], v[46:47]
	v_add_f32_e32 v1, 1.0, v1
	v_rcp_f32_e32 v61, v1
	v_pk_mul_f32 v[44:45], v[44:45], v[0:1] op_sel_hi:[1,0]
	v_mul_f32_e32 v1, 0xbfb8aa3b, v9
	v_exp_f32_e32 v1, v1
	v_pk_mul_f32 v[46:47], v[46:47], v[58:59]
	v_pk_mul_f32 v[44:45], v[6:7], v[44:45]
	v_pk_mul_f32 v[46:47], v[60:61], v[46:47]
	v_add_f32_e32 v1, 1.0, v1
	v_rcp_f32_e32 v63, v1
	v_pk_mul_f32 v[44:45], v[44:45], v[8:9]
	v_and_b32_sdwa v1, v47, v217 dst_sel:DWORD dst_unused:UNUSED_PAD src0_sel:WORD_1 src1_sel:DWORD
	v_add3_u32 v1, v47, v1, s12
	v_pk_mul_f32 v[8:9], v[62:63], v[44:45]
	v_and_b32_sdwa v44, v46, v217 dst_sel:DWORD dst_unused:UNUSED_PAD src0_sel:WORD_1 src1_sel:DWORD
	v_add3_u32 v44, v46, v44, s12
	v_and_b32_sdwa v46, v8, v217 dst_sel:DWORD dst_unused:UNUSED_PAD src0_sel:WORD_1 src1_sel:DWORD
	v_and_b32_sdwa v45, v9, v217 dst_sel:DWORD dst_unused:UNUSED_PAD src0_sel:WORD_1 src1_sel:DWORD
	v_add3_u32 v8, v8, v46, s12
	v_add3_u32 v9, v9, v45, s12
	v_and_b32_e32 v8, 0xffff0000, v8
	v_and_b32_e32 v9, 0xffff0000, v9
	v_or_b32_sdwa v8, v8, v44 dst_sel:DWORD dst_unused:UNUSED_PAD src0_sel:DWORD src1_sel:WORD_1
	v_lshlrev_b32_e32 v44, 16, v10
	v_or_b32_sdwa v9, v9, v1 dst_sel:DWORD dst_unused:UNUSED_PAD src0_sel:DWORD src1_sel:WORD_1
	v_mul_f32_e32 v1, 0xbfb8aa3b, v44
	v_exp_f32_e32 v1, v1
	v_and_b32_e32 v10, 0xffff0000, v10
	v_lshlrev_b32_e32 v45, 16, v11
	v_and_b32_e32 v11, 0xffff0000, v11
	v_add_f32_e32 v1, 1.0, v1
	v_rcp_f32_e32 v46, v1
	v_mul_f32_e32 v1, 0xbfb8aa3b, v10
	v_exp_f32_e32 v1, v1
	s_nop 0
	v_add_f32_e32 v1, 1.0, v1
	v_rcp_f32_e32 v58, v1
	v_pk_mul_f32 v[42:43], v[42:43], v[0:1] op_sel_hi:[1,0]
	v_mul_f32_e32 v1, 0xbfb8aa3b, v45
	v_exp_f32_e32 v1, v1
	v_pk_mul_f32 v[42:43], v[4:5], v[42:43]
	v_add_f32_e32 v1, 1.0, v1
	v_rcp_f32_e32 v47, v1
	v_pk_mul_f32 v[0:1], v[40:41], v[0:1] op_sel_hi:[1,0]
	v_pk_mul_f32 v[42:43], v[42:43], v[44:45]
	v_pk_mul_f32 v[0:1], v[2:3], v[0:1]
	v_pk_mul_f32 v[42:43], v[42:43], v[46:47]
	v_pk_mul_f32 v[0:1], v[0:1], v[10:11]
	v_mul_f32_e32 v10, 0xbfb8aa3b, v11
	v_exp_f32_e32 v10, v10
	v_and_b32_sdwa v11, v42, v217 dst_sel:DWORD dst_unused:UNUSED_PAD src0_sel:WORD_1 src1_sel:DWORD
	v_add3_u32 v40, v42, v11, s12
	v_add_f32_e32 v10, 1.0, v10
	v_rcp_f32_e32 v59, v10
	v_and_b32_sdwa v10, v43, v217 dst_sel:DWORD dst_unused:UNUSED_PAD src0_sel:WORD_1 src1_sel:DWORD
	v_add3_u32 v10, v43, v10, s12
	v_pk_mul_f32 v[0:1], v[0:1], v[58:59]
	s_nop 0
	v_and_b32_sdwa v11, v1, v217 dst_sel:DWORD dst_unused:UNUSED_PAD src0_sel:WORD_1 src1_sel:DWORD
	v_and_b32_sdwa v41, v0, v217 dst_sel:DWORD dst_unused:UNUSED_PAD src0_sel:WORD_1 src1_sel:DWORD
	v_add3_u32 v1, v1, v11, s12
	v_add3_u32 v0, v0, v41, s12
	v_and_b32_e32 v1, 0xffff0000, v1
	v_and_b32_e32 v0, 0xffff0000, v0
	v_or_b32_sdwa v11, v1, v10 dst_sel:DWORD dst_unused:UNUSED_PAD src0_sel:DWORD src1_sel:WORD_1
	v_or_b32_sdwa v10, v0, v40 dst_sel:DWORD dst_unused:UNUSED_PAD src0_sel:DWORD src1_sel:WORD_1
	global_store_dwordx4 v[56:57], v[8:11], off
	v_pk_mul_f32 v[0:1], v[38:39], v[38:39]
	v_pk_mul_f32 v[40:41], v[32:33], v[32:33]
	v_pk_mul_f32 v[8:9], v[36:37], v[36:37]
	v_pk_mul_f32 v[10:11], v[34:35], v[34:35]
	v_add_f32_e32 v0, v0, v8
	v_add_f32_e32 v0, v1, v0
	v_add_f32_e32 v0, v9, v0
	v_add_f32_e32 v0, v10, v0
	v_add_f32_e32 v0, v40, v0
	v_or_b32_e32 v8, 6, v52
	v_add_f32_e32 v0, v11, v0
	v_mad_i64_i32 v[10:11], s[0:1], v8, s23, v[54:55]
	v_ashrrev_i32_e32 v9, 31, v8
	v_lshl_add_u64 v[10:11], v[10:11], 0, s[10:11]
	v_lshl_add_u64 v[10:11], v[10:11], 0, v[184:185]
	v_lshlrev_b64 v[8:9], 11, v[8:9]
	v_add_f32_e32 v0, v41, v0
	v_lshl_add_u64 v[40:41], v[50:51], 0, v[8:9]
	v_add_co_u32_e32 v8, vcc, s22, v10
	v_add_f32_dpp v0, v0, v0 quad_perm:[1,0,3,2] row_mask:0xf bank_mask:0xf bound_ctrl:1
	s_nop 0
	v_addc_co_u32_e32 v9, vcc, 0, v11, vcc
	global_load_dwordx4 v[8:11], v[8:9], off offset:2368
	v_add_f32_dpp v0, v0, v0 quad_perm:[2,3,0,1] row_mask:0xf bank_mask:0xf bound_ctrl:1
	s_waitcnt vmcnt(0)
; #define DPPF(v, ctrl) __builtin_bit_cast(float, __builtin_amdgcn_update_dpp(0, __builtin_bit_cast(int, (v)), (ctrl), 0xf, 0xf, true))
; DI float sum8(float v) { v += DPPF(v, 0xB1); v += DPPF(v, 0x4E); v += DPPF(v, 0x141); return v; }
; DI unsigned pack2(float a, float b) { return (unsigned)f2bf(a) | ((unsigned)f2bf(b) << 16); }
; DI float bflo(unsigned w) { return __uint_as_float(w << 16); }
; DI float bfhi(unsigned w) { return __uint_as_float(w & 0xffff0000u); }
; DI float sigmoidf_(float x) { return __builtin_amdgcn_rcpf(1.0f + __expf(-x)); }
; DI void gla3_phase(const P& p, int l, const bf16_t* PROJ, const float* US, bf16_t* OGLA, char* smem, int bid, int nb) {
;     ...
;       for (int i = 0; i < 8; ++i) {
;         float ss = 0.f;
; #pragma unroll
;         for (int j = 0; j < 8; ++j) ss += o[i][j] * o[i][j];
;         ss = sum8(ss); ss += DPPF(ss, 0x140);
;         { const unsigned w = __builtin_bit_cast(unsigned, ss); auto pr = __builtin_amdgcn_permlane16_swap(w, w, false, false);
;           ss = __builtin_bit_cast(float, (unsigned)pr[0]) + __builtin_bit_cast(float, (unsigned)pr[1]); }
;         const float rstd = __builtin_amdgcn_rsqf(ss * (1.0f / 256.f) + 1e-5f);
;         const int t = c * 64 + ty * 8 + i;
;         const uint4 rw = *(const uint4*)(PROJ + (size_t)t * NP + C_GR + h * 256 + tx * 8);
;         const float rr[8] = {bflo(rw.x), bfhi(rw.x), bflo(rw.y), bfhi(rw.y), bflo(rw.z), bfhi(rw.z), bflo(rw.w), bfhi(rw.w)};
;         float y[8];
; #pragma unroll
;         for (int j = 0; j < 8; ++j) y[j] = o[i][j] * rstd * gn[j] * rr[j] * sigmoidf_(rr[j]);
;         uint4 w; w.x = pack2(y[0], y[1]); w.y = pack2(y[2], y[3]); w.z = pack2(y[4], y[5]); w.w = pack2(y[6], y[7]);
;         *(uint4*)(OGLA + (size_t)t * 1024 + h * 256 + tx * 8) = w;
	v_lshlrev_b32_e32 v42, 16, v8
	v_add_f32_dpp v0, v0, v0 row_half_mirror row_mask:0xf bank_mask:0xf bound_ctrl:1
	v_and_b32_e32 v8, 0xffff0000, v8
	v_lshlrev_b32_e32 v43, 16, v9
	v_add_f32_dpp v0, v0, v0 row_mirror row_mask:0xf bank_mask:0xf bound_ctrl:1
	v_mov_b32_e32 v1, v0
	s_nop 1
	v_permlane16_swap_b32_e32 v0, v1
	v_add_f32_e32 v0, v0, v1
	v_mul_f32_e32 v1, 0xbfb8aa3b, v42
	v_exp_f32_e32 v1, v1
	v_fmamk_f32 v0, v0, 0x3b800000, v218
	v_rsq_f32_e32 v0, v0
	v_and_b32_e32 v9, 0xffff0000, v9
	v_add_f32_e32 v1, 1.0, v1
	v_rcp_f32_e32 v44, v1
	v_mul_f32_e32 v1, 0xbfb8aa3b, v8
	v_exp_f32_e32 v1, v1
	s_nop 0
	v_add_f32_e32 v1, 1.0, v1
	v_rcp_f32_e32 v46, v1
	v_pk_mul_f32 v[38:39], v[38:39], v[0:1] op_sel_hi:[1,0]
	v_mul_f32_e32 v1, 0xbfb8aa3b, v43
	v_exp_f32_e32 v1, v1
	v_pk_mul_f32 v[38:39], v[48:49], v[38:39]
	v_add_f32_e32 v1, 1.0, v1
	v_rcp_f32_e32 v45, v1
	v_pk_mul_f32 v[36:37], v[36:37], v[0:1] op_sel_hi:[1,0]
	v_mul_f32_e32 v1, 0xbfb8aa3b, v9
	v_exp_f32_e32 v1, v1
	v_pk_mul_f32 v[38:39], v[38:39], v[42:43]
	v_pk_mul_f32 v[36:37], v[6:7], v[36:37]
	v_pk_mul_f32 v[38:39], v[44:45], v[38:39]
	v_add_f32_e32 v1, 1.0, v1
	v_rcp_f32_e32 v47, v1
	v_pk_mul_f32 v[36:37], v[36:37], v[8:9]
	v_and_b32_sdwa v1, v39, v217 dst_sel:DWORD dst_unused:UNUSED_PAD src0_sel:WORD_1 src1_sel:DWORD
	v_add3_u32 v1, v39, v1, s12
	v_pk_mul_f32 v[8:9], v[46:47], v[36:37]
	v_and_b32_sdwa v36, v38, v217 dst_sel:DWORD dst_unused:UNUSED_PAD src0_sel:WORD_1 src1_sel:DWORD
	v_add3_u32 v36, v38, v36, s12
	v_and_b32_sdwa v38, v8, v217 dst_sel:DWORD dst_unused:UNUSED_PAD src0_sel:WORD_1 src1_sel:DWORD
	v_and_b32_sdwa v37, v9, v217 dst_sel:DWORD dst_unused:UNUSED_PAD src0_sel:WORD_1 src1_sel:DWORD
	v_add3_u32 v8, v8, v38, s12
	v_add3_u32 v9, v9, v37, s12
	v_and_b32_e32 v8, 0xffff0000, v8
	v_and_b32_e32 v9, 0xffff0000, v9
	v_or_b32_sdwa v8, v8, v36 dst_sel:DWORD dst_unused:UNUSED_PAD src0_sel:DWORD src1_sel:WORD_1
	v_lshlrev_b32_e32 v36, 16, v10
	v_or_b32_sdwa v9, v9, v1 dst_sel:DWORD dst_unused:UNUSED_PAD src0_sel:DWORD src1_sel:WORD_1
	v_mul_f32_e32 v1, 0xbfb8aa3b, v36
	v_exp_f32_e32 v1, v1
	v_and_b32_e32 v10, 0xffff0000, v10
	v_lshlrev_b32_e32 v37, 16, v11
	v_and_b32_e32 v11, 0xffff0000, v11
	v_add_f32_e32 v1, 1.0, v1
	v_rcp_f32_e32 v38, v1
	v_mul_f32_e32 v1, 0xbfb8aa3b, v10
	v_exp_f32_e32 v1, v1
	s_nop 0
	v_add_f32_e32 v1, 1.0, v1
	v_rcp_f32_e32 v42, v1
	v_pk_mul_f32 v[34:35], v[34:35], v[0:1] op_sel_hi:[1,0]
	v_mul_f32_e32 v1, 0xbfb8aa3b, v37
	v_exp_f32_e32 v1, v1
	v_pk_mul_f32 v[34:35], v[4:5], v[34:35]
	v_add_f32_e32 v1, 1.0, v1
	v_rcp_f32_e32 v39, v1
	v_pk_mul_f32 v[0:1], v[32:33], v[0:1] op_sel_hi:[1,0]
	v_pk_mul_f32 v[34:35], v[34:35], v[36:37]
	v_pk_mul_f32 v[0:1], v[2:3], v[0:1]
	v_pk_mul_f32 v[34:35], v[34:35], v[38:39]
	v_pk_mul_f32 v[0:1], v[0:1], v[10:11]
	v_mul_f32_e32 v10, 0xbfb8aa3b, v11
	v_exp_f32_e32 v10, v10
	v_and_b32_sdwa v11, v34, v217 dst_sel:DWORD dst_unused:UNUSED_PAD src0_sel:WORD_1 src1_sel:DWORD
	v_add3_u32 v32, v34, v11, s12
	v_add_f32_e32 v10, 1.0, v10
	v_rcp_f32_e32 v43, v10
	v_and_b32_sdwa v10, v35, v217 dst_sel:DWORD dst_unused:UNUSED_PAD src0_sel:WORD_1 src1_sel:DWORD
	v_add3_u32 v10, v35, v10, s12
	v_pk_mul_f32 v[0:1], v[0:1], v[42:43]
	s_nop 0
	v_and_b32_sdwa v11, v1, v217 dst_sel:DWORD dst_unused:UNUSED_PAD src0_sel:WORD_1 src1_sel:DWORD
	v_and_b32_sdwa v33, v0, v217 dst_sel:DWORD dst_unused:UNUSED_PAD src0_sel:WORD_1 src1_sel:DWORD
	v_add3_u32 v1, v1, v11, s12
	v_add3_u32 v0, v0, v33, s12
	v_and_b32_e32 v1, 0xffff0000, v1
	v_and_b32_e32 v0, 0xffff0000, v0
	v_or_b32_sdwa v11, v1, v10 dst_sel:DWORD dst_unused:UNUSED_PAD src0_sel:DWORD src1_sel:WORD_1
	v_or_b32_sdwa v10, v0, v32 dst_sel:DWORD dst_unused:UNUSED_PAD src0_sel:DWORD src1_sel:WORD_1
	global_store_dwordx4 v[40:41], v[8:11], off
	v_pk_mul_f32 v[0:1], v[30:31], v[30:31]
	v_pk_mul_f32 v[32:33], v[24:25], v[24:25]
	v_pk_mul_f32 v[8:9], v[28:29], v[28:29]
	v_pk_mul_f32 v[10:11], v[26:27], v[26:27]
	v_add_f32_e32 v0, v0, v8
	v_add_f32_e32 v0, v1, v0
	v_add_f32_e32 v0, v9, v0
	v_add_f32_e32 v0, v10, v0
	v_add_f32_e32 v0, v32, v0
	v_or_b32_e32 v8, 7, v52
	v_add_f32_e32 v0, v11, v0
	v_mad_i64_i32 v[10:11], s[0:1], v8, s23, v[54:55]
	v_ashrrev_i32_e32 v9, 31, v8
	v_lshl_add_u64 v[10:11], v[10:11], 0, s[10:11]
	v_lshl_add_u64 v[10:11], v[10:11], 0, v[184:185]
	v_lshlrev_b64 v[8:9], 11, v[8:9]
	v_add_f32_e32 v0, v33, v0
	v_lshl_add_u64 v[32:33], v[50:51], 0, v[8:9]
	v_add_co_u32_e32 v8, vcc, s22, v10
	v_add_f32_dpp v0, v0, v0 quad_perm:[1,0,3,2] row_mask:0xf bank_mask:0xf bound_ctrl:1
	s_nop 0
	v_addc_co_u32_e32 v9, vcc, 0, v11, vcc
	global_load_dwordx4 v[8:11], v[8:9], off offset:2368
	v_add_f32_dpp v0, v0, v0 quad_perm:[2,3,0,1] row_mask:0xf bank_mask:0xf bound_ctrl:1
	s_mov_b32 s1, s17
	v_writelane_b32 v247, s0, 47
	v_add_f32_dpp v0, v0, v0 row_half_mirror row_mask:0xf bank_mask:0xf bound_ctrl:1
	s_waitcnt vmcnt(0)
; #define DPPF(v, ctrl) __builtin_bit_cast(float, __builtin_amdgcn_update_dpp(0, __builtin_bit_cast(int, (v)), (ctrl), 0xf, 0xf, true))
; DI float sum8(float v) { v += DPPF(v, 0xB1); v += DPPF(v, 0x4E); v += DPPF(v, 0x141); return v; }
; DI unsigned pack2(float a, float b) { return (unsigned)f2bf(a) | ((unsigned)f2bf(b) << 16); }
; DI float bflo(unsigned w) { return __uint_as_float(w << 16); }
; DI float bfhi(unsigned w) { return __uint_as_float(w & 0xffff0000u); }
; DI float sigmoidf_(float x) { return __builtin_amdgcn_rcpf(1.0f + __expf(-x)); }
; DI void gla3_phase(const P& p, int l, const bf16_t* PROJ, const float* US, bf16_t* OGLA, char* smem, int bid, int nb) {
;     ...
;   for (int it = bid; it < 1024; it += nb) {
;     ...
;       for (int i = 0; i < 8; ++i) {
;         float ss = 0.f;
; #pragma unroll
;         for (int j = 0; j < 8; ++j) ss += o[i][j] * o[i][j];
;         ss = sum8(ss); ss += DPPF(ss, 0x140);
;         { const unsigned w = __builtin_bit_cast(unsigned, ss); auto pr = __builtin_amdgcn_permlane16_swap(w, w, false, false);
;           ss = __builtin_bit_cast(float, (unsigned)pr[0]) + __builtin_bit_cast(float, (unsigned)pr[1]); }
;         const float rstd = __builtin_amdgcn_rsqf(ss * (1.0f / 256.f) + 1e-5f);
;         const int t = c * 64 + ty * 8 + i;
;         const uint4 rw = *(const uint4*)(PROJ + (size_t)t * NP + C_GR + h * 256 + tx * 8);
;         const float rr[8] = {bflo(rw.x), bfhi(rw.x), bflo(rw.y), bfhi(rw.y), bflo(rw.z), bfhi(rw.z), bflo(rw.w), bfhi(rw.w)};
;         float y[8];
; #pragma unroll
;         for (int j = 0; j < 8; ++j) y[j] = o[i][j] * rstd * gn[j] * rr[j] * sigmoidf_(rr[j]);
;         uint4 w; w.x = pack2(y[0], y[1]); w.y = pack2(y[2], y[3]); w.z = pack2(y[4], y[5]); w.w = pack2(y[6], y[7]);
;         *(uint4*)(OGLA + (size_t)t * 1024 + h * 256 + tx * 8) = w;
	v_lshlrev_b32_e32 v34, 16, v8
	v_add_f32_dpp v0, v0, v0 row_mirror row_mask:0xf bank_mask:0xf bound_ctrl:1
	v_mov_b32_e32 v1, v0
	s_nop 1
	v_permlane16_swap_b32_e32 v0, v1
	v_add_f32_e32 v0, v0, v1
	v_mul_f32_e32 v1, 0xbfb8aa3b, v34
	v_exp_f32_e32 v1, v1
	v_and_b32_e32 v8, 0xffff0000, v8
	v_fmamk_f32 v0, v0, 0x3b800000, v218
	v_rsq_f32_e32 v0, v0
	v_add_f32_e32 v1, 1.0, v1
	v_rcp_f32_e32 v36, v1
	v_mul_f32_e32 v1, 0xbfb8aa3b, v8
	v_exp_f32_e32 v1, v1
	v_lshlrev_b32_e32 v35, 16, v9
	v_and_b32_e32 v9, 0xffff0000, v9
	v_writelane_b32 v247, s1, 48
	v_add_f32_e32 v1, 1.0, v1
	v_rcp_f32_e32 v38, v1
	v_pk_mul_f32 v[30:31], v[30:31], v[0:1] op_sel_hi:[1,0]
	v_mul_f32_e32 v1, 0xbfb8aa3b, v35
	v_exp_f32_e32 v1, v1
	v_pk_mul_f32 v[30:31], v[48:49], v[30:31]
	v_readlane_b32 s0, v249, 43
	v_pk_mul_f32 v[30:31], v[30:31], v[34:35]
	v_add_f32_e32 v1, 1.0, v1
	v_rcp_f32_e32 v37, v1
	v_pk_mul_f32 v[28:29], v[28:29], v[0:1] op_sel_hi:[1,0]
	v_mul_f32_e32 v1, 0xbfb8aa3b, v9
	v_exp_f32_e32 v1, v1
	v_pk_mul_f32 v[6:7], v[6:7], v[28:29]
	v_pk_mul_f32 v[30:31], v[36:37], v[30:31]
	v_pk_mul_f32 v[6:7], v[6:7], v[8:9]
	v_add_f32_e32 v1, 1.0, v1
	v_rcp_f32_e32 v39, v1
	v_and_b32_sdwa v8, v30, v217 dst_sel:DWORD dst_unused:UNUSED_PAD src0_sel:WORD_1 src1_sel:DWORD
	v_and_b32_sdwa v1, v31, v217 dst_sel:DWORD dst_unused:UNUSED_PAD src0_sel:WORD_1 src1_sel:DWORD
	v_add3_u32 v8, v30, v8, s12
	v_pk_mul_f32 v[6:7], v[38:39], v[6:7]
	v_add3_u32 v1, v31, v1, s12
	v_and_b32_sdwa v28, v6, v217 dst_sel:DWORD dst_unused:UNUSED_PAD src0_sel:WORD_1 src1_sel:DWORD
	v_and_b32_sdwa v9, v7, v217 dst_sel:DWORD dst_unused:UNUSED_PAD src0_sel:WORD_1 src1_sel:DWORD
	v_add3_u32 v6, v6, v28, s12
	v_add3_u32 v7, v7, v9, s12
	v_and_b32_e32 v6, 0xffff0000, v6
	v_and_b32_e32 v7, 0xffff0000, v7
	v_or_b32_sdwa v6, v6, v8 dst_sel:DWORD dst_unused:UNUSED_PAD src0_sel:DWORD src1_sel:WORD_1
	v_lshlrev_b32_e32 v8, 16, v10
	v_or_b32_sdwa v7, v7, v1 dst_sel:DWORD dst_unused:UNUSED_PAD src0_sel:DWORD src1_sel:WORD_1
	v_mul_f32_e32 v1, 0xbfb8aa3b, v8
	v_exp_f32_e32 v1, v1
	v_and_b32_e32 v10, 0xffff0000, v10
	v_lshlrev_b32_e32 v9, 16, v11
	v_and_b32_e32 v11, 0xffff0000, v11
	v_add_f32_e32 v1, 1.0, v1
	v_rcp_f32_e32 v28, v1
	v_mul_f32_e32 v1, 0xbfb8aa3b, v10
	v_exp_f32_e32 v1, v1
	s_add_i32 s9, s9, s0
	s_add_i32 s8, s8, s0
	s_cmpk_gt_i32 s9, 0x3ff
	v_add_f32_e32 v1, 1.0, v1
	v_rcp_f32_e32 v30, v1
	v_pk_mul_f32 v[26:27], v[26:27], v[0:1] op_sel_hi:[1,0]
	v_mul_f32_e32 v1, 0xbfb8aa3b, v9
	v_exp_f32_e32 v1, v1
	v_pk_mul_f32 v[4:5], v[4:5], v[26:27]
	v_readlane_b32 s1, v249, 44
	v_pk_mul_f32 v[4:5], v[4:5], v[8:9]
	v_add_f32_e32 v1, 1.0, v1
	v_rcp_f32_e32 v29, v1
	v_pk_mul_f32 v[0:1], v[24:25], v[0:1] op_sel_hi:[1,0]
	v_pk_mul_f32 v[4:5], v[4:5], v[28:29]
	v_pk_mul_f32 v[0:1], v[2:3], v[0:1]
	v_mul_f32_e32 v2, 0xbfb8aa3b, v11
	v_exp_f32_e32 v2, v2
	v_pk_mul_f32 v[0:1], v[0:1], v[10:11]
	v_and_b32_sdwa v3, v4, v217 dst_sel:DWORD dst_unused:UNUSED_PAD src0_sel:WORD_1 src1_sel:DWORD
	v_add3_u32 v3, v4, v3, s12
	v_add_f32_e32 v2, 1.0, v2
	v_rcp_f32_e32 v31, v2
	v_and_b32_sdwa v2, v5, v217 dst_sel:DWORD dst_unused:UNUSED_PAD src0_sel:WORD_1 src1_sel:DWORD
	v_add3_u32 v2, v5, v2, s12
	v_pk_mul_f32 v[0:1], v[0:1], v[30:31]
	s_nop 0
	v_and_b32_sdwa v4, v1, v217 dst_sel:DWORD dst_unused:UNUSED_PAD src0_sel:WORD_1 src1_sel:DWORD
	v_and_b32_sdwa v5, v0, v217 dst_sel:DWORD dst_unused:UNUSED_PAD src0_sel:WORD_1 src1_sel:DWORD
	v_add3_u32 v1, v1, v4, s12
	v_add3_u32 v0, v0, v5, s12
	v_and_b32_e32 v1, 0xffff0000, v1
	v_and_b32_e32 v0, 0xffff0000, v0
	v_or_b32_sdwa v9, v1, v2 dst_sel:DWORD dst_unused:UNUSED_PAD src0_sel:DWORD src1_sel:WORD_1
	v_or_b32_sdwa v8, v0, v3 dst_sel:DWORD dst_unused:UNUSED_PAD src0_sel:DWORD src1_sel:WORD_1
	global_store_dwordx4 v[32:33], v[6:9], off
	s_cbranch_scc0 .LBB0_1318

; #define MFMA16(a, b, c) __builtin_amdgcn_mfma_f32_16x16x32_bf16((a), (b), (c), 0, 0, 0)
; DI void score_phase(const bf16_t* PROJ, unsigned short* SC, int c, char* smem, int bid, int nb) {
;     ...
;     for (int h = 0; h < 16; ++h) {
;       const bf16x8 qa0 = *(const bf16x8*)(rowp0 + C_IQ + h * 64 + fq * 8), qa1 = *(const bf16x8*)(rowp0 + C_IQ + h * 64 + 32 + fq * 8);
;       const bf16x8 qb0f = *(const bf16x8*)(rowp1 + C_IQ + h * 64 + fq * 8), qb1f = *(const bf16x8*)(rowp1 + C_IQ + h * 64 + 32 + fq * 8);
;       const float w0 = sW[fr * 17 + h], w1 = sW[(16 + fr) * 17 + h];
; #pragma unroll
;       for (int nj = 0; nj < 8; ++nj) {
;         f32x4 d = MFMA16(kf[nj][0], qa0, ((f32x4){0.f, 0.f, 0.f, 0.f}));
;         d = MFMA16(kf[nj][1], qa1, d);
;         f32x4 e = MFMA16(kf[nj][0], qb0f, ((f32x4){0.f, 0.f, 0.f, 0.f}));
;         e = MFMA16(kf[nj][1], qb1f, e);
; #pragma unroll
;         for (int r = 0; r < 4; ++r) { sc[0][nj][r] += w0 * fmaxf(d[r], 0.f); sc[1][nj][r] += w1 * fmaxf(e[r], 0.f); }
;       }
;     }
.LBB0_1343:
	v_lshl_add_u64 v[72:73], v[136:137], 0, s[6:7]
	v_add_co_u32_e32 v68, vcc, s2, v72
	s_add_u32 s6, s6, 0x80
	s_nop 0
	v_addc_co_u32_e32 v69, vcc, 0, v73, vcc
	v_add_co_u32_e32 v76, vcc, s3, v72
	global_load_dwordx4 v[64:67], v[68:69], off offset:128
	s_nop 0
	global_load_dwordx4 v[68:71], v[68:69], off offset:192
	v_addc_co_u32_e32 v77, vcc, 0, v73, vcc
	global_load_dwordx4 v[72:75], v[76:77], off offset:128
	s_nop 0
	global_load_dwordx4 v[76:79], v[76:77], off offset:192
	ds_read_b32 v152, v158
	ds_read_b32 v150, v158 offset:1088
	s_addc_u32 s7, s7, 0
	v_add_u32_e32 v158, 4, v158
	s_cmpk_eq_i32 s6, 0x800
	s_waitcnt vmcnt(3)
	v_mfma_f32_16x16x32_bf16 v[160:163], v[0:3], v[64:67], 0
	s_waitcnt vmcnt(1)
	v_mfma_f32_16x16x32_bf16 v[164:167], v[0:3], v[72:75], 0
	v_mfma_f32_16x16x32_bf16 v[160:163], v[4:7], v[68:71], v[160:163]
	s_waitcnt vmcnt(0)
	v_mfma_f32_16x16x32_bf16 v[164:167], v[4:7], v[76:79], v[164:167]
	s_nop 5
	v_max_f32_e32 v160, 0, v160
	s_nop 0
	v_max_f32_e32 v164, 0, v164
	v_max_f32_e32 v161, 0, v161
	v_max_f32_e32 v165, 0, v165
	s_waitcnt lgkmcnt(1)
	v_pk_fma_f32 v[146:147], v[152:153], v[160:161], v[146:147] op_sel_hi:[0,1,1]
	v_max_f32_e32 v160, 0, v162
	v_max_f32_e32 v162, 0, v166
	v_max_f32_e32 v161, 0, v163
	v_max_f32_e32 v163, 0, v167
	v_pk_fma_f32 v[148:149], v[152:153], v[160:161], v[148:149] op_sel_hi:[0,1,1]
	s_waitcnt lgkmcnt(0)
	v_pk_fma_f32 v[114:115], v[150:151], v[162:163], v[114:115] op_sel_hi:[0,1,1]
	v_mfma_f32_16x16x32_bf16 v[160:163], v[8:11], v[64:67], 0
	v_fma_f32 v112, v150, v164, v112
	v_fma_f32 v113, v150, v165, v113
	v_mfma_f32_16x16x32_bf16 v[164:167], v[8:11], v[72:75], 0
	v_mfma_f32_16x16x32_bf16 v[160:163], v[12:15], v[68:71], v[160:163]
	v_mfma_f32_16x16x32_bf16 v[164:167], v[12:15], v[76:79], v[164:167]
	s_nop 6
	v_max_f32_e32 v160, 0, v160
	v_max_f32_e32 v164, 0, v164
	v_max_f32_e32 v161, 0, v161
	v_max_f32_e32 v165, 0, v165
	v_pk_fma_f32 v[142:143], v[152:153], v[160:161], v[142:143] op_sel_hi:[0,1,1]
	v_max_f32_e32 v160, 0, v162
	v_max_f32_e32 v162, 0, v166
	v_max_f32_e32 v161, 0, v163
	v_max_f32_e32 v163, 0, v167
	v_pk_fma_f32 v[144:145], v[152:153], v[160:161], v[144:145] op_sel_hi:[0,1,1]
	v_pk_fma_f32 v[110:111], v[150:151], v[162:163], v[110:111] op_sel_hi:[0,1,1]
	v_mfma_f32_16x16x32_bf16 v[160:163], v[16:19], v[64:67], 0
	v_fma_f32 v108, v150, v164, v108
	v_fma_f32 v109, v150, v165, v109
	v_mfma_f32_16x16x32_bf16 v[164:167], v[16:19], v[72:75], 0
	v_mfma_f32_16x16x32_bf16 v[160:163], v[20:23], v[68:71], v[160:163]
	v_mfma_f32_16x16x32_bf16 v[164:167], v[20:23], v[76:79], v[164:167]
	s_nop 6
	v_max_f32_e32 v160, 0, v160
	v_max_f32_e32 v164, 0, v164
	v_max_f32_e32 v161, 0, v161
	v_max_f32_e32 v165, 0, v165
	v_pk_fma_f32 v[138:139], v[152:153], v[160:161], v[138:139] op_sel_hi:[0,1,1]
	v_max_f32_e32 v160, 0, v162
	v_max_f32_e32 v162, 0, v166
	v_max_f32_e32 v161, 0, v163
	v_max_f32_e32 v163, 0, v167
	v_pk_fma_f32 v[140:141], v[152:153], v[160:161], v[140:141] op_sel_hi:[0,1,1]
	v_pk_fma_f32 v[106:107], v[150:151], v[162:163], v[106:107] op_sel_hi:[0,1,1]
	v_mfma_f32_16x16x32_bf16 v[160:163], v[24:27], v[64:67], 0
	v_fma_f32 v104, v150, v164, v104
	v_fma_f32 v105, v150, v165, v105
	v_mfma_f32_16x16x32_bf16 v[164:167], v[24:27], v[72:75], 0
	v_mfma_f32_16x16x32_bf16 v[160:163], v[28:31], v[68:71], v[160:163]
	v_mfma_f32_16x16x32_bf16 v[164:167], v[28:31], v[76:79], v[164:167]
	s_nop 6
	v_max_f32_e32 v160, 0, v160
	v_max_f32_e32 v164, 0, v164
	v_max_f32_e32 v161, 0, v161
	v_max_f32_e32 v165, 0, v165
	v_pk_fma_f32 v[132:133], v[152:153], v[160:161], v[132:133] op_sel_hi:[0,1,1]
	v_max_f32_e32 v160, 0, v162
	v_max_f32_e32 v162, 0, v166
	v_max_f32_e32 v161, 0, v163
	v_max_f32_e32 v163, 0, v167
	v_pk_fma_f32 v[134:135], v[152:153], v[160:161], v[134:135] op_sel_hi:[0,1,1]
	v_pk_fma_f32 v[102:103], v[150:151], v[162:163], v[102:103] op_sel_hi:[0,1,1]
	v_mfma_f32_16x16x32_bf16 v[160:163], v[32:35], v[64:67], 0
	v_fma_f32 v100, v150, v164, v100
	v_fma_f32 v101, v150, v165, v101
	v_mfma_f32_16x16x32_bf16 v[164:167], v[32:35], v[72:75], 0
	v_mfma_f32_16x16x32_bf16 v[160:163], v[36:39], v[68:71], v[160:163]
	v_mfma_f32_16x16x32_bf16 v[164:167], v[36:39], v[76:79], v[164:167]
	s_nop 6
	v_max_f32_e32 v160, 0, v160
	v_max_f32_e32 v164, 0, v164
	v_max_f32_e32 v161, 0, v161
	v_max_f32_e32 v165, 0, v165
	v_pk_fma_f32 v[128:129], v[152:153], v[160:161], v[128:129] op_sel_hi:[0,1,1]
	v_max_f32_e32 v160, 0, v162
	v_max_f32_e32 v162, 0, v166
	v_max_f32_e32 v161, 0, v163
	v_max_f32_e32 v163, 0, v167
	v_pk_fma_f32 v[130:131], v[152:153], v[160:161], v[130:131] op_sel_hi:[0,1,1]
	v_pk_fma_f32 v[98:99], v[150:151], v[162:163], v[98:99] op_sel_hi:[0,1,1]
	v_mfma_f32_16x16x32_bf16 v[160:163], v[40:43], v[64:67], 0
	v_fma_f32 v96, v150, v164, v96
	v_fma_f32 v97, v150, v165, v97
	v_mfma_f32_16x16x32_bf16 v[164:167], v[40:43], v[72:75], 0
	v_mfma_f32_16x16x32_bf16 v[160:163], v[44:47], v[68:71], v[160:163]
	v_mfma_f32_16x16x32_bf16 v[164:167], v[44:47], v[76:79], v[164:167]
	s_nop 6
	v_max_f32_e32 v160, 0, v160
	v_max_f32_e32 v164, 0, v164
	v_max_f32_e32 v161, 0, v161
	v_max_f32_e32 v165, 0, v165
	v_pk_fma_f32 v[124:125], v[152:153], v[160:161], v[124:125] op_sel_hi:[0,1,1]
	v_max_f32_e32 v160, 0, v162
	v_max_f32_e32 v162, 0, v166
	v_max_f32_e32 v161, 0, v163
	v_max_f32_e32 v163, 0, v167
	v_pk_fma_f32 v[126:127], v[152:153], v[160:161], v[126:127] op_sel_hi:[0,1,1]
	v_pk_fma_f32 v[94:95], v[150:151], v[162:163], v[94:95] op_sel_hi:[0,1,1]
	v_mfma_f32_16x16x32_bf16 v[160:163], v[48:51], v[64:67], 0
	v_fma_f32 v92, v150, v164, v92
	v_fma_f32 v93, v150, v165, v93
	v_mfma_f32_16x16x32_bf16 v[64:67], v[56:59], v[64:67], 0
; #define MFMA16(a, b, c) __builtin_amdgcn_mfma_f32_16x16x32_bf16((a), (b), (c), 0, 0, 0)
; DI void score_phase(const bf16_t* PROJ, unsigned short* SC, int c, char* smem, int bid, int nb) {
;     ...
;       for (int nj = 0; nj < 8; ++nj) {
;         f32x4 d = MFMA16(kf[nj][0], qa0, ((f32x4){0.f, 0.f, 0.f, 0.f}));
;         d = MFMA16(kf[nj][1], qa1, d);
;         f32x4 e = MFMA16(kf[nj][0], qb0f, ((f32x4){0.f, 0.f, 0.f, 0.f}));
;         e = MFMA16(kf[nj][1], qb1f, e);
; #pragma unroll
;         for (int r = 0; r < 4; ++r) { sc[0][nj][r] += w0 * fmaxf(d[r], 0.f); sc[1][nj][r] += w1 * fmaxf(e[r], 0.f); }
;       }
;     }
; #pragma unroll
;     for (int mi = 0; mi < 2; ++mi) {
;       const int t = q0 + mi * 16 + fr;
;       unsigned short* op = SC + (size_t)(t - c * 4096) * S + s0 + fq * 4;
; #pragma unroll
;       for (int nj = 0; nj < 8; ++nj) {
;         unsigned w0 = __builtin_bit_cast(unsigned, __builtin_amdgcn_cvt_pkrtz(sc[mi][nj][0], sc[mi][nj][1]));
;         unsigned w1 = __builtin_bit_cast(unsigned, __builtin_amdgcn_cvt_pkrtz(sc[mi][nj][2], sc[mi][nj][3]));
;         const unsigned m0 = ((w0 >> 15) & 0x00010001u) * 0xffffu, m1 = ((w1 >> 15) & 0x00010001u) * 0xffffu;
;         w0 ^= (m0 | 0x80008000u); w1 ^= (m1 | 0x80008000u);
;         uint2 st2; st2.x = w0; st2.y = w1;
;         *(uint2*)(op + nj * 16) = st2;
;       }
	v_mfma_f32_16x16x32_bf16 v[164:167], v[48:51], v[72:75], 0
	v_mfma_f32_16x16x32_bf16 v[160:163], v[52:55], v[68:71], v[160:163]
	v_mfma_f32_16x16x32_bf16 v[64:67], v[60:63], v[68:71], v[64:67]
	v_mfma_f32_16x16x32_bf16 v[68:71], v[56:59], v[72:75], 0
	s_nop 5
	v_max_f32_e32 v160, 0, v160
	v_mfma_f32_16x16x32_bf16 v[164:167], v[52:55], v[76:79], v[164:167]
	v_max_f32_e32 v64, 0, v64
	v_max_f32_e32 v65, 0, v65
	v_mfma_f32_16x16x32_bf16 v[68:71], v[60:63], v[76:79], v[68:71]
	v_fma_f32 v116, v152, v64, v116
	v_fma_f32 v117, v152, v65, v117
	s_nop 1
	s_nop 0
	v_max_f32_e32 v164, 0, v164
	v_max_f32_e32 v161, 0, v161
	v_max_f32_e32 v165, 0, v165
	v_pk_fma_f32 v[120:121], v[152:153], v[160:161], v[120:121] op_sel_hi:[0,1,1]
	v_max_f32_e32 v160, 0, v162
	v_max_f32_e32 v69, 0, v69
	v_max_f32_e32 v64, v66, v66
	v_max_f32_e32 v66, 0, v70
	v_max_f32_e32 v162, 0, v166
	v_max_f32_e32 v64, 0, v64
	v_max_f32_e32 v65, 0, v67
	v_max_f32_e32 v161, 0, v163
	v_max_f32_e32 v159, v167, v167
	v_pk_fma_f32 v[118:119], v[152:153], v[64:65], v[118:119] op_sel_hi:[0,1,1]
	v_max_f32_e32 v64, v71, v71
	v_max_f32_e32 v163, 0, v159
	v_max_f32_e32 v68, 0, v68
	v_max_f32_e32 v67, 0, v64
	v_pk_fma_f32 v[88:89], v[150:151], v[164:165], v[88:89] op_sel_hi:[0,1,1]
	v_pk_fma_f32 v[122:123], v[152:153], v[160:161], v[122:123] op_sel_hi:[0,1,1]
	v_pk_fma_f32 v[90:91], v[150:151], v[162:163], v[90:91] op_sel_hi:[0,1,1]
	v_pk_fma_f32 v[84:85], v[150:151], v[68:69], v[84:85] op_sel_hi:[0,1,1]
	v_pk_fma_f32 v[86:87], v[150:151], v[66:67], v[86:87] op_sel_hi:[0,1,1]
	s_cbranch_scc0 .LBB0_1343
	v_add_u32_e32 v0, v157, v155
	v_ashrrev_i32_e32 v1, 31, v0
	v_lshlrev_b64 v[4:5], 15, v[0:1]
	v_cvt_pkrtz_f16_f32 v1, v146, v147
	v_cvt_pkrtz_f16_f32 v6, v148, v149
	v_lshrrev_b32_e32 v7, 15, v6
	v_lshrrev_b32_e32 v8, 15, v1
	v_and_b32_e32 v7, 0x10001, v7
	v_and_b32_e32 v8, 0x10001, v8
	s_ashr_i32 s5, s4, 31
	v_mul_u32_u24_e32 v8, 0xffff, v8
	v_mul_u32_u24_e32 v7, 0xffff, v7
	v_lshl_add_u64 v[2:3], s[4:5], 1, v[80:81]
	v_or_b32_e32 v7, 0x80008000, v7
	v_or_b32_e32 v8, 0x80008000, v8
	v_lshl_add_u64 v[4:5], v[2:3], 0, v[4:5]
	v_xor_b32_e32 v7, v7, v6
	v_xor_b32_e32 v6, v8, v1
	global_store_dwordx2 v[4:5], v[6:7], off
	v_cvt_pkrtz_f16_f32 v1, v142, v143
	v_cvt_pkrtz_f16_f32 v6, v144, v145
	v_lshrrev_b32_e32 v7, 15, v6
	v_lshrrev_b32_e32 v8, 15, v1
	v_and_b32_e32 v7, 0x10001, v7
	v_and_b32_e32 v8, 0x10001, v8
	v_mul_u32_u24_e32 v8, 0xffff, v8
	v_mul_u32_u24_e32 v7, 0xffff, v7
	v_or_b32_e32 v7, 0x80008000, v7
	v_or_b32_e32 v8, 0x80008000, v8
	v_xor_b32_e32 v7, v7, v6
	v_xor_b32_e32 v6, v8, v1
	global_store_dwordx2 v[4:5], v[6:7], off offset:32
	v_cvt_pkrtz_f16_f32 v1, v138, v139
	v_cvt_pkrtz_f16_f32 v6, v140, v141
	v_lshrrev_b32_e32 v7, 15, v6
	v_lshrrev_b32_e32 v8, 15, v1
	v_and_b32_e32 v7, 0x10001, v7
	v_and_b32_e32 v8, 0x10001, v8
	v_mul_u32_u24_e32 v8, 0xffff, v8
	v_mul_u32_u24_e32 v7, 0xffff, v7
	v_or_b32_e32 v7, 0x80008000, v7
	v_or_b32_e32 v8, 0x80008000, v8
	v_xor_b32_e32 v7, v7, v6
	v_xor_b32_e32 v6, v8, v1
	global_store_dwordx2 v[4:5], v[6:7], off offset:64
	v_cvt_pkrtz_f16_f32 v1, v132, v133
	v_cvt_pkrtz_f16_f32 v6, v134, v135
	v_lshrrev_b32_e32 v7, 15, v6
	v_lshrrev_b32_e32 v8, 15, v1
	v_and_b32_e32 v7, 0x10001, v7
	v_and_b32_e32 v8, 0x10001, v8
	v_mul_u32_u24_e32 v8, 0xffff, v8
	v_mul_u32_u24_e32 v7, 0xffff, v7
	v_or_b32_e32 v7, 0x80008000, v7
	v_or_b32_e32 v8, 0x80008000, v8
	v_xor_b32_e32 v7, v7, v6
	v_xor_b32_e32 v6, v8, v1
	global_store_dwordx2 v[4:5], v[6:7], off offset:96
	v_cvt_pkrtz_f16_f32 v1, v128, v129
	v_cvt_pkrtz_f16_f32 v6, v130, v131
	v_lshrrev_b32_e32 v7, 15, v6
	v_lshrrev_b32_e32 v8, 15, v1
	v_and_b32_e32 v7, 0x10001, v7
	v_and_b32_e32 v8, 0x10001, v8
	v_mul_u32_u24_e32 v8, 0xffff, v8
	v_mul_u32_u24_e32 v7, 0xffff, v7
	v_or_b32_e32 v7, 0x80008000, v7
	v_or_b32_e32 v8, 0x80008000, v8
	v_xor_b32_e32 v7, v7, v6
	v_xor_b32_e32 v6, v8, v1
	global_store_dwordx2 v[4:5], v[6:7], off offset:128
	v_cvt_pkrtz_f16_f32 v1, v124, v125
	v_cvt_pkrtz_f16_f32 v6, v126, v127
	v_lshrrev_b32_e32 v7, 15, v6
	v_lshrrev_b32_e32 v8, 15, v1
	v_and_b32_e32 v7, 0x10001, v7
	v_and_b32_e32 v8, 0x10001, v8
	v_mul_u32_u24_e32 v8, 0xffff, v8
	v_mul_u32_u24_e32 v7, 0xffff, v7
	v_or_b32_e32 v7, 0x80008000, v7
	v_or_b32_e32 v8, 0x80008000, v8
	v_xor_b32_e32 v7, v7, v6
	v_xor_b32_e32 v6, v8, v1
	global_store_dwordx2 v[4:5], v[6:7], off offset:160
	v_cvt_pkrtz_f16_f32 v1, v120, v121
	v_cvt_pkrtz_f16_f32 v6, v122, v123
	v_lshrrev_b32_e32 v7, 15, v6
; DI void score_phase(const bf16_t* PROJ, unsigned short* SC, int c, char* smem, int bid, int nb) {
;     ...
; #pragma unroll
;     for (int mi = 0; mi < 2; ++mi) {
;       const int t = q0 + mi * 16 + fr;
;       unsigned short* op = SC + (size_t)(t - c * 4096) * S + s0 + fq * 4;
; #pragma unroll
;       for (int nj = 0; nj < 8; ++nj) {
;         unsigned w0 = __builtin_bit_cast(unsigned, __builtin_amdgcn_cvt_pkrtz(sc[mi][nj][0], sc[mi][nj][1]));
;         unsigned w1 = __builtin_bit_cast(unsigned, __builtin_amdgcn_cvt_pkrtz(sc[mi][nj][2], sc[mi][nj][3]));
;         const unsigned m0 = ((w0 >> 15) & 0x00010001u) * 0xffffu, m1 = ((w1 >> 15) & 0x00010001u) * 0xffffu;
;         w0 ^= (m0 | 0x80008000u); w1 ^= (m1 | 0x80008000u);
;         uint2 st2; st2.x = w0; st2.y = w1;
;         *(uint2*)(op + nj * 16) = st2;
;       }
;     }
;   }
	v_lshrrev_b32_e32 v8, 15, v1
	v_and_b32_e32 v7, 0x10001, v7
	v_and_b32_e32 v8, 0x10001, v8
	v_mul_u32_u24_e32 v8, 0xffff, v8
	v_mul_u32_u24_e32 v7, 0xffff, v7
	v_or_b32_e32 v7, 0x80008000, v7
	v_or_b32_e32 v8, 0x80008000, v8
	v_xor_b32_e32 v7, v7, v6
	v_xor_b32_e32 v6, v8, v1
	global_store_dwordx2 v[4:5], v[6:7], off offset:192
	v_cvt_pkrtz_f16_f32 v1, v116, v117
	v_cvt_pkrtz_f16_f32 v6, v118, v119
	v_lshrrev_b32_e32 v7, 15, v6
	v_lshrrev_b32_e32 v8, 15, v1
	v_and_b32_e32 v7, 0x10001, v7
	v_and_b32_e32 v8, 0x10001, v8
	v_mul_u32_u24_e32 v8, 0xffff, v8
	v_mul_u32_u24_e32 v7, 0xffff, v7
	v_or_b32_e32 v7, 0x80008000, v7
	v_or_b32_e32 v8, 0x80008000, v8
	v_or_b32_e32 v0, 16, v0
	v_xor_b32_e32 v7, v7, v6
	v_xor_b32_e32 v6, v8, v1
	v_ashrrev_i32_e32 v1, 31, v0
	v_lshlrev_b64 v[0:1], 15, v[0:1]
	v_lshl_add_u64 v[0:1], v[2:3], 0, v[0:1]
	v_cvt_pkrtz_f16_f32 v2, v112, v113
	v_cvt_pkrtz_f16_f32 v3, v114, v115
	global_store_dwordx2 v[4:5], v[6:7], off offset:224
	v_lshrrev_b32_e32 v4, 15, v3
	v_lshrrev_b32_e32 v5, 15, v2
	v_and_b32_e32 v4, 0x10001, v4
	v_and_b32_e32 v5, 0x10001, v5
	v_mul_u32_u24_e32 v5, 0xffff, v5
	v_mul_u32_u24_e32 v4, 0xffff, v4
	v_or_b32_e32 v4, 0x80008000, v4
	v_or_b32_e32 v5, 0x80008000, v5
	v_xor_b32_e32 v3, v4, v3
	v_xor_b32_e32 v2, v5, v2
	global_store_dwordx2 v[0:1], v[2:3], off
	v_cvt_pkrtz_f16_f32 v2, v108, v109
	v_cvt_pkrtz_f16_f32 v3, v110, v111
	v_lshrrev_b32_e32 v4, 15, v3
	v_lshrrev_b32_e32 v5, 15, v2
	v_and_b32_e32 v4, 0x10001, v4
	v_and_b32_e32 v5, 0x10001, v5
	v_mul_u32_u24_e32 v5, 0xffff, v5
	v_mul_u32_u24_e32 v4, 0xffff, v4
	v_or_b32_e32 v4, 0x80008000, v4
	v_or_b32_e32 v5, 0x80008000, v5
	v_xor_b32_e32 v3, v4, v3
	v_xor_b32_e32 v2, v5, v2
	global_store_dwordx2 v[0:1], v[2:3], off offset:32
	v_cvt_pkrtz_f16_f32 v2, v104, v105
	v_cvt_pkrtz_f16_f32 v3, v106, v107
	v_lshrrev_b32_e32 v4, 15, v3
	v_lshrrev_b32_e32 v5, 15, v2
	v_and_b32_e32 v4, 0x10001, v4
	v_and_b32_e32 v5, 0x10001, v5
	v_mul_u32_u24_e32 v5, 0xffff, v5
	v_mul_u32_u24_e32 v4, 0xffff, v4
	v_or_b32_e32 v4, 0x80008000, v4
	v_or_b32_e32 v5, 0x80008000, v5
	v_xor_b32_e32 v3, v4, v3
	v_xor_b32_e32 v2, v5, v2
	global_store_dwordx2 v[0:1], v[2:3], off offset:64
	v_cvt_pkrtz_f16_f32 v2, v100, v101
	v_cvt_pkrtz_f16_f32 v3, v102, v103
	v_lshrrev_b32_e32 v4, 15, v3
	v_lshrrev_b32_e32 v5, 15, v2
	v_and_b32_e32 v4, 0x10001, v4
	v_and_b32_e32 v5, 0x10001, v5
	v_mul_u32_u24_e32 v5, 0xffff, v5
	v_mul_u32_u24_e32 v4, 0xffff, v4
	v_or_b32_e32 v4, 0x80008000, v4
	v_or_b32_e32 v5, 0x80008000, v5
	v_xor_b32_e32 v3, v4, v3
	v_xor_b32_e32 v2, v5, v2
	global_store_dwordx2 v[0:1], v[2:3], off offset:96
	v_cvt_pkrtz_f16_f32 v2, v96, v97
	v_cvt_pkrtz_f16_f32 v3, v98, v99
	v_lshrrev_b32_e32 v4, 15, v3
	v_lshrrev_b32_e32 v5, 15, v2
	v_and_b32_e32 v4, 0x10001, v4
	v_and_b32_e32 v5, 0x10001, v5
	v_mul_u32_u24_e32 v5, 0xffff, v5
	v_mul_u32_u24_e32 v4, 0xffff, v4
	v_or_b32_e32 v4, 0x80008000, v4
	v_or_b32_e32 v5, 0x80008000, v5
	v_xor_b32_e32 v3, v4, v3
	v_xor_b32_e32 v2, v5, v2
	global_store_dwordx2 v[0:1], v[2:3], off offset:128
	v_cvt_pkrtz_f16_f32 v2, v92, v93
	v_cvt_pkrtz_f16_f32 v3, v94, v95
	v_lshrrev_b32_e32 v4, 15, v3
	v_lshrrev_b32_e32 v5, 15, v2
	v_and_b32_e32 v4, 0x10001, v4
	v_and_b32_e32 v5, 0x10001, v5
	v_mul_u32_u24_e32 v5, 0xffff, v5
	v_mul_u32_u24_e32 v4, 0xffff, v4
	v_or_b32_e32 v4, 0x80008000, v4
	v_or_b32_e32 v5, 0x80008000, v5
	v_xor_b32_e32 v3, v4, v3
	v_xor_b32_e32 v2, v5, v2
	global_store_dwordx2 v[0:1], v[2:3], off offset:160
	v_cvt_pkrtz_f16_f32 v2, v88, v89
	v_cvt_pkrtz_f16_f32 v3, v90, v91
	v_lshrrev_b32_e32 v4, 15, v3
	v_lshrrev_b32_e32 v5, 15, v2
	v_and_b32_e32 v4, 0x10001, v4
	v_and_b32_e32 v5, 0x10001, v5
	v_mul_u32_u24_e32 v5, 0xffff, v5
	v_mul_u32_u24_e32 v4, 0xffff, v4
	v_or_b32_e32 v4, 0x80008000, v4
	v_or_b32_e32 v5, 0x80008000, v5
	v_xor_b32_e32 v3, v4, v3
	v_xor_b32_e32 v2, v5, v2
	global_store_dwordx2 v[0:1], v[2:3], off offset:192
	v_cvt_pkrtz_f16_f32 v2, v84, v85
	v_cvt_pkrtz_f16_f32 v3, v86, v87
	v_lshrrev_b32_e32 v4, 15, v3
	v_lshrrev_b32_e32 v5, 15, v2
	v_and_b32_e32 v4, 0x10001, v4
	v_and_b32_e32 v5, 0x10001, v5
	v_mul_u32_u24_e32 v5, 0xffff, v5
	v_mul_u32_u24_e32 v4, 0xffff, v4
	v_readlane_b32 s2, v249, 43
	v_or_b32_e32 v4, 0x80008000, v4
	v_or_b32_e32 v5, 0x80008000, v5
	s_add_i32 s8, s8, s2
	v_xor_b32_e32 v3, v4, v3
	v_xor_b32_e32 v2, v5, v2
	s_cmpk_gt_i32 s8, 0x60f
	v_readlane_b32 s3, v249, 44
	global_store_dwordx2 v[0:1], v[2:3], off offset:224
	s_cbranch_scc0 .LBB0_1336

; #define MFMA16(a, b, c) __builtin_amdgcn_mfma_f32_16x16x32_bf16((a), (b), (c), 0, 0, 0)
; DI void score_phase(const bf16_t* PROJ, unsigned short* SC, int c, char* smem, int bid, int nb) {
;     ...
;     for (int h = 0; h < 16; ++h) {
;       const bf16x8 qa0 = *(const bf16x8*)(rowp0 + C_IQ + h * 64 + fq * 8), qa1 = *(const bf16x8*)(rowp0 + C_IQ + h * 64 + 32 + fq * 8);
;       const bf16x8 qb0f = *(const bf16x8*)(rowp1 + C_IQ + h * 64 + fq * 8), qb1f = *(const bf16x8*)(rowp1 + C_IQ + h * 64 + 32 + fq * 8);
;       const float w0 = sW[fr * 17 + h], w1 = sW[(16 + fr) * 17 + h];
; #pragma unroll
;       for (int nj = 0; nj < 8; ++nj) {
;         f32x4 d = MFMA16(kf[nj][0], qa0, ((f32x4){0.f, 0.f, 0.f, 0.f}));
;         d = MFMA16(kf[nj][1], qa1, d);
;         f32x4 e = MFMA16(kf[nj][0], qb0f, ((f32x4){0.f, 0.f, 0.f, 0.f}));
;         e = MFMA16(kf[nj][1], qb1f, e);
; #pragma unroll
;         for (int r = 0; r < 4; ++r) { sc[0][nj][r] += w0 * fmaxf(d[r], 0.f); sc[1][nj][r] += w1 * fmaxf(e[r], 0.f); }
;       }
;     }
.LBB0_1574:
	v_lshl_add_u64 v[72:73], v[138:139], 0, s[6:7]
	v_add_co_u32_e32 v68, vcc, s2, v72
	s_add_u32 s6, s6, 0x80
	s_nop 0
	v_addc_co_u32_e32 v69, vcc, 0, v73, vcc
	global_load_dwordx4 v[64:67], v[68:69], off offset:128
	s_nop 0
	global_load_dwordx4 v[68:71], v[68:69], off offset:192
	v_add_co_u32_e32 v76, vcc, s3, v72
	s_addc_u32 s7, s7, 0
	s_nop 0
	v_addc_co_u32_e32 v77, vcc, 0, v73, vcc
	global_load_dwordx4 v[72:75], v[76:77], off offset:128
	s_nop 0
	global_load_dwordx4 v[76:79], v[76:77], off offset:192
	ds_read_b32 v154, v157
	ds_read_b32 v152, v157 offset:1088
	v_add_u32_e32 v157, 4, v157
	s_cmpk_eq_i32 s6, 0x800
	s_waitcnt vmcnt(3)
	v_mfma_f32_16x16x32_bf16 v[158:161], v[0:3], v[64:67], 0
	s_waitcnt vmcnt(1)
	v_mfma_f32_16x16x32_bf16 v[162:165], v[0:3], v[72:75], 0
	v_mfma_f32_16x16x32_bf16 v[158:161], v[4:7], v[68:71], v[158:161]
	s_waitcnt vmcnt(0)
	v_mfma_f32_16x16x32_bf16 v[162:165], v[4:7], v[76:79], v[162:165]
	s_nop 5
	v_max_f32_e32 v158, 0, v158
	v_max_f32_e32 v159, 0, v159
	s_waitcnt lgkmcnt(1)
	v_pk_fma_f32 v[148:149], v[154:155], v[158:159], v[148:149] op_sel_hi:[0,1,1]
	v_max_f32_e32 v163, 0, v163
	v_max_f32_e32 v158, v160, v160
	v_max_f32_e32 v160, 0, v164
	v_max_f32_e32 v158, 0, v158
	v_max_f32_e32 v159, 0, v161
	v_pk_fma_f32 v[150:151], v[154:155], v[158:159], v[150:151] op_sel_hi:[0,1,1]
	v_max_f32_e32 v161, 0, v165
	s_waitcnt lgkmcnt(0)
	v_pk_fma_f32 v[116:117], v[152:153], v[160:161], v[116:117] op_sel_hi:[0,1,1]
	v_mfma_f32_16x16x32_bf16 v[158:161], v[8:11], v[64:67], 0
	v_max_f32_e32 v162, 0, v162
	v_pk_fma_f32 v[114:115], v[152:153], v[162:163], v[114:115] op_sel_hi:[0,1,1]
	v_mfma_f32_16x16x32_bf16 v[162:165], v[8:11], v[72:75], 0
	v_mfma_f32_16x16x32_bf16 v[158:161], v[12:15], v[68:71], v[158:161]
	v_mfma_f32_16x16x32_bf16 v[162:165], v[12:15], v[76:79], v[162:165]
	s_nop 6
	v_max_f32_e32 v158, 0, v158
	v_max_f32_e32 v159, 0, v159
	v_pk_fma_f32 v[144:145], v[154:155], v[158:159], v[144:145] op_sel_hi:[0,1,1]
	v_max_f32_e32 v163, 0, v163
	v_max_f32_e32 v158, v160, v160
	v_max_f32_e32 v160, 0, v164
	v_max_f32_e32 v158, 0, v158
	v_max_f32_e32 v159, 0, v161
	v_pk_fma_f32 v[146:147], v[154:155], v[158:159], v[146:147] op_sel_hi:[0,1,1]
	v_max_f32_e32 v161, 0, v165
	v_pk_fma_f32 v[112:113], v[152:153], v[160:161], v[112:113] op_sel_hi:[0,1,1]
	v_mfma_f32_16x16x32_bf16 v[158:161], v[16:19], v[64:67], 0
	v_max_f32_e32 v162, 0, v162
	v_pk_fma_f32 v[110:111], v[152:153], v[162:163], v[110:111] op_sel_hi:[0,1,1]
	v_mfma_f32_16x16x32_bf16 v[162:165], v[16:19], v[72:75], 0
	v_mfma_f32_16x16x32_bf16 v[158:161], v[20:23], v[68:71], v[158:161]
	v_mfma_f32_16x16x32_bf16 v[162:165], v[20:23], v[76:79], v[162:165]
	s_nop 6
	v_max_f32_e32 v158, 0, v158
	v_max_f32_e32 v159, 0, v159
	v_pk_fma_f32 v[140:141], v[154:155], v[158:159], v[140:141] op_sel_hi:[0,1,1]
	v_max_f32_e32 v163, 0, v163
	v_max_f32_e32 v158, v160, v160
	v_max_f32_e32 v160, 0, v164
	v_max_f32_e32 v158, 0, v158
	v_max_f32_e32 v159, 0, v161
	v_pk_fma_f32 v[142:143], v[154:155], v[158:159], v[142:143] op_sel_hi:[0,1,1]
	v_max_f32_e32 v161, 0, v165
	v_pk_fma_f32 v[108:109], v[152:153], v[160:161], v[108:109] op_sel_hi:[0,1,1]
	v_mfma_f32_16x16x32_bf16 v[158:161], v[24:27], v[64:67], 0
	v_max_f32_e32 v162, 0, v162
	v_pk_fma_f32 v[106:107], v[152:153], v[162:163], v[106:107] op_sel_hi:[0,1,1]
	v_mfma_f32_16x16x32_bf16 v[162:165], v[24:27], v[72:75], 0
	v_mfma_f32_16x16x32_bf16 v[158:161], v[28:31], v[68:71], v[158:161]
	v_mfma_f32_16x16x32_bf16 v[162:165], v[28:31], v[76:79], v[162:165]
	s_nop 6
	v_max_f32_e32 v158, 0, v158
	v_max_f32_e32 v159, 0, v159
	v_pk_fma_f32 v[134:135], v[154:155], v[158:159], v[134:135] op_sel_hi:[0,1,1]
	v_max_f32_e32 v163, 0, v163
	v_max_f32_e32 v158, v160, v160
	v_max_f32_e32 v160, 0, v164
	v_max_f32_e32 v158, 0, v158
	v_max_f32_e32 v159, 0, v161
	v_pk_fma_f32 v[136:137], v[154:155], v[158:159], v[136:137] op_sel_hi:[0,1,1]
	v_max_f32_e32 v161, 0, v165
	v_pk_fma_f32 v[104:105], v[152:153], v[160:161], v[104:105] op_sel_hi:[0,1,1]
	v_mfma_f32_16x16x32_bf16 v[158:161], v[32:35], v[64:67], 0
	v_max_f32_e32 v162, 0, v162
	v_pk_fma_f32 v[102:103], v[152:153], v[162:163], v[102:103] op_sel_hi:[0,1,1]
	v_mfma_f32_16x16x32_bf16 v[162:165], v[32:35], v[72:75], 0
	v_mfma_f32_16x16x32_bf16 v[158:161], v[36:39], v[68:71], v[158:161]
	v_mfma_f32_16x16x32_bf16 v[162:165], v[36:39], v[76:79], v[162:165]
	s_nop 6
	v_max_f32_e32 v158, 0, v158
	v_max_f32_e32 v159, 0, v159
	v_pk_fma_f32 v[130:131], v[154:155], v[158:159], v[130:131] op_sel_hi:[0,1,1]
	v_max_f32_e32 v163, 0, v163
	v_max_f32_e32 v158, v160, v160
	v_max_f32_e32 v160, 0, v164
	v_max_f32_e32 v158, 0, v158
	v_max_f32_e32 v159, 0, v161
	v_pk_fma_f32 v[132:133], v[154:155], v[158:159], v[132:133] op_sel_hi:[0,1,1]
	v_max_f32_e32 v161, 0, v165
	v_pk_fma_f32 v[100:101], v[152:153], v[160:161], v[100:101] op_sel_hi:[0,1,1]
	v_mfma_f32_16x16x32_bf16 v[158:161], v[40:43], v[64:67], 0
	v_max_f32_e32 v162, 0, v162
	v_pk_fma_f32 v[98:99], v[152:153], v[162:163], v[98:99] op_sel_hi:[0,1,1]
	v_mfma_f32_16x16x32_bf16 v[162:165], v[40:43], v[72:75], 0
	v_mfma_f32_16x16x32_bf16 v[158:161], v[44:47], v[68:71], v[158:161]
	v_mfma_f32_16x16x32_bf16 v[162:165], v[44:47], v[76:79], v[162:165]
	s_nop 6
	v_max_f32_e32 v158, 0, v158
	v_max_f32_e32 v159, 0, v159
	v_pk_fma_f32 v[126:127], v[154:155], v[158:159], v[126:127] op_sel_hi:[0,1,1]
	v_max_f32_e32 v163, 0, v163
	v_max_f32_e32 v158, v160, v160
	v_max_f32_e32 v160, 0, v164
	v_max_f32_e32 v158, 0, v158
	v_max_f32_e32 v159, 0, v161
	v_pk_fma_f32 v[128:129], v[154:155], v[158:159], v[128:129] op_sel_hi:[0,1,1]
	v_max_f32_e32 v161, 0, v165
; #define MFMA16(a, b, c) __builtin_amdgcn_mfma_f32_16x16x32_bf16((a), (b), (c), 0, 0, 0)
; DI void score_phase(const bf16_t* PROJ, unsigned short* SC, int c, char* smem, int bid, int nb) {
;     ...
;       for (int nj = 0; nj < 8; ++nj) {
;         f32x4 d = MFMA16(kf[nj][0], qa0, ((f32x4){0.f, 0.f, 0.f, 0.f}));
;         d = MFMA16(kf[nj][1], qa1, d);
;         f32x4 e = MFMA16(kf[nj][0], qb0f, ((f32x4){0.f, 0.f, 0.f, 0.f}));
;         e = MFMA16(kf[nj][1], qb1f, e);
; #pragma unroll
;         for (int r = 0; r < 4; ++r) { sc[0][nj][r] += w0 * fmaxf(d[r], 0.f); sc[1][nj][r] += w1 * fmaxf(e[r], 0.f); }
;       }
;     }
; #pragma unroll
;     for (int mi = 0; mi < 2; ++mi) {
;       const int t = q0 + mi * 16 + fr;
;       unsigned short* op = SC + (size_t)(t - c * 4096) * S + s0 + fq * 4;
; #pragma unroll
;       for (int nj = 0; nj < 8; ++nj) {
;         unsigned w0 = __builtin_bit_cast(unsigned, __builtin_amdgcn_cvt_pkrtz(sc[mi][nj][0], sc[mi][nj][1]));
;         unsigned w1 = __builtin_bit_cast(unsigned, __builtin_amdgcn_cvt_pkrtz(sc[mi][nj][2], sc[mi][nj][3]));
;         const unsigned m0 = ((w0 >> 15) & 0x00010001u) * 0xffffu, m1 = ((w1 >> 15) & 0x00010001u) * 0xffffu;
;         w0 ^= (m0 | 0x80008000u); w1 ^= (m1 | 0x80008000u);
;         uint2 st2; st2.x = w0; st2.y = w1;
;         *(uint2*)(op + nj * 16) = st2;
;       }
	v_pk_fma_f32 v[96:97], v[152:153], v[160:161], v[96:97] op_sel_hi:[0,1,1]
	v_mfma_f32_16x16x32_bf16 v[158:161], v[48:51], v[64:67], 0
	v_max_f32_e32 v162, 0, v162
	v_pk_fma_f32 v[94:95], v[152:153], v[162:163], v[94:95] op_sel_hi:[0,1,1]
	v_mfma_f32_16x16x32_bf16 v[64:67], v[56:59], v[64:67], 0
	v_mfma_f32_16x16x32_bf16 v[158:161], v[52:55], v[68:71], v[158:161]
	v_mfma_f32_16x16x32_bf16 v[162:165], v[48:51], v[72:75], 0
	v_mfma_f32_16x16x32_bf16 v[64:67], v[60:63], v[68:71], v[64:67]
	s_nop 5
	v_max_f32_e32 v158, 0, v158
	v_mfma_f32_16x16x32_bf16 v[68:71], v[56:59], v[72:75], 0
	v_max_f32_e32 v159, 0, v159
	v_mfma_f32_16x16x32_bf16 v[162:165], v[52:55], v[76:79], v[162:165]
	v_max_f32_e32 v64, 0, v64
	v_max_f32_e32 v65, 0, v65
	v_pk_fma_f32 v[122:123], v[154:155], v[158:159], v[122:123] op_sel_hi:[0,1,1]
	v_mfma_f32_16x16x32_bf16 v[68:71], v[60:63], v[76:79], v[68:71]
	v_fma_f32 v118, v154, v64, v118
	v_fma_f32 v119, v154, v65, v119
	s_nop 1
	v_max_f32_e32 v163, 0, v163
	v_max_f32_e32 v158, v160, v160
	v_max_f32_e32 v160, 0, v164
	s_nop 0
	v_max_f32_e32 v69, 0, v69
	v_max_f32_e32 v64, v66, v66
	v_max_f32_e32 v66, 0, v70
	v_max_f32_e32 v158, 0, v158
	v_max_f32_e32 v159, 0, v161
	v_max_f32_e32 v64, 0, v64
	v_max_f32_e32 v65, 0, v67
	v_pk_fma_f32 v[124:125], v[154:155], v[158:159], v[124:125] op_sel_hi:[0,1,1]
	v_max_f32_e32 v158, v165, v165
	v_pk_fma_f32 v[120:121], v[154:155], v[64:65], v[120:121] op_sel_hi:[0,1,1]
	v_max_f32_e32 v64, v71, v71
	v_max_f32_e32 v162, 0, v162
	v_max_f32_e32 v161, 0, v158
	v_max_f32_e32 v68, 0, v68
	v_max_f32_e32 v67, 0, v64
	v_pk_fma_f32 v[90:91], v[152:153], v[162:163], v[90:91] op_sel_hi:[0,1,1]
	v_pk_fma_f32 v[92:93], v[152:153], v[160:161], v[92:93] op_sel_hi:[0,1,1]
	v_pk_fma_f32 v[86:87], v[152:153], v[68:69], v[86:87] op_sel_hi:[0,1,1]
	v_pk_fma_f32 v[88:89], v[152:153], v[66:67], v[88:89] op_sel_hi:[0,1,1]
	s_cbranch_scc0 .LBB0_1574
	v_cvt_pkrtz_f16_f32 v4, v148, v149
	v_cvt_pkrtz_f16_f32 v5, v150, v151
	v_lshrrev_b32_e32 v6, 15, v5
	v_lshrrev_b32_e32 v7, 15, v4
	v_and_b32_e32 v6, 0x10001, v6
	v_and_b32_e32 v7, 0x10001, v7
	s_ashr_i32 s5, s4, 31
	v_mul_u32_u24_e32 v7, 0xffff, v7
	v_mul_u32_u24_e32 v6, 0xffff, v6
	v_lshl_add_u64 v[0:1], s[4:5], 1, v[80:81]
	v_lshlrev_b64 v[2:3], 15, v[84:85]
	v_or_b32_e32 v6, 0x80008000, v6
	v_or_b32_e32 v7, 0x80008000, v7
	v_lshl_add_u64 v[2:3], v[0:1], 0, v[2:3]
	v_xor_b32_e32 v5, v6, v5
	v_xor_b32_e32 v4, v7, v4
	global_store_dwordx2 v[2:3], v[4:5], off
	v_cvt_pkrtz_f16_f32 v4, v144, v145
	v_cvt_pkrtz_f16_f32 v5, v146, v147
	v_lshrrev_b32_e32 v6, 15, v5
	v_lshrrev_b32_e32 v7, 15, v4
	v_and_b32_e32 v6, 0x10001, v6
	v_and_b32_e32 v7, 0x10001, v7
	v_mul_u32_u24_e32 v7, 0xffff, v7
	v_mul_u32_u24_e32 v6, 0xffff, v6
	v_or_b32_e32 v6, 0x80008000, v6
	v_or_b32_e32 v7, 0x80008000, v7
	v_xor_b32_e32 v5, v6, v5
	v_xor_b32_e32 v4, v7, v4
	global_store_dwordx2 v[2:3], v[4:5], off offset:32
	v_cvt_pkrtz_f16_f32 v4, v140, v141
	v_cvt_pkrtz_f16_f32 v5, v142, v143
	v_lshrrev_b32_e32 v6, 15, v5
	v_lshrrev_b32_e32 v7, 15, v4
	v_and_b32_e32 v6, 0x10001, v6
	v_and_b32_e32 v7, 0x10001, v7
	v_mul_u32_u24_e32 v7, 0xffff, v7
	v_mul_u32_u24_e32 v6, 0xffff, v6
	v_or_b32_e32 v6, 0x80008000, v6
	v_or_b32_e32 v7, 0x80008000, v7
	v_xor_b32_e32 v5, v6, v5
	v_xor_b32_e32 v4, v7, v4
	global_store_dwordx2 v[2:3], v[4:5], off offset:64
	v_cvt_pkrtz_f16_f32 v4, v134, v135
	v_cvt_pkrtz_f16_f32 v5, v136, v137
	v_lshrrev_b32_e32 v6, 15, v5
	v_lshrrev_b32_e32 v7, 15, v4
	v_and_b32_e32 v6, 0x10001, v6
	v_and_b32_e32 v7, 0x10001, v7
	v_mul_u32_u24_e32 v7, 0xffff, v7
	v_mul_u32_u24_e32 v6, 0xffff, v6
	v_or_b32_e32 v6, 0x80008000, v6
	v_or_b32_e32 v7, 0x80008000, v7
	v_xor_b32_e32 v5, v6, v5
	v_xor_b32_e32 v4, v7, v4
	global_store_dwordx2 v[2:3], v[4:5], off offset:96
	v_cvt_pkrtz_f16_f32 v4, v130, v131
	v_cvt_pkrtz_f16_f32 v5, v132, v133
	v_lshrrev_b32_e32 v6, 15, v5
	v_lshrrev_b32_e32 v7, 15, v4
	v_and_b32_e32 v6, 0x10001, v6
	v_and_b32_e32 v7, 0x10001, v7
	v_mul_u32_u24_e32 v7, 0xffff, v7
	v_mul_u32_u24_e32 v6, 0xffff, v6
	v_or_b32_e32 v6, 0x80008000, v6
	v_or_b32_e32 v7, 0x80008000, v7
	v_xor_b32_e32 v5, v6, v5
	v_xor_b32_e32 v4, v7, v4
	global_store_dwordx2 v[2:3], v[4:5], off offset:128
	v_cvt_pkrtz_f16_f32 v4, v126, v127
	v_cvt_pkrtz_f16_f32 v5, v128, v129
	v_lshrrev_b32_e32 v6, 15, v5
	v_lshrrev_b32_e32 v7, 15, v4
	v_and_b32_e32 v6, 0x10001, v6
	v_and_b32_e32 v7, 0x10001, v7
	v_mul_u32_u24_e32 v7, 0xffff, v7
	v_mul_u32_u24_e32 v6, 0xffff, v6
	v_or_b32_e32 v6, 0x80008000, v6
	v_or_b32_e32 v7, 0x80008000, v7
	v_xor_b32_e32 v5, v6, v5
	v_xor_b32_e32 v4, v7, v4
	global_store_dwordx2 v[2:3], v[4:5], off offset:160
; DI void score_phase(const bf16_t* PROJ, unsigned short* SC, int c, char* smem, int bid, int nb) {
;     ...
; #pragma unroll
;     for (int mi = 0; mi < 2; ++mi) {
;       const int t = q0 + mi * 16 + fr;
;       unsigned short* op = SC + (size_t)(t - c * 4096) * S + s0 + fq * 4;
; #pragma unroll
;       for (int nj = 0; nj < 8; ++nj) {
;         unsigned w0 = __builtin_bit_cast(unsigned, __builtin_amdgcn_cvt_pkrtz(sc[mi][nj][0], sc[mi][nj][1]));
;         unsigned w1 = __builtin_bit_cast(unsigned, __builtin_amdgcn_cvt_pkrtz(sc[mi][nj][2], sc[mi][nj][3]));
;         const unsigned m0 = ((w0 >> 15) & 0x00010001u) * 0xffffu, m1 = ((w1 >> 15) & 0x00010001u) * 0xffffu;
;         w0 ^= (m0 | 0x80008000u); w1 ^= (m1 | 0x80008000u);
;         uint2 st2; st2.x = w0; st2.y = w1;
;         *(uint2*)(op + nj * 16) = st2;
;       }
;     }
;   }
	v_cvt_pkrtz_f16_f32 v4, v122, v123
	v_cvt_pkrtz_f16_f32 v5, v124, v125
	v_lshrrev_b32_e32 v6, 15, v5
	v_lshrrev_b32_e32 v7, 15, v4
	v_and_b32_e32 v6, 0x10001, v6
	v_and_b32_e32 v7, 0x10001, v7
	v_mul_u32_u24_e32 v7, 0xffff, v7
	v_mul_u32_u24_e32 v6, 0xffff, v6
	v_or_b32_e32 v6, 0x80008000, v6
	v_or_b32_e32 v7, 0x80008000, v7
	v_xor_b32_e32 v5, v6, v5
	v_xor_b32_e32 v4, v7, v4
	global_store_dwordx2 v[2:3], v[4:5], off offset:192
	v_cvt_pkrtz_f16_f32 v4, v118, v119
	v_cvt_pkrtz_f16_f32 v5, v120, v121
	v_lshrrev_b32_e32 v6, 15, v5
	v_lshrrev_b32_e32 v7, 15, v4
	v_and_b32_e32 v6, 0x10001, v6
	v_and_b32_e32 v7, 0x10001, v7
	v_mul_u32_u24_e32 v7, 0xffff, v7
	v_mul_u32_u24_e32 v6, 0xffff, v6
	v_or_b32_e32 v6, 0x80008000, v6
	v_or_b32_e32 v7, 0x80008000, v7
	v_xor_b32_e32 v5, v6, v5
	v_xor_b32_e32 v4, v7, v4
	global_store_dwordx2 v[2:3], v[4:5], off offset:224
	v_or_b32_e32 v2, 16, v84
	v_ashrrev_i32_e32 v3, 31, v2
	v_lshlrev_b64 v[2:3], 15, v[2:3]
	v_lshl_add_u64 v[0:1], v[0:1], 0, v[2:3]
	v_cvt_pkrtz_f16_f32 v2, v114, v115
	v_cvt_pkrtz_f16_f32 v3, v116, v117
	v_lshrrev_b32_e32 v4, 15, v3
	v_lshrrev_b32_e32 v5, 15, v2
	v_and_b32_e32 v4, 0x10001, v4
	v_and_b32_e32 v5, 0x10001, v5
	v_mul_u32_u24_e32 v5, 0xffff, v5
	v_mul_u32_u24_e32 v4, 0xffff, v4
	v_or_b32_e32 v4, 0x80008000, v4
	v_or_b32_e32 v5, 0x80008000, v5
	v_xor_b32_e32 v3, v4, v3
	v_xor_b32_e32 v2, v5, v2
	global_store_dwordx2 v[0:1], v[2:3], off
	v_cvt_pkrtz_f16_f32 v2, v110, v111
	v_cvt_pkrtz_f16_f32 v3, v112, v113
	v_lshrrev_b32_e32 v4, 15, v3
	v_lshrrev_b32_e32 v5, 15, v2
	v_and_b32_e32 v4, 0x10001, v4
	v_and_b32_e32 v5, 0x10001, v5
	v_mul_u32_u24_e32 v5, 0xffff, v5
	v_mul_u32_u24_e32 v4, 0xffff, v4
	v_or_b32_e32 v4, 0x80008000, v4
	v_or_b32_e32 v5, 0x80008000, v5
	v_xor_b32_e32 v3, v4, v3
	v_xor_b32_e32 v2, v5, v2
	global_store_dwordx2 v[0:1], v[2:3], off offset:32
	v_cvt_pkrtz_f16_f32 v2, v106, v107
	v_cvt_pkrtz_f16_f32 v3, v108, v109
	v_lshrrev_b32_e32 v4, 15, v3
	v_lshrrev_b32_e32 v5, 15, v2
	v_and_b32_e32 v4, 0x10001, v4
	v_and_b32_e32 v5, 0x10001, v5
	v_mul_u32_u24_e32 v5, 0xffff, v5
	v_mul_u32_u24_e32 v4, 0xffff, v4
	v_or_b32_e32 v4, 0x80008000, v4
	v_or_b32_e32 v5, 0x80008000, v5
	v_xor_b32_e32 v3, v4, v3
	v_xor_b32_e32 v2, v5, v2
	global_store_dwordx2 v[0:1], v[2:3], off offset:64
	v_cvt_pkrtz_f16_f32 v2, v102, v103
	v_cvt_pkrtz_f16_f32 v3, v104, v105
	v_lshrrev_b32_e32 v4, 15, v3
	v_lshrrev_b32_e32 v5, 15, v2
	v_and_b32_e32 v4, 0x10001, v4
	v_and_b32_e32 v5, 0x10001, v5
	v_mul_u32_u24_e32 v5, 0xffff, v5
	v_mul_u32_u24_e32 v4, 0xffff, v4
	v_or_b32_e32 v4, 0x80008000, v4
	v_or_b32_e32 v5, 0x80008000, v5
	v_xor_b32_e32 v3, v4, v3
	v_xor_b32_e32 v2, v5, v2
	global_store_dwordx2 v[0:1], v[2:3], off offset:96
	v_cvt_pkrtz_f16_f32 v2, v98, v99
	v_cvt_pkrtz_f16_f32 v3, v100, v101
	v_lshrrev_b32_e32 v4, 15, v3
	v_lshrrev_b32_e32 v5, 15, v2
	v_and_b32_e32 v4, 0x10001, v4
	v_and_b32_e32 v5, 0x10001, v5
	v_mul_u32_u24_e32 v5, 0xffff, v5
	v_mul_u32_u24_e32 v4, 0xffff, v4
	v_or_b32_e32 v4, 0x80008000, v4
	v_or_b32_e32 v5, 0x80008000, v5
	v_xor_b32_e32 v3, v4, v3
	v_xor_b32_e32 v2, v5, v2
	global_store_dwordx2 v[0:1], v[2:3], off offset:128
	v_cvt_pkrtz_f16_f32 v2, v94, v95
	v_cvt_pkrtz_f16_f32 v3, v96, v97
	v_lshrrev_b32_e32 v4, 15, v3
	v_lshrrev_b32_e32 v5, 15, v2
	v_and_b32_e32 v4, 0x10001, v4
	v_and_b32_e32 v5, 0x10001, v5
	v_mul_u32_u24_e32 v5, 0xffff, v5
	v_mul_u32_u24_e32 v4, 0xffff, v4
	v_or_b32_e32 v4, 0x80008000, v4
	v_or_b32_e32 v5, 0x80008000, v5
	v_xor_b32_e32 v3, v4, v3
	v_xor_b32_e32 v2, v5, v2
	global_store_dwordx2 v[0:1], v[2:3], off offset:160
	v_cvt_pkrtz_f16_f32 v2, v90, v91
	v_cvt_pkrtz_f16_f32 v3, v92, v93
	v_lshrrev_b32_e32 v4, 15, v3
	v_lshrrev_b32_e32 v5, 15, v2
	v_and_b32_e32 v4, 0x10001, v4
	v_and_b32_e32 v5, 0x10001, v5
	v_mul_u32_u24_e32 v5, 0xffff, v5
	v_mul_u32_u24_e32 v4, 0xffff, v4
	v_or_b32_e32 v4, 0x80008000, v4
	v_or_b32_e32 v5, 0x80008000, v5
	v_xor_b32_e32 v3, v4, v3
	v_xor_b32_e32 v2, v5, v2
	global_store_dwordx2 v[0:1], v[2:3], off offset:192
	v_cvt_pkrtz_f16_f32 v2, v86, v87
	v_cvt_pkrtz_f16_f32 v3, v88, v89
	v_lshrrev_b32_e32 v4, 15, v3
	v_lshrrev_b32_e32 v5, 15, v2
	v_and_b32_e32 v4, 0x10001, v4
	v_and_b32_e32 v5, 0x10001, v5
	v_mul_u32_u24_e32 v5, 0xffff, v5
	v_mul_u32_u24_e32 v4, 0xffff, v4
	v_readlane_b32 s2, v249, 43
	v_or_b32_e32 v4, 0x80008000, v4
	v_or_b32_e32 v5, 0x80008000, v5
	s_add_i32 s8, s8, s2
	v_xor_b32_e32 v3, v4, v3
	v_xor_b32_e32 v2, v5, v2
	s_cmpk_gt_i32 s8, 0x20f
	v_readlane_b32 s3, v249, 44
	global_store_dwordx2 v[0:1], v[2:3], off offset:224
	s_cbranch_scc0 .LBB0_1568
	s_branch .LBB0_1577
